# baseline (speedup 1.0000x reference)
; #define PG8_STAGE(bufoff, gbase, voff) do { _Pragma("unroll") for (int _i = 0; _i < 2; ++_i) \
;         __builtin_amdgcn_global_load_lds((const unsigned*)((const char*)(gbase) + (voff)[_i]), (LAS unsigned*)(lds + (bufoff) + ldsw + _i * 8192), 16, 0, 0); } while (0)
; #define PG8_LDA(dst, b, h) do { _Pragma("unroll") for (int m = 0; m < 4; ++m) _Pragma("unroll") for (int k = 0; k < 2; ++k) dst[m][k] = *(const LAS bf16x8*)(lds + PG8_SA(b, h) + aoff + m * 2048 + k * 1024); } while (0)
; #define PG8_WAIT_V(n) asm volatile("s_waitcnt vmcnt(" #n ")" ::: "memory")
; #define PG8_BAR __builtin_amdgcn_s_barrier()
; template <class Epi, class Sched>
; __device__ __forceinline__ void gemm_phase(LAS unsigned char* lds, const Gemm g, const Sched& S, const Epi& E, const int tid) {
;     ...
;         for (int t = 0; t < nt; t += 2) {
;             const bool last = (t == nt - 2);
;             const char* a1 = cA + (size_t)(t + 1) * kstepA;
;             const char* a2 = last ? nA : cA + (size_t)(t + 2) * kstepA; const char* b2 = last ? nB : cB + (size_t)(t + 2) * kstep;
;             const char* a3 = a2 + kstepA; const char* b3 = b2 + kstep;
;             if constexpr (Epi::HAS_MID) { if (t == g.tmid) E.mid(acc, cur, ui, wr, wc, fr, fq); }
;             PG8_LDB(B0, 0, 0); PG8_LDB(B1, 0, 1); PG8_SCHED; PG8_LDA(At, 0, 0); PG8_STAGE(PG8_SA(1, 1), a1 + hstepA, voffA);
;             PG8_WAIT_V(8); PG8_WAIT_L(0); PG8_BAR; PG8_MMA(0, 0, At, B0); PG8_MMA(0, 1, At, B1); PG8_BAR; PG8_SCHED;
;             PG8_LDA(At, 0, 1); PG8_STAGE(PG8_SB(0, 0), b2, voffB); PG8_STAGE(PG8_SB(0, 1), b2 + hstepB, voffB); PG8_STAGE(PG8_SA(0, 0), a2, voffA);
;             PG8_WAIT_V(8); PG8_WAIT_L(0); PG8_BAR; PG8_MMA(1, 0, At, B0); PG8_MMA(1, 1, At, B1); PG8_BAR; PG8_SCHED;
;             PG8_LDB(B0, 1, 0); PG8_LDB(B1, 1, 1); PG8_SCHED; PG8_LDA(At, 1, 0); PG8_STAGE(PG8_SA(0, 1), a2 + hstepA, voffA);
;             PG8_WAIT_V(8); PG8_WAIT_L(0); PG8_BAR; PG8_MMA(0, 0, At, B0); PG8_MMA(0, 1, At, B1); PG8_BAR; PG8_SCHED;
;             PG8_LDA(At, 1, 1); PG8_STAGE(PG8_SB(1, 0), b3, voffB); PG8_STAGE(PG8_SB(1, 1), b3 + hstepB, voffB); PG8_STAGE(PG8_SA(1, 0), a3, voffA);
;             PG8_WAIT_V(8); PG8_WAIT_L(0); PG8_BAR; PG8_MMA(1, 0, At, B0); PG8_MMA(1, 1, At, B1); PG8_BAR; PG8_SCHED;
;         }
;         if (wr == 0) PG8_BAR;
;         E(acc, cur, ui, wr, wc, fr, fq);
;         if (!has_next) break;
.Lp2_skip3:
	s_setprio 0
	s_add_i32 s48, s48, 2
	s_add_u32 s8, s8, 0x100
	s_addc_u32 s9, s9, 0
	s_add_u32 s38, s38, 0x100
	s_addc_u32 s39, s39, 0
	s_cmp_gt_u32 s48, 29
	s_barrier
	s_cbranch_scc0 .LBB0_285
	s_and_b64 vcc, exec, s[90:91]
	s_cbranch_vccz .LBB0_288
	s_barrier

; #define PG8_STAGE(bufoff, gbase, voff) do { _Pragma("unroll") for (int _i = 0; _i < 2; ++_i) \
;         __builtin_amdgcn_global_load_lds((const unsigned*)((const char*)(gbase) + (voff)[_i]), (LAS unsigned*)(lds + (bufoff) + ldsw + _i * 8192), 16, 0, 0); } while (0)
; #define PG8_LDA(dst, b, h) do { _Pragma("unroll") for (int m = 0; m < 4; ++m) _Pragma("unroll") for (int k = 0; k < 2; ++k) dst[m][k] = *(const LAS bf16x8*)(lds + PG8_SA(b, h) + aoff + m * 2048 + k * 1024); } while (0)
; #define PG8_LDB(dst, b, h) do { _Pragma("unroll") for (int n = 0; n < 2; ++n) _Pragma("unroll") for (int k = 0; k < 2; ++k) dst[n][k] = *(const LAS bf16x8*)(lds + PG8_SB(b, h) + boff + n * 2048 + k * 1024); } while (0)
; #define PG8_MMA(ai, bj, At, Bt) do { __builtin_amdgcn_s_setprio(1); _Pragma("unroll") for (int m = 0; m < 4; ++m) _Pragma("unroll") for (int n = 0; n < 2; ++n) _Pragma("unroll") for (int k = 0; k < 2; ++k) \
;         acc[ai][bj][m][n] = __builtin_amdgcn_mfma_f32_16x16x32_bf16(Bt[n][k], At[m][k], acc[ai][bj][m][n], 0, 0, 0); __builtin_amdgcn_s_setprio(0); } while (0)
; #define PG8_WAIT_V(n) asm volatile("s_waitcnt vmcnt(" #n ")" ::: "memory")
; #define PG8_WAIT_L(n) asm volatile("s_waitcnt lgkmcnt(" #n ")" ::: "memory")
; #define PG8_BAR __builtin_amdgcn_s_barrier()
; #define PG8_SCHED __builtin_amdgcn_sched_barrier(0)
; template <class Epi, class Sched>
; __device__ __forceinline__ void gemm_phase(LAS unsigned char* lds, const Gemm g, const Sched& S, const Epi& E, const int tid) {
;     ...
;             PG8_LDB(B0, 0, 0); PG8_LDB(B1, 0, 1); PG8_SCHED; PG8_LDA(At, 0, 0); PG8_STAGE(PG8_SA(1, 1), a1 + hstepA, voffA);
;             PG8_WAIT_V(8); PG8_WAIT_L(0); PG8_BAR; PG8_MMA(0, 0, At, B0); PG8_MMA(0, 1, At, B1); PG8_BAR; PG8_SCHED;
;             PG8_LDA(At, 0, 1); PG8_STAGE(PG8_SB(0, 0), b2, voffB); PG8_STAGE(PG8_SB(0, 1), b2 + hstepB, voffB); PG8_STAGE(PG8_SA(0, 0), a2, voffA);
;             PG8_WAIT_V(8); PG8_WAIT_L(0); PG8_BAR; PG8_MMA(1, 0, At, B0); PG8_MMA(1, 1, At, B1); PG8_BAR; PG8_SCHED;
.LBB0_714:
	ds_read_b128 v[152:155], v148
	ds_read_b128 v[156:159], v148 offset:1024
	ds_read_b128 v[160:163], v148 offset:2048
	ds_read_b128 v[164:167], v148 offset:3072
	ds_read_b128 v[168:171], v149
	ds_read_b128 v[172:175], v149 offset:1024
	ds_read_b128 v[176:179], v149 offset:2048
	ds_read_b128 v[180:183], v149 offset:3072
	s_add_u32 s36, s38, 0x100
	s_addc_u32 s37, s39, 0
	s_cmp_eq_u32 s65, 4
	s_cselect_b32 s59, s29, s37
	s_cselect_b32 s58, s28, s36
	s_cselect_b32 s49, s7, s27
	s_cselect_b32 s48, s18, s19
	v_lshl_add_u64 v[216:217], s[38:39], 0, v[138:139]
	s_add_i32 m0, s50, 0xc000
	ds_read_b128 v[184:187], v150
	ds_read_b128 v[188:191], v150 offset:1024
	ds_read_b128 v[192:195], v150 offset:2048
	ds_read_b128 v[196:199], v150 offset:3072
	ds_read_b128 v[200:203], v150 offset:4096
	ds_read_b128 v[204:207], v150 offset:5120
	ds_read_b128 v[208:211], v150 offset:6144
	ds_read_b128 v[212:215], v150 offset:7168
	global_load_lds_dwordx4 v[216:217], off
	v_lshl_add_u64 v[216:217], s[38:39], 0, v[140:141]
	s_add_i32 m0, s50, 0xe000
	s_nop 0
	global_load_lds_dwordx4 v[216:217], off
	s_waitcnt vmcnt(8)
	s_waitcnt lgkmcnt(0)
	s_barrier
	s_setprio 1
	s_waitcnt lgkmcnt(0)
	v_mfma_f32_16x16x32_bf16 v[124:127], v[152:155], v[184:187], v[124:127]
	v_mfma_f32_16x16x32_bf16 v[120:123], v[160:163], v[184:187], v[120:123]
	v_mfma_f32_16x16x32_bf16 v[116:119], v[152:155], v[192:195], v[116:119]
	v_mfma_f32_16x16x32_bf16 v[112:115], v[160:163], v[192:195], v[112:115]
	v_mfma_f32_16x16x32_bf16 v[104:107], v[152:155], v[200:203], v[104:107]
	v_mfma_f32_16x16x32_bf16 v[96:99], v[160:163], v[200:203], v[96:99]
	v_mfma_f32_16x16x32_bf16 v[88:91], v[152:155], v[208:211], v[88:91]
	v_mfma_f32_16x16x32_bf16 v[80:83], v[160:163], v[208:211], v[80:83]
	v_mfma_f32_16x16x32_bf16 v[124:127], v[156:159], v[188:191], v[124:127]
	v_mfma_f32_16x16x32_bf16 v[120:123], v[164:167], v[188:191], v[120:123]
	v_mfma_f32_16x16x32_bf16 v[116:119], v[156:159], v[196:199], v[116:119]
	v_mfma_f32_16x16x32_bf16 v[112:115], v[164:167], v[196:199], v[112:115]
	v_mfma_f32_16x16x32_bf16 v[104:107], v[156:159], v[204:207], v[104:107]
	v_mfma_f32_16x16x32_bf16 v[96:99], v[164:167], v[204:207], v[96:99]
	v_mfma_f32_16x16x32_bf16 v[88:91], v[156:159], v[212:215], v[88:91]
	v_mfma_f32_16x16x32_bf16 v[80:83], v[164:167], v[212:215], v[80:83]
	s_setprio 0
	s_setprio 1
	v_mfma_f32_16x16x32_bf16 v[108:111], v[168:171], v[184:187], v[108:111]
	v_mfma_f32_16x16x32_bf16 v[100:103], v[176:179], v[184:187], v[100:103]
	v_mfma_f32_16x16x32_bf16 v[92:95], v[168:171], v[192:195], v[92:95]
	v_mfma_f32_16x16x32_bf16 v[84:87], v[176:179], v[192:195], v[84:87]
	v_mfma_f32_16x16x32_bf16 v[76:79], v[168:171], v[200:203], v[76:79]
	v_mfma_f32_16x16x32_bf16 v[72:75], v[176:179], v[200:203], v[72:75]
	v_mfma_f32_16x16x32_bf16 v[68:71], v[168:171], v[208:211], v[68:71]
	v_mfma_f32_16x16x32_bf16 v[64:67], v[176:179], v[208:211], v[64:67]
	v_mfma_f32_16x16x32_bf16 v[108:111], v[172:175], v[188:191], v[108:111]
	v_mfma_f32_16x16x32_bf16 v[100:103], v[180:183], v[188:191], v[100:103]
	v_mfma_f32_16x16x32_bf16 v[92:95], v[172:175], v[196:199], v[92:95]
	v_mfma_f32_16x16x32_bf16 v[84:87], v[180:183], v[196:199], v[84:87]
	v_mfma_f32_16x16x32_bf16 v[76:79], v[172:175], v[204:207], v[76:79]
	v_mfma_f32_16x16x32_bf16 v[72:75], v[180:183], v[204:207], v[72:75]
	v_mfma_f32_16x16x32_bf16 v[68:71], v[172:175], v[212:215], v[68:71]
	v_mfma_f32_16x16x32_bf16 v[64:67], v[180:183], v[212:215], v[64:67]
	s_setprio 0
	s_barrier
	s_add_i32 s16, s62, s41
	v_lshl_add_u64 v[216:217], s[48:49], 0, v[132:133]
	s_mov_b32 m0, s16
	ds_read_b128 v[184:187], v150 offset:16384
	ds_read_b128 v[188:191], v150 offset:17408
	ds_read_b128 v[192:195], v150 offset:18432
	ds_read_b128 v[196:199], v150 offset:19456
	ds_read_b128 v[200:203], v150 offset:20480
	ds_read_b128 v[204:207], v150 offset:21504
	ds_read_b128 v[208:211], v150 offset:22528
	ds_read_b128 v[212:215], v150 offset:23552
	global_load_lds_dwordx4 v[216:217], off
	s_add_i32 m0, s16, 0x2000
	s_add_u32 s38, s48, 0x20000
	v_lshl_add_u64 v[218:219], s[48:49], 0, v[128:129]
	s_addc_u32 s39, s49, 0
	s_add_i32 s16, s63, s41
	global_load_lds_dwordx4 v[218:219], off
	v_lshl_add_u64 v[220:221], s[38:39], 0, v[132:133]
	s_mov_b32 m0, s16
	v_lshl_add_u64 v[222:223], s[58:59], 0, v[130:131]
	global_load_lds_dwordx4 v[220:221], off
	v_lshl_add_u64 v[220:221], s[38:39], 0, v[128:129]
	s_add_i32 m0, s16, 0x2000
	s_nop 0
	global_load_lds_dwordx4 v[220:221], off
	v_lshl_add_u64 v[220:221], s[58:59], 0, v[134:135]
	s_mov_b32 m0, s50
	s_nop 0
	global_load_lds_dwordx4 v[220:221], off
	s_mov_b32 m0, s52
	s_nop 0
	global_load_lds_dwordx4 v[222:223], off
	s_waitcnt vmcnt(8)
	s_waitcnt lgkmcnt(0)
	s_barrier
; #define PG8_STAGE(bufoff, gbase, voff) do { _Pragma("unroll") for (int _i = 0; _i < 2; ++_i) \
;         __builtin_amdgcn_global_load_lds((const unsigned*)((const char*)(gbase) + (voff)[_i]), (LAS unsigned*)(lds + (bufoff) + ldsw + _i * 8192), 16, 0, 0); } while (0)
; #define PG8_LDA(dst, b, h) do { _Pragma("unroll") for (int m = 0; m < 4; ++m) _Pragma("unroll") for (int k = 0; k < 2; ++k) dst[m][k] = *(const LAS bf16x8*)(lds + PG8_SA(b, h) + aoff + m * 2048 + k * 1024); } while (0)
; #define PG8_LDB(dst, b, h) do { _Pragma("unroll") for (int n = 0; n < 2; ++n) _Pragma("unroll") for (int k = 0; k < 2; ++k) dst[n][k] = *(const LAS bf16x8*)(lds + PG8_SB(b, h) + boff + n * 2048 + k * 1024); } while (0)
; #define PG8_MMA(ai, bj, At, Bt) do { __builtin_amdgcn_s_setprio(1); _Pragma("unroll") for (int m = 0; m < 4; ++m) _Pragma("unroll") for (int n = 0; n < 2; ++n) _Pragma("unroll") for (int k = 0; k < 2; ++k) \
;         acc[ai][bj][m][n] = __builtin_amdgcn_mfma_f32_16x16x32_bf16(Bt[n][k], At[m][k], acc[ai][bj][m][n], 0, 0, 0); __builtin_amdgcn_s_setprio(0); } while (0)
; #define PG8_WAIT_V(n) asm volatile("s_waitcnt vmcnt(" #n ")" ::: "memory")
; #define PG8_WAIT_L(n) asm volatile("s_waitcnt lgkmcnt(" #n ")" ::: "memory")
; #define PG8_BAR __builtin_amdgcn_s_barrier()
; #define PG8_SCHED __builtin_amdgcn_sched_barrier(0)
; template <class Epi, class Sched>
; __device__ __forceinline__ void gemm_phase(LAS unsigned char* lds, const Gemm g, const Sched& S, const Epi& E, const int tid) {
;     ...
;             PG8_WAIT_V(8); PG8_WAIT_L(0); PG8_BAR; PG8_MMA(1, 0, At, B0); PG8_MMA(1, 1, At, B1); PG8_BAR; PG8_SCHED;
;             PG8_LDB(B0, 1, 0); PG8_LDB(B1, 1, 1); PG8_SCHED; PG8_LDA(At, 1, 0); PG8_STAGE(PG8_SA(0, 1), a2 + hstepA, voffA);
;             PG8_WAIT_V(8); PG8_WAIT_L(0); PG8_BAR; PG8_MMA(0, 0, At, B0); PG8_MMA(0, 1, At, B1); PG8_BAR; PG8_SCHED;
	s_setprio 1
	s_waitcnt lgkmcnt(0)
	v_mfma_f32_16x16x32_bf16 v[60:63], v[152:155], v[184:187], v[60:63]
	v_mfma_f32_16x16x32_bf16 v[56:59], v[160:163], v[184:187], v[56:59]
	v_mfma_f32_16x16x32_bf16 v[52:55], v[152:155], v[192:195], v[52:55]
	v_mfma_f32_16x16x32_bf16 v[48:51], v[160:163], v[192:195], v[48:51]
	v_mfma_f32_16x16x32_bf16 v[40:43], v[152:155], v[200:203], v[40:43]
	v_mfma_f32_16x16x32_bf16 v[32:35], v[160:163], v[200:203], v[32:35]
	v_mfma_f32_16x16x32_bf16 v[24:27], v[152:155], v[208:211], v[24:27]
	v_mfma_f32_16x16x32_bf16 v[16:19], v[160:163], v[208:211], v[16:19]
	v_mfma_f32_16x16x32_bf16 v[60:63], v[156:159], v[188:191], v[60:63]
	v_mfma_f32_16x16x32_bf16 v[56:59], v[164:167], v[188:191], v[56:59]
	v_mfma_f32_16x16x32_bf16 v[52:55], v[156:159], v[196:199], v[52:55]
	v_mfma_f32_16x16x32_bf16 v[48:51], v[164:167], v[196:199], v[48:51]
	v_mfma_f32_16x16x32_bf16 v[40:43], v[156:159], v[204:207], v[40:43]
	v_mfma_f32_16x16x32_bf16 v[32:35], v[164:167], v[204:207], v[32:35]
	v_mfma_f32_16x16x32_bf16 v[24:27], v[156:159], v[212:215], v[24:27]
	v_mfma_f32_16x16x32_bf16 v[16:19], v[164:167], v[212:215], v[16:19]
	s_setprio 0
	s_setprio 1
	v_mfma_f32_16x16x32_bf16 v[44:47], v[168:171], v[184:187], v[44:47]
	v_mfma_f32_16x16x32_bf16 v[36:39], v[176:179], v[184:187], v[36:39]
	v_mfma_f32_16x16x32_bf16 v[28:31], v[168:171], v[192:195], v[28:31]
	v_mfma_f32_16x16x32_bf16 v[20:23], v[176:179], v[192:195], v[20:23]
	v_mfma_f32_16x16x32_bf16 v[12:15], v[168:171], v[200:203], v[12:15]
	v_mfma_f32_16x16x32_bf16 v[8:11], v[176:179], v[200:203], v[8:11]
	v_mfma_f32_16x16x32_bf16 v[4:7], v[168:171], v[208:211], v[4:7]
	v_mfma_f32_16x16x32_bf16 v[0:3], v[176:179], v[208:211], v[0:3]
	v_mfma_f32_16x16x32_bf16 v[44:47], v[172:175], v[188:191], v[44:47]
	v_mfma_f32_16x16x32_bf16 v[36:39], v[180:183], v[188:191], v[36:39]
	v_mfma_f32_16x16x32_bf16 v[28:31], v[172:175], v[196:199], v[28:31]
	v_mfma_f32_16x16x32_bf16 v[20:23], v[180:183], v[196:199], v[20:23]
	v_mfma_f32_16x16x32_bf16 v[12:15], v[172:175], v[204:207], v[12:15]
	v_mfma_f32_16x16x32_bf16 v[8:11], v[180:183], v[204:207], v[8:11]
	v_mfma_f32_16x16x32_bf16 v[4:7], v[172:175], v[212:215], v[4:7]
	v_mfma_f32_16x16x32_bf16 v[0:3], v[180:183], v[212:215], v[0:3]
	s_setprio 0
	s_barrier
	s_add_i32 s16, 0, 0x18000
	s_add_i32 s17, 0, 0x1c000
	v_add_u32_e32 v164, s16, v147
	v_add_u32_e32 v180, s17, v147
	ds_read_b128 v[152:155], v164
	ds_read_b128 v[156:159], v164 offset:1024
	ds_read_b128 v[160:163], v164 offset:2048
	ds_read_b128 v[164:167], v164 offset:3072
	ds_read_b128 v[168:171], v180
	ds_read_b128 v[172:175], v180 offset:1024
	ds_read_b128 v[176:179], v180 offset:2048
	ds_read_b128 v[180:183], v180 offset:3072
	s_add_u32 s38, s58, 0x30000
	s_addc_u32 s39, s59, 0
	s_mov_b32 m0, s53
	v_lshl_add_u64 v[224:225], s[38:39], 0, v[134:135]
	ds_read_b128 v[184:187], v150 offset:32768
	ds_read_b128 v[188:191], v150 offset:33792
	ds_read_b128 v[192:195], v150 offset:34816
	ds_read_b128 v[196:199], v150 offset:35840
	ds_read_b128 v[200:203], v150 offset:36864
	ds_read_b128 v[204:207], v150 offset:37888
	ds_read_b128 v[208:211], v150 offset:38912
	ds_read_b128 v[212:215], v150 offset:39936
	global_load_lds_dwordx4 v[224:225], off
	v_lshl_add_u64 v[224:225], s[38:39], 0, v[130:131]
	s_mov_b32 m0, s54
	s_nop 0
	global_load_lds_dwordx4 v[224:225], off
	s_waitcnt vmcnt(8)
	s_waitcnt lgkmcnt(0)
	s_barrier
	s_setprio 1
	s_waitcnt lgkmcnt(0)
	v_mfma_f32_16x16x32_bf16 v[124:127], v[152:155], v[184:187], v[124:127]
	v_mfma_f32_16x16x32_bf16 v[120:123], v[160:163], v[184:187], v[120:123]
	v_mfma_f32_16x16x32_bf16 v[116:119], v[152:155], v[192:195], v[116:119]
	v_mfma_f32_16x16x32_bf16 v[112:115], v[160:163], v[192:195], v[112:115]
	v_mfma_f32_16x16x32_bf16 v[104:107], v[152:155], v[200:203], v[104:107]
	v_mfma_f32_16x16x32_bf16 v[96:99], v[160:163], v[200:203], v[96:99]
	v_mfma_f32_16x16x32_bf16 v[88:91], v[152:155], v[208:211], v[88:91]
	v_mfma_f32_16x16x32_bf16 v[80:83], v[160:163], v[208:211], v[80:83]
	v_mfma_f32_16x16x32_bf16 v[124:127], v[156:159], v[188:191], v[124:127]
	v_mfma_f32_16x16x32_bf16 v[120:123], v[164:167], v[188:191], v[120:123]
	v_mfma_f32_16x16x32_bf16 v[116:119], v[156:159], v[196:199], v[116:119]
	v_mfma_f32_16x16x32_bf16 v[112:115], v[164:167], v[196:199], v[112:115]
	v_mfma_f32_16x16x32_bf16 v[104:107], v[156:159], v[204:207], v[104:107]
	v_mfma_f32_16x16x32_bf16 v[96:99], v[164:167], v[204:207], v[96:99]
	v_mfma_f32_16x16x32_bf16 v[88:91], v[156:159], v[212:215], v[88:91]
	v_mfma_f32_16x16x32_bf16 v[80:83], v[164:167], v[212:215], v[80:83]
	s_setprio 0
	s_setprio 1
	v_mfma_f32_16x16x32_bf16 v[108:111], v[168:171], v[184:187], v[108:111]
	v_mfma_f32_16x16x32_bf16 v[100:103], v[176:179], v[184:187], v[100:103]
	v_mfma_f32_16x16x32_bf16 v[92:95], v[168:171], v[192:195], v[92:95]
	v_mfma_f32_16x16x32_bf16 v[84:87], v[176:179], v[192:195], v[84:87]
	v_mfma_f32_16x16x32_bf16 v[76:79], v[168:171], v[200:203], v[76:79]
	v_mfma_f32_16x16x32_bf16 v[72:75], v[176:179], v[200:203], v[72:75]
	v_mfma_f32_16x16x32_bf16 v[68:71], v[168:171], v[208:211], v[68:71]
	v_mfma_f32_16x16x32_bf16 v[64:67], v[176:179], v[208:211], v[64:67]
	v_mfma_f32_16x16x32_bf16 v[108:111], v[172:175], v[188:191], v[108:111]
	v_mfma_f32_16x16x32_bf16 v[100:103], v[180:183], v[188:191], v[100:103]
	v_mfma_f32_16x16x32_bf16 v[92:95], v[172:175], v[196:199], v[92:95]
	v_mfma_f32_16x16x32_bf16 v[84:87], v[180:183], v[196:199], v[84:87]
	v_mfma_f32_16x16x32_bf16 v[76:79], v[172:175], v[204:207], v[76:79]
	v_mfma_f32_16x16x32_bf16 v[72:75], v[180:183], v[204:207], v[72:75]
	v_mfma_f32_16x16x32_bf16 v[68:71], v[172:175], v[212:215], v[68:71]
	v_mfma_f32_16x16x32_bf16 v[64:67], v[180:183], v[212:215], v[64:67]
	s_setprio 0
	s_barrier
; #define PG8_STAGE(bufoff, gbase, voff) do { _Pragma("unroll") for (int _i = 0; _i < 2; ++_i) \
;         __builtin_amdgcn_global_load_lds((const unsigned*)((const char*)(gbase) + (voff)[_i]), (LAS unsigned*)(lds + (bufoff) + ldsw + _i * 8192), 16, 0, 0); } while (0)
; #define PG8_LDA(dst, b, h) do { _Pragma("unroll") for (int m = 0; m < 4; ++m) _Pragma("unroll") for (int k = 0; k < 2; ++k) dst[m][k] = *(const LAS bf16x8*)(lds + PG8_SA(b, h) + aoff + m * 2048 + k * 1024); } while (0)
; #define PG8_MMA(ai, bj, At, Bt) do { __builtin_amdgcn_s_setprio(1); _Pragma("unroll") for (int m = 0; m < 4; ++m) _Pragma("unroll") for (int n = 0; n < 2; ++n) _Pragma("unroll") for (int k = 0; k < 2; ++k) \
;         acc[ai][bj][m][n] = __builtin_amdgcn_mfma_f32_16x16x32_bf16(Bt[n][k], At[m][k], acc[ai][bj][m][n], 0, 0, 0); __builtin_amdgcn_s_setprio(0); } while (0)
; #define PG8_WAIT_V(n) asm volatile("s_waitcnt vmcnt(" #n ")" ::: "memory")
; #define PG8_WAIT_L(n) asm volatile("s_waitcnt lgkmcnt(" #n ")" ::: "memory")
; #define PG8_BAR __builtin_amdgcn_s_barrier()
; #define PG8_SCHED __builtin_amdgcn_sched_barrier(0)
; template <class Epi, class Sched>
; __device__ __forceinline__ void gemm_phase(LAS unsigned char* lds, const Gemm g, const Sched& S, const Epi& E, const int tid) {
;     ...
;         for (int t = 0; t < nt; t += 2) {
;             const bool last = (t == nt - 2);
;             const char* a1 = cA + (size_t)(t + 1) * kstepA;
;             const char* a2 = last ? nA : cA + (size_t)(t + 2) * kstepA; const char* b2 = last ? nB : cB + (size_t)(t + 2) * kstep;
;     ...
;             PG8_LDA(At, 1, 1); PG8_STAGE(PG8_SB(1, 0), b3, voffB); PG8_STAGE(PG8_SB(1, 1), b3 + hstepB, voffB); PG8_STAGE(PG8_SA(1, 0), a3, voffA);
;             PG8_WAIT_V(8); PG8_WAIT_L(0); PG8_BAR; PG8_MMA(1, 0, At, B0); PG8_MMA(1, 1, At, B1); PG8_BAR; PG8_SCHED;
;         }
	s_add_i32 s16, s16, s41
	v_lshl_add_u64 v[216:217], v[216:217], 0, s[20:21]
	s_mov_b32 m0, s16
	ds_read_b128 v[184:187], v150 offset:49152
	ds_read_b128 v[188:191], v150 offset:50176
	ds_read_b128 v[192:195], v150 offset:51200
	ds_read_b128 v[196:199], v150 offset:52224
	ds_read_b128 v[200:203], v150 offset:53248
	ds_read_b128 v[204:207], v150 offset:54272
	ds_read_b128 v[208:211], v150 offset:55296
	ds_read_b128 v[212:215], v150 offset:56320
	global_load_lds_dwordx4 v[216:217], off
	s_add_i32 m0, s16, 0x2000
	s_add_u32 s38, s48, 0x20080
	v_lshl_add_u64 v[216:217], v[218:219], 0, s[20:21]
	s_addc_u32 s39, s49, 0
	s_add_i32 s16, s17, s41
	global_load_lds_dwordx4 v[216:217], off
	v_lshl_add_u64 v[216:217], s[38:39], 0, v[132:133]
	s_mov_b32 m0, s16
	s_nop 0
	global_load_lds_dwordx4 v[216:217], off
	v_lshl_add_u64 v[216:217], s[38:39], 0, v[128:129]
	s_add_i32 m0, s16, 0x2000
	s_nop 0
	global_load_lds_dwordx4 v[216:217], off
	v_lshl_add_u64 v[216:217], v[220:221], 0, s[20:21]
	s_mov_b32 m0, s60
	s_nop 0
	global_load_lds_dwordx4 v[216:217], off
	v_lshl_add_u64 v[216:217], v[222:223], 0, s[20:21]
	s_mov_b32 m0, s61
	s_nop 0
	global_load_lds_dwordx4 v[216:217], off
	s_waitcnt vmcnt(8)
	s_waitcnt lgkmcnt(0)
	s_barrier
	s_setprio 1
	s_waitcnt lgkmcnt(0)
	v_mfma_f32_16x16x32_bf16 v[60:63], v[152:155], v[184:187], v[60:63]
	v_mfma_f32_16x16x32_bf16 v[56:59], v[160:163], v[184:187], v[56:59]
	v_mfma_f32_16x16x32_bf16 v[52:55], v[152:155], v[192:195], v[52:55]
	v_mfma_f32_16x16x32_bf16 v[48:51], v[160:163], v[192:195], v[48:51]
	v_mfma_f32_16x16x32_bf16 v[40:43], v[152:155], v[200:203], v[40:43]
	v_mfma_f32_16x16x32_bf16 v[32:35], v[160:163], v[200:203], v[32:35]
	v_mfma_f32_16x16x32_bf16 v[24:27], v[152:155], v[208:211], v[24:27]
	v_mfma_f32_16x16x32_bf16 v[16:19], v[160:163], v[208:211], v[16:19]
	v_mfma_f32_16x16x32_bf16 v[60:63], v[156:159], v[188:191], v[60:63]
	v_mfma_f32_16x16x32_bf16 v[56:59], v[164:167], v[188:191], v[56:59]
	v_mfma_f32_16x16x32_bf16 v[52:55], v[156:159], v[196:199], v[52:55]
	v_mfma_f32_16x16x32_bf16 v[48:51], v[164:167], v[196:199], v[48:51]
	v_mfma_f32_16x16x32_bf16 v[40:43], v[156:159], v[204:207], v[40:43]
	v_mfma_f32_16x16x32_bf16 v[32:35], v[164:167], v[204:207], v[32:35]
	v_mfma_f32_16x16x32_bf16 v[24:27], v[156:159], v[212:215], v[24:27]
	v_mfma_f32_16x16x32_bf16 v[16:19], v[164:167], v[212:215], v[16:19]
	s_setprio 0
	s_setprio 1
	v_mfma_f32_16x16x32_bf16 v[44:47], v[168:171], v[184:187], v[44:47]
	v_mfma_f32_16x16x32_bf16 v[36:39], v[176:179], v[184:187], v[36:39]
	v_mfma_f32_16x16x32_bf16 v[28:31], v[168:171], v[192:195], v[28:31]
	v_mfma_f32_16x16x32_bf16 v[20:23], v[176:179], v[192:195], v[20:23]
	v_mfma_f32_16x16x32_bf16 v[12:15], v[168:171], v[200:203], v[12:15]
	v_mfma_f32_16x16x32_bf16 v[8:11], v[176:179], v[200:203], v[8:11]
	v_mfma_f32_16x16x32_bf16 v[4:7], v[168:171], v[208:211], v[4:7]
	v_mfma_f32_16x16x32_bf16 v[0:3], v[176:179], v[208:211], v[0:3]
	v_mfma_f32_16x16x32_bf16 v[44:47], v[172:175], v[188:191], v[44:47]
	v_mfma_f32_16x16x32_bf16 v[36:39], v[180:183], v[188:191], v[36:39]
	v_mfma_f32_16x16x32_bf16 v[28:31], v[172:175], v[196:199], v[28:31]
	v_mfma_f32_16x16x32_bf16 v[20:23], v[180:183], v[196:199], v[20:23]
	v_mfma_f32_16x16x32_bf16 v[12:15], v[172:175], v[204:207], v[12:15]
	v_mfma_f32_16x16x32_bf16 v[8:11], v[180:183], v[204:207], v[8:11]
	v_mfma_f32_16x16x32_bf16 v[4:7], v[172:175], v[212:215], v[4:7]
	v_mfma_f32_16x16x32_bf16 v[0:3], v[180:183], v[212:215], v[0:3]
	s_setprio 0
	s_add_i32 s65, s65, 2
	s_add_u32 s19, s19, 0x100
	s_addc_u32 s27, s27, 0
	s_cmp_gt_u32 s65, 5
	s_mov_b64 s[38:39], s[36:37]
	s_barrier
	s_cbranch_scc0 .LBB0_714
	s_and_b64 vcc, exec, s[24:25]
	s_cbranch_vccz .LBB0_717
	s_barrier

; #define PG8_STAGE(bufoff, gbase, voff) do { _Pragma("unroll") for (int _i = 0; _i < 2; ++_i) \
;         __builtin_amdgcn_global_load_lds((const unsigned*)((const char*)(gbase) + (voff)[_i]), (LAS unsigned*)(lds + (bufoff) + ldsw + _i * 8192), 16, 0, 0); } while (0)
; #define PG8_LDA(dst, b, h) do { _Pragma("unroll") for (int m = 0; m < 4; ++m) _Pragma("unroll") for (int k = 0; k < 2; ++k) dst[m][k] = *(const LAS bf16x8*)(lds + PG8_SA(b, h) + aoff + m * 2048 + k * 1024); } while (0)
; #define PG8_LDB(dst, b, h) do { _Pragma("unroll") for (int n = 0; n < 2; ++n) _Pragma("unroll") for (int k = 0; k < 2; ++k) dst[n][k] = *(const LAS bf16x8*)(lds + PG8_SB(b, h) + boff + n * 2048 + k * 1024); } while (0)
; #define PG8_MMA(ai, bj, At, Bt) do { __builtin_amdgcn_s_setprio(1); _Pragma("unroll") for (int m = 0; m < 4; ++m) _Pragma("unroll") for (int n = 0; n < 2; ++n) _Pragma("unroll") for (int k = 0; k < 2; ++k) \
;         acc[ai][bj][m][n] = __builtin_amdgcn_mfma_f32_16x16x32_bf16(Bt[n][k], At[m][k], acc[ai][bj][m][n], 0, 0, 0); __builtin_amdgcn_s_setprio(0); } while (0)
; #define PG8_WAIT_V(n) asm volatile("s_waitcnt vmcnt(" #n ")" ::: "memory")
; #define PG8_WAIT_L(n) asm volatile("s_waitcnt lgkmcnt(" #n ")" ::: "memory")
; #define PG8_BAR __builtin_amdgcn_s_barrier()
; template <class Epi, class Sched>
; __device__ __forceinline__ void gemm_phase(LAS unsigned char* lds, const Gemm g, const Sched& S, const Epi& E, const int tid) {
;     ...
;             const bool last = (t == nt - 2);
;             const char* a1 = cA + (size_t)(t + 1) * kstepA;
;             const char* a2 = last ? nA : cA + (size_t)(t + 2) * kstepA; const char* b2 = last ? nB : cB + (size_t)(t + 2) * kstep;
;             const char* a3 = a2 + kstepA; const char* b3 = b2 + kstep;
;             if constexpr (Epi::HAS_MID) { if (t == g.tmid) E.mid(acc, cur, ui, wr, wc, fr, fq); }
;             PG8_LDB(B0, 0, 0); PG8_LDB(B1, 0, 1); PG8_SCHED; PG8_LDA(At, 0, 0); PG8_STAGE(PG8_SA(1, 1), a1 + hstepA, voffA);
;             PG8_WAIT_V(8); PG8_WAIT_L(0); PG8_BAR; PG8_MMA(0, 0, At, B0); PG8_MMA(0, 1, At, B1); PG8_BAR; PG8_SCHED;
;             PG8_LDA(At, 0, 1); PG8_STAGE(PG8_SB(0, 0), b2, voffB); PG8_STAGE(PG8_SB(0, 1), b2 + hstepB, voffB); PG8_STAGE(PG8_SA(0, 0), a2, voffA);
;             PG8_WAIT_V(8); PG8_WAIT_L(0); PG8_BAR; PG8_MMA(1, 0, At, B0); PG8_MMA(1, 1, At, B1); PG8_BAR; PG8_SCHED;
.LBB0_802:
	ds_read_b128 v[16:19], v209
	ds_read_b128 v[20:23], v209 offset:1024
	ds_read_b128 v[104:107], v209 offset:2048
	ds_read_b128 v[140:143], v209 offset:3072
	ds_read_b128 v[144:147], v210
	ds_read_b128 v[148:151], v210 offset:1024
	ds_read_b128 v[178:181], v210 offset:2048
	ds_read_b128 v[212:215], v210 offset:3072
	s_add_u32 s4, s8, 0xfffe0080
	s_addc_u32 s5, s9, -1
	s_cmp_eq_u32 s83, 4
	s_cselect_b32 s29, s18, s5
	s_cselect_b32 s28, s19, s4
	s_cselect_b32 s27, s50, s75
	s_cselect_b32 s26, s51, s65
	v_lshl_add_u64 v[182:183], s[8:9], 0, v[168:169]
	s_add_i32 m0, s25, 0xc000
	ds_read_b128 v[216:219], v206
	ds_read_b128 v[220:223], v206 offset:1024
	ds_read_b128 v[224:227], v206 offset:2048
	ds_read_b128 v[228:231], v206 offset:3072
	ds_read_b128 v[232:235], v206 offset:4096
	ds_read_b128 v[236:239], v206 offset:5120
	ds_read_b128 v[240:243], v206 offset:6144
	ds_read_b128 v[244:247], v206 offset:7168
	global_load_lds_dwordx4 v[182:183], off
	v_lshl_add_u64 v[182:183], s[8:9], 0, v[170:171]
	s_add_i32 m0, s25, 0xe000
	s_nop 0
	global_load_lds_dwordx4 v[182:183], off
	s_waitcnt vmcnt(8)
	s_waitcnt lgkmcnt(0)
	s_barrier
	s_setprio 1
	s_waitcnt lgkmcnt(0)
	v_mfma_f32_16x16x32_bf16 v[136:139], v[16:19], v[216:219], v[136:139]
	v_mfma_f32_16x16x32_bf16 v[132:135], v[104:107], v[216:219], v[132:135]
	v_mfma_f32_16x16x32_bf16 v[120:123], v[16:19], v[224:227], v[120:123]
	v_mfma_f32_16x16x32_bf16 v[116:119], v[104:107], v[224:227], v[116:119]
	v_mfma_f32_16x16x32_bf16 v[100:103], v[16:19], v[232:235], v[100:103]
	v_mfma_f32_16x16x32_bf16 v[96:99], v[104:107], v[232:235], v[96:99]
	v_mfma_f32_16x16x32_bf16 v[84:87], v[16:19], v[240:243], v[84:87]
	v_mfma_f32_16x16x32_bf16 v[80:83], v[104:107], v[240:243], v[80:83]
	v_mfma_f32_16x16x32_bf16 v[136:139], v[20:23], v[220:223], v[136:139]
	v_mfma_f32_16x16x32_bf16 v[132:135], v[140:143], v[220:223], v[132:135]
	v_mfma_f32_16x16x32_bf16 v[120:123], v[20:23], v[228:231], v[120:123]
	v_mfma_f32_16x16x32_bf16 v[116:119], v[140:143], v[228:231], v[116:119]
	v_mfma_f32_16x16x32_bf16 v[100:103], v[20:23], v[236:239], v[100:103]
	v_mfma_f32_16x16x32_bf16 v[96:99], v[140:143], v[236:239], v[96:99]
	v_mfma_f32_16x16x32_bf16 v[84:87], v[20:23], v[244:247], v[84:87]
	v_mfma_f32_16x16x32_bf16 v[80:83], v[140:143], v[244:247], v[80:83]
	s_setprio 0
	s_setprio 1
	v_mfma_f32_16x16x32_bf16 v[128:131], v[144:147], v[216:219], v[128:131]
	v_mfma_f32_16x16x32_bf16 v[124:127], v[178:181], v[216:219], v[124:127]
	v_mfma_f32_16x16x32_bf16 v[112:115], v[144:147], v[224:227], v[112:115]
	v_mfma_f32_16x16x32_bf16 v[108:111], v[178:181], v[224:227], v[108:111]
	v_mfma_f32_16x16x32_bf16 v[92:95], v[144:147], v[232:235], v[92:95]
	v_mfma_f32_16x16x32_bf16 v[88:91], v[178:181], v[232:235], v[88:91]
	v_mfma_f32_16x16x32_bf16 v[76:79], v[144:147], v[240:243], v[76:79]
	v_mfma_f32_16x16x32_bf16 v[72:75], v[178:181], v[240:243], v[72:75]
	v_mfma_f32_16x16x32_bf16 v[128:131], v[148:151], v[220:223], v[128:131]
	v_mfma_f32_16x16x32_bf16 v[124:127], v[212:215], v[220:223], v[124:127]
	v_mfma_f32_16x16x32_bf16 v[112:115], v[148:151], v[228:231], v[112:115]
	v_mfma_f32_16x16x32_bf16 v[108:111], v[212:215], v[228:231], v[108:111]
	v_mfma_f32_16x16x32_bf16 v[92:95], v[148:151], v[236:239], v[92:95]
	v_mfma_f32_16x16x32_bf16 v[88:91], v[212:215], v[236:239], v[88:91]
	v_mfma_f32_16x16x32_bf16 v[76:79], v[148:151], v[244:247], v[76:79]
	v_mfma_f32_16x16x32_bf16 v[72:75], v[212:215], v[244:247], v[72:75]
	s_setprio 0
	s_barrier
	s_add_i32 s4, s54, s30
	v_lshl_add_u64 v[182:183], s[26:27], 0, v[154:155]
	s_mov_b32 m0, s4
	ds_read_b128 v[216:219], v206 offset:16384
	ds_read_b128 v[220:223], v206 offset:17408
	ds_read_b128 v[224:227], v206 offset:18432
	ds_read_b128 v[228:231], v206 offset:19456
	ds_read_b128 v[232:235], v206 offset:20480
	ds_read_b128 v[236:239], v206 offset:21504
	ds_read_b128 v[240:243], v206 offset:22528
	ds_read_b128 v[244:247], v206 offset:23552
	global_load_lds_dwordx4 v[182:183], off
	s_add_i32 m0, s4, 0x2000
	s_add_u32 s96, s26, 0x20000
	v_lshl_add_u64 v[248:249], s[26:27], 0, v[158:159]
	s_addc_u32 s97, s27, 0
	s_add_i32 s4, s55, s30
	global_load_lds_dwordx4 v[248:249], off
	v_lshl_add_u64 v[250:251], s[96:97], 0, v[154:155]
	s_mov_b32 m0, s4
	v_lshl_add_u64 v[174:175], s[28:29], 0, v[156:157]
	global_load_lds_dwordx4 v[250:251], off
	v_lshl_add_u64 v[250:251], s[96:97], 0, v[158:159]
	s_add_i32 m0, s4, 0x2000
	s_nop 0
	global_load_lds_dwordx4 v[250:251], off
	v_lshl_add_u64 v[250:251], s[28:29], 0, v[152:153]
	s_mov_b32 m0, s25
	s_nop 0
	global_load_lds_dwordx4 v[250:251], off
	s_mov_b32 m0, s31
	s_nop 0
	global_load_lds_dwordx4 v[174:175], off
	s_waitcnt vmcnt(8)
	s_waitcnt lgkmcnt(0)
	s_barrier
; #define PG8_STAGE(bufoff, gbase, voff) do { _Pragma("unroll") for (int _i = 0; _i < 2; ++_i) \
;         __builtin_amdgcn_global_load_lds((const unsigned*)((const char*)(gbase) + (voff)[_i]), (LAS unsigned*)(lds + (bufoff) + ldsw + _i * 8192), 16, 0, 0); } while (0)
; #define PG8_LDA(dst, b, h) do { _Pragma("unroll") for (int m = 0; m < 4; ++m) _Pragma("unroll") for (int k = 0; k < 2; ++k) dst[m][k] = *(const LAS bf16x8*)(lds + PG8_SA(b, h) + aoff + m * 2048 + k * 1024); } while (0)
; #define PG8_LDB(dst, b, h) do { _Pragma("unroll") for (int n = 0; n < 2; ++n) _Pragma("unroll") for (int k = 0; k < 2; ++k) dst[n][k] = *(const LAS bf16x8*)(lds + PG8_SB(b, h) + boff + n * 2048 + k * 1024); } while (0)
; #define PG8_MMA(ai, bj, At, Bt) do { __builtin_amdgcn_s_setprio(1); _Pragma("unroll") for (int m = 0; m < 4; ++m) _Pragma("unroll") for (int n = 0; n < 2; ++n) _Pragma("unroll") for (int k = 0; k < 2; ++k) \
;         acc[ai][bj][m][n] = __builtin_amdgcn_mfma_f32_16x16x32_bf16(Bt[n][k], At[m][k], acc[ai][bj][m][n], 0, 0, 0); __builtin_amdgcn_s_setprio(0); } while (0)
; #define PG8_WAIT_V(n) asm volatile("s_waitcnt vmcnt(" #n ")" ::: "memory")
; #define PG8_WAIT_L(n) asm volatile("s_waitcnt lgkmcnt(" #n ")" ::: "memory")
; #define PG8_BAR __builtin_amdgcn_s_barrier()
; #define PG8_SCHED __builtin_amdgcn_sched_barrier(0)
; template <class Epi, class Sched>
; __device__ __forceinline__ void gemm_phase(LAS unsigned char* lds, const Gemm g, const Sched& S, const Epi& E, const int tid) {
;     ...
;             PG8_WAIT_V(8); PG8_WAIT_L(0); PG8_BAR; PG8_MMA(1, 0, At, B0); PG8_MMA(1, 1, At, B1); PG8_BAR; PG8_SCHED;
;             PG8_LDB(B0, 1, 0); PG8_LDB(B1, 1, 1); PG8_SCHED; PG8_LDA(At, 1, 0); PG8_STAGE(PG8_SA(0, 1), a2 + hstepA, voffA);
;             PG8_WAIT_V(8); PG8_WAIT_L(0); PG8_BAR; PG8_MMA(0, 0, At, B0); PG8_MMA(0, 1, At, B1); PG8_BAR; PG8_SCHED;
	s_setprio 1
	s_waitcnt lgkmcnt(0)
	v_mfma_f32_16x16x32_bf16 v[68:71], v[16:19], v[216:219], v[68:71]
	v_mfma_f32_16x16x32_bf16 v[64:67], v[104:107], v[216:219], v[64:67]
	v_mfma_f32_16x16x32_bf16 v[52:55], v[16:19], v[224:227], v[52:55]
	v_mfma_f32_16x16x32_bf16 v[48:51], v[104:107], v[224:227], v[48:51]
	v_mfma_f32_16x16x32_bf16 v[36:39], v[16:19], v[232:235], v[36:39]
	v_mfma_f32_16x16x32_bf16 v[32:35], v[104:107], v[232:235], v[32:35]
	v_mfma_f32_16x16x32_bf16 v[12:15], v[16:19], v[240:243], v[12:15]
	v_mfma_f32_16x16x32_bf16 v[8:11], v[104:107], v[240:243], v[8:11]
	v_mfma_f32_16x16x32_bf16 v[68:71], v[20:23], v[220:223], v[68:71]
	v_mfma_f32_16x16x32_bf16 v[64:67], v[140:143], v[220:223], v[64:67]
	v_mfma_f32_16x16x32_bf16 v[52:55], v[20:23], v[228:231], v[52:55]
	v_mfma_f32_16x16x32_bf16 v[48:51], v[140:143], v[228:231], v[48:51]
	v_mfma_f32_16x16x32_bf16 v[36:39], v[20:23], v[236:239], v[36:39]
	v_mfma_f32_16x16x32_bf16 v[32:35], v[140:143], v[236:239], v[32:35]
	v_mfma_f32_16x16x32_bf16 v[12:15], v[20:23], v[244:247], v[12:15]
	v_mfma_f32_16x16x32_bf16 v[8:11], v[140:143], v[244:247], v[8:11]
	s_setprio 0
	s_setprio 1
	v_mfma_f32_16x16x32_bf16 v[44:47], v[144:147], v[224:227], v[44:47]
	v_mfma_f32_16x16x32_bf16 v[40:43], v[178:181], v[224:227], v[40:43]
	v_mfma_f32_16x16x32_bf16 v[28:31], v[144:147], v[232:235], v[28:31]
	v_mfma_f32_16x16x32_bf16 v[24:27], v[178:181], v[232:235], v[24:27]
	v_mfma_f32_16x16x32_bf16 v[4:7], v[144:147], v[240:243], v[4:7]
	v_mfma_f32_16x16x32_bf16 v[0:3], v[178:181], v[240:243], v[0:3]
	v_mfma_f32_16x16x32_bf16 v[16:19], v[144:147], v[216:219], v[60:63]
	v_mfma_f32_16x16x32_bf16 v[20:23], v[178:181], v[216:219], v[56:59]
	v_mfma_f32_16x16x32_bf16 v[44:47], v[148:151], v[228:231], v[44:47]
	v_mfma_f32_16x16x32_bf16 v[40:43], v[212:215], v[228:231], v[40:43]
	v_mfma_f32_16x16x32_bf16 v[28:31], v[148:151], v[236:239], v[28:31]
	v_mfma_f32_16x16x32_bf16 v[24:27], v[212:215], v[236:239], v[24:27]
	v_mfma_f32_16x16x32_bf16 v[4:7], v[148:151], v[244:247], v[4:7]
	v_mfma_f32_16x16x32_bf16 v[0:3], v[212:215], v[244:247], v[0:3]
	v_mfma_f32_16x16x32_bf16 v[16:19], v[148:151], v[220:223], v[16:19]
	v_mfma_f32_16x16x32_bf16 v[20:23], v[212:215], v[220:223], v[20:23]
	s_setprio 0
	s_barrier
	s_add_i32 s4, 0, 0x18000
	s_add_i32 s5, 0, 0x1c000
	v_add_u32_e32 v140, s4, v185
	v_add_u32_e32 v173, s5, v185
	ds_read_b128 v[56:59], v140
	ds_read_b128 v[60:63], v140 offset:1024
	ds_read_b128 v[104:107], v140 offset:2048
	ds_read_b128 v[140:143], v140 offset:3072
	ds_read_b128 v[144:147], v173
	ds_read_b128 v[148:151], v173 offset:1024
	ds_read_b128 v[178:181], v173 offset:2048
	ds_read_b128 v[212:215], v173 offset:3072
	s_add_u32 s28, s28, 0x20000
	s_addc_u32 s29, s29, 0
	s_mov_b32 m0, s41
	v_lshl_add_u64 v[176:177], s[28:29], 0, v[152:153]
	ds_read_b128 v[216:219], v206 offset:32768
	ds_read_b128 v[220:223], v206 offset:33792
	ds_read_b128 v[224:227], v206 offset:34816
	ds_read_b128 v[228:231], v206 offset:35840
	ds_read_b128 v[232:235], v206 offset:36864
	ds_read_b128 v[236:239], v206 offset:37888
	ds_read_b128 v[240:243], v206 offset:38912
	ds_read_b128 v[244:247], v206 offset:39936
	global_load_lds_dwordx4 v[176:177], off
	v_lshl_add_u64 v[176:177], s[28:29], 0, v[156:157]
	s_mov_b32 m0, s48
	s_nop 0
	global_load_lds_dwordx4 v[176:177], off
	s_waitcnt vmcnt(8)
	s_waitcnt lgkmcnt(0)
	s_barrier
	s_setprio 1
	s_waitcnt lgkmcnt(0)
	v_mfma_f32_16x16x32_bf16 v[136:139], v[56:59], v[216:219], v[136:139]
	v_mfma_f32_16x16x32_bf16 v[132:135], v[104:107], v[216:219], v[132:135]
	v_mfma_f32_16x16x32_bf16 v[120:123], v[56:59], v[224:227], v[120:123]
	v_mfma_f32_16x16x32_bf16 v[116:119], v[104:107], v[224:227], v[116:119]
	v_mfma_f32_16x16x32_bf16 v[100:103], v[56:59], v[232:235], v[100:103]
	v_mfma_f32_16x16x32_bf16 v[96:99], v[104:107], v[232:235], v[96:99]
	v_mfma_f32_16x16x32_bf16 v[84:87], v[56:59], v[240:243], v[84:87]
	v_mfma_f32_16x16x32_bf16 v[80:83], v[104:107], v[240:243], v[80:83]
	v_mfma_f32_16x16x32_bf16 v[136:139], v[60:63], v[220:223], v[136:139]
	v_mfma_f32_16x16x32_bf16 v[132:135], v[140:143], v[220:223], v[132:135]
	v_mfma_f32_16x16x32_bf16 v[120:123], v[60:63], v[228:231], v[120:123]
	v_mfma_f32_16x16x32_bf16 v[116:119], v[140:143], v[228:231], v[116:119]
	v_mfma_f32_16x16x32_bf16 v[100:103], v[60:63], v[236:239], v[100:103]
	v_mfma_f32_16x16x32_bf16 v[96:99], v[140:143], v[236:239], v[96:99]
	v_mfma_f32_16x16x32_bf16 v[84:87], v[60:63], v[244:247], v[84:87]
	v_mfma_f32_16x16x32_bf16 v[80:83], v[140:143], v[244:247], v[80:83]
	s_setprio 0
	s_setprio 1
	v_mfma_f32_16x16x32_bf16 v[128:131], v[144:147], v[216:219], v[128:131]
	v_mfma_f32_16x16x32_bf16 v[124:127], v[178:181], v[216:219], v[124:127]
	v_mfma_f32_16x16x32_bf16 v[112:115], v[144:147], v[224:227], v[112:115]
	v_mfma_f32_16x16x32_bf16 v[108:111], v[178:181], v[224:227], v[108:111]
	v_mfma_f32_16x16x32_bf16 v[92:95], v[144:147], v[232:235], v[92:95]
	v_mfma_f32_16x16x32_bf16 v[88:91], v[178:181], v[232:235], v[88:91]
	v_mfma_f32_16x16x32_bf16 v[76:79], v[144:147], v[240:243], v[76:79]
	v_mfma_f32_16x16x32_bf16 v[72:75], v[178:181], v[240:243], v[72:75]
	v_mfma_f32_16x16x32_bf16 v[128:131], v[148:151], v[220:223], v[128:131]
	v_mfma_f32_16x16x32_bf16 v[124:127], v[212:215], v[220:223], v[124:127]
	v_mfma_f32_16x16x32_bf16 v[112:115], v[148:151], v[228:231], v[112:115]
	v_mfma_f32_16x16x32_bf16 v[108:111], v[212:215], v[228:231], v[108:111]
	v_mfma_f32_16x16x32_bf16 v[92:95], v[148:151], v[236:239], v[92:95]
	v_mfma_f32_16x16x32_bf16 v[88:91], v[212:215], v[236:239], v[88:91]
	v_mfma_f32_16x16x32_bf16 v[76:79], v[148:151], v[244:247], v[76:79]
	v_mfma_f32_16x16x32_bf16 v[72:75], v[212:215], v[244:247], v[72:75]
	s_setprio 0
	s_barrier
; #define PG8_STAGE(bufoff, gbase, voff) do { _Pragma("unroll") for (int _i = 0; _i < 2; ++_i) \
;         __builtin_amdgcn_global_load_lds((const unsigned*)((const char*)(gbase) + (voff)[_i]), (LAS unsigned*)(lds + (bufoff) + ldsw + _i * 8192), 16, 0, 0); } while (0)
; #define PG8_LDA(dst, b, h) do { _Pragma("unroll") for (int m = 0; m < 4; ++m) _Pragma("unroll") for (int k = 0; k < 2; ++k) dst[m][k] = *(const LAS bf16x8*)(lds + PG8_SA(b, h) + aoff + m * 2048 + k * 1024); } while (0)
; #define PG8_MMA(ai, bj, At, Bt) do { __builtin_amdgcn_s_setprio(1); _Pragma("unroll") for (int m = 0; m < 4; ++m) _Pragma("unroll") for (int n = 0; n < 2; ++n) _Pragma("unroll") for (int k = 0; k < 2; ++k) \
;         acc[ai][bj][m][n] = __builtin_amdgcn_mfma_f32_16x16x32_bf16(Bt[n][k], At[m][k], acc[ai][bj][m][n], 0, 0, 0); __builtin_amdgcn_s_setprio(0); } while (0)
; #define PG8_WAIT_V(n) asm volatile("s_waitcnt vmcnt(" #n ")" ::: "memory")
; #define PG8_WAIT_L(n) asm volatile("s_waitcnt lgkmcnt(" #n ")" ::: "memory")
; #define PG8_BAR __builtin_amdgcn_s_barrier()
; #define PG8_SCHED __builtin_amdgcn_sched_barrier(0)
; template <class Epi, class Sched>
; __device__ __forceinline__ void gemm_phase(LAS unsigned char* lds, const Gemm g, const Sched& S, const Epi& E, const int tid) {
;     ...
;         for (int t = 0; t < nt; t += 2) {
;             const bool last = (t == nt - 2);
;             const char* a1 = cA + (size_t)(t + 1) * kstepA;
;             const char* a2 = last ? nA : cA + (size_t)(t + 2) * kstepA; const char* b2 = last ? nB : cB + (size_t)(t + 2) * kstep;
;     ...
;             PG8_LDA(At, 1, 1); PG8_STAGE(PG8_SB(1, 0), b3, voffB); PG8_STAGE(PG8_SB(1, 1), b3 + hstepB, voffB); PG8_STAGE(PG8_SA(1, 0), a3, voffA);
;             PG8_WAIT_V(8); PG8_WAIT_L(0); PG8_BAR; PG8_MMA(1, 0, At, B0); PG8_MMA(1, 1, At, B1); PG8_BAR; PG8_SCHED;
;         }
	s_add_i32 s4, s4, s30
	v_lshl_add_u64 v[176:177], v[182:183], 0, s[60:61]
	s_mov_b32 m0, s4
	ds_read_b128 v[216:219], v206 offset:49152
	ds_read_b128 v[220:223], v206 offset:50176
	ds_read_b128 v[224:227], v206 offset:51200
	ds_read_b128 v[228:231], v206 offset:52224
	ds_read_b128 v[232:235], v206 offset:53248
	ds_read_b128 v[236:239], v206 offset:54272
	ds_read_b128 v[240:243], v206 offset:55296
	ds_read_b128 v[244:247], v206 offset:56320
	global_load_lds_dwordx4 v[176:177], off
	s_add_i32 m0, s4, 0x2000
	s_add_u32 s26, s26, 0x20080
	v_lshl_add_u64 v[176:177], v[248:249], 0, s[60:61]
	s_addc_u32 s27, s27, 0
	s_add_i32 s4, s5, s30
	global_load_lds_dwordx4 v[176:177], off
	v_lshl_add_u64 v[176:177], s[26:27], 0, v[154:155]
	s_mov_b32 m0, s4
	v_lshl_add_u64 v[174:175], v[174:175], 0, s[60:61]
	global_load_lds_dwordx4 v[176:177], off
	v_lshl_add_u64 v[176:177], s[26:27], 0, v[158:159]
	s_add_i32 m0, s4, 0x2000
	s_nop 0
	global_load_lds_dwordx4 v[176:177], off
	v_lshl_add_u64 v[176:177], v[250:251], 0, s[60:61]
	s_mov_b32 m0, s49
	s_nop 0
	global_load_lds_dwordx4 v[176:177], off
	s_mov_b32 m0, s52
	s_nop 0
	global_load_lds_dwordx4 v[174:175], off
	s_waitcnt vmcnt(8)
	s_waitcnt lgkmcnt(0)
	s_barrier
	s_setprio 1
	s_waitcnt lgkmcnt(0)
	v_mfma_f32_16x16x32_bf16 v[68:71], v[56:59], v[216:219], v[68:71]
	v_mfma_f32_16x16x32_bf16 v[64:67], v[104:107], v[216:219], v[64:67]
	v_mfma_f32_16x16x32_bf16 v[52:55], v[56:59], v[224:227], v[52:55]
	v_mfma_f32_16x16x32_bf16 v[48:51], v[104:107], v[224:227], v[48:51]
	v_mfma_f32_16x16x32_bf16 v[36:39], v[56:59], v[232:235], v[36:39]
	v_mfma_f32_16x16x32_bf16 v[32:35], v[104:107], v[232:235], v[32:35]
	v_mfma_f32_16x16x32_bf16 v[12:15], v[56:59], v[240:243], v[12:15]
	v_mfma_f32_16x16x32_bf16 v[8:11], v[104:107], v[240:243], v[8:11]
	v_mfma_f32_16x16x32_bf16 v[68:71], v[60:63], v[220:223], v[68:71]
	v_mfma_f32_16x16x32_bf16 v[64:67], v[140:143], v[220:223], v[64:67]
	v_mfma_f32_16x16x32_bf16 v[52:55], v[60:63], v[228:231], v[52:55]
	v_mfma_f32_16x16x32_bf16 v[48:51], v[140:143], v[228:231], v[48:51]
	v_mfma_f32_16x16x32_bf16 v[36:39], v[60:63], v[236:239], v[36:39]
	v_mfma_f32_16x16x32_bf16 v[32:35], v[140:143], v[236:239], v[32:35]
	v_mfma_f32_16x16x32_bf16 v[12:15], v[60:63], v[244:247], v[12:15]
	v_mfma_f32_16x16x32_bf16 v[8:11], v[140:143], v[244:247], v[8:11]
	s_setprio 0
	s_setprio 1
	v_mfma_f32_16x16x32_bf16 v[16:19], v[144:147], v[216:219], v[16:19]
	v_mfma_f32_16x16x32_bf16 v[60:63], v[148:151], v[220:223], v[16:19]
	v_mfma_f32_16x16x32_bf16 v[16:19], v[178:181], v[216:219], v[20:23]
	v_mfma_f32_16x16x32_bf16 v[56:59], v[212:215], v[220:223], v[16:19]
	v_mfma_f32_16x16x32_bf16 v[16:19], v[144:147], v[224:227], v[44:47]
	v_mfma_f32_16x16x32_bf16 v[44:47], v[148:151], v[228:231], v[16:19]
	v_mfma_f32_16x16x32_bf16 v[16:19], v[178:181], v[224:227], v[40:43]
	v_mfma_f32_16x16x32_bf16 v[40:43], v[212:215], v[228:231], v[16:19]
	v_mfma_f32_16x16x32_bf16 v[16:19], v[144:147], v[232:235], v[28:31]
	v_mfma_f32_16x16x32_bf16 v[28:31], v[148:151], v[236:239], v[16:19]
	v_mfma_f32_16x16x32_bf16 v[16:19], v[178:181], v[232:235], v[24:27]
	v_mfma_f32_16x16x32_bf16 v[4:7], v[144:147], v[240:243], v[4:7]
	v_mfma_f32_16x16x32_bf16 v[0:3], v[178:181], v[240:243], v[0:3]
	v_mfma_f32_16x16x32_bf16 v[24:27], v[212:215], v[236:239], v[16:19]
	v_mfma_f32_16x16x32_bf16 v[4:7], v[148:151], v[244:247], v[4:7]
	v_mfma_f32_16x16x32_bf16 v[0:3], v[212:215], v[244:247], v[0:3]
	s_setprio 0
	s_add_i32 s83, s83, 2
	s_add_u32 s8, s8, 0x100
	s_addc_u32 s9, s9, 0
	s_add_u32 s65, s65, 0x100
	s_addc_u32 s75, s75, 0
	s_cmp_gt_u32 s83, 5
	s_barrier
	s_cbranch_scc0 .LBB0_802
	s_and_b64 vcc, exec, s[62:63]
	s_cbranch_vccz .LBB0_805
	s_barrier

; #define PG8_STAGE(bufoff, gbase, voff) do { _Pragma("unroll") for (int _i = 0; _i < 2; ++_i) \
;         __builtin_amdgcn_global_load_lds((const unsigned*)((const char*)(gbase) + (voff)[_i]), (LAS unsigned*)(lds + (bufoff) + ldsw + _i * 8192), 16, 0, 0); } while (0)
; #define PG8_LDA(dst, b, h) do { _Pragma("unroll") for (int m = 0; m < 4; ++m) _Pragma("unroll") for (int k = 0; k < 2; ++k) dst[m][k] = *(const LAS bf16x8*)(lds + PG8_SA(b, h) + aoff + m * 2048 + k * 1024); } while (0)
; #define PG8_LDB(dst, b, h) do { _Pragma("unroll") for (int n = 0; n < 2; ++n) _Pragma("unroll") for (int k = 0; k < 2; ++k) dst[n][k] = *(const LAS bf16x8*)(lds + PG8_SB(b, h) + boff + n * 2048 + k * 1024); } while (0)
; #define PG8_MMA(ai, bj, At, Bt) do { __builtin_amdgcn_s_setprio(1); _Pragma("unroll") for (int m = 0; m < 4; ++m) _Pragma("unroll") for (int n = 0; n < 2; ++n) _Pragma("unroll") for (int k = 0; k < 2; ++k) \
;         acc[ai][bj][m][n] = __builtin_amdgcn_mfma_f32_16x16x32_bf16(Bt[n][k], At[m][k], acc[ai][bj][m][n], 0, 0, 0); __builtin_amdgcn_s_setprio(0); } while (0)
; #define PG8_WAIT_V(n) asm volatile("s_waitcnt vmcnt(" #n ")" ::: "memory")
; #define PG8_WAIT_L(n) asm volatile("s_waitcnt lgkmcnt(" #n ")" ::: "memory")
; #define PG8_BAR __builtin_amdgcn_s_barrier()
; template <class Epi, class Sched>
; __device__ __forceinline__ void gemm_phase(LAS unsigned char* lds, const Gemm g, const Sched& S, const Epi& E, const int tid) {
;     ...
;             const bool last = (t == nt - 2);
;             const char* a1 = cA + (size_t)(t + 1) * kstepA;
;             const char* a2 = last ? nA : cA + (size_t)(t + 2) * kstepA; const char* b2 = last ? nB : cB + (size_t)(t + 2) * kstep;
;             const char* a3 = a2 + kstepA; const char* b3 = b2 + kstep;
;             if constexpr (Epi::HAS_MID) { if (t == g.tmid) E.mid(acc, cur, ui, wr, wc, fr, fq); }
;             PG8_LDB(B0, 0, 0); PG8_LDB(B1, 0, 1); PG8_SCHED; PG8_LDA(At, 0, 0); PG8_STAGE(PG8_SA(1, 1), a1 + hstepA, voffA);
;             PG8_WAIT_V(8); PG8_WAIT_L(0); PG8_BAR; PG8_MMA(0, 0, At, B0); PG8_MMA(0, 1, At, B1); PG8_BAR; PG8_SCHED;
;             PG8_LDA(At, 0, 1); PG8_STAGE(PG8_SB(0, 0), b2, voffB); PG8_STAGE(PG8_SB(0, 1), b2 + hstepB, voffB); PG8_STAGE(PG8_SA(0, 0), a2, voffA);
;             PG8_WAIT_V(8); PG8_WAIT_L(0); PG8_BAR; PG8_MMA(1, 0, At, B0); PG8_MMA(1, 1, At, B1); PG8_BAR; PG8_SCHED;
.LBB0_936:
	ds_read_b128 v[40:43], v197
	ds_read_b128 v[44:47], v197 offset:1024
	ds_read_b128 v[116:119], v197 offset:2048
	ds_read_b128 v[124:127], v197 offset:3072
	ds_read_b128 v[136:139], v198
	ds_read_b128 v[148:151], v198 offset:1024
	ds_read_b128 v[152:155], v198 offset:2048
	ds_read_b128 v[156:159], v198 offset:3072
	s_add_u32 s8, s6, 0x100
	s_addc_u32 s9, s7, 0
	s_cmp_eq_u32 s88, 8
	s_cselect_b32 s31, s25, s9
	s_cselect_b32 s30, s24, s8
	s_cselect_b32 s27, s29, s41
	s_cselect_b32 s26, s28, s40
	v_lshl_add_u64 v[218:219], s[6:7], 0, v[174:175]
	s_add_i32 m0, s52, 0xc000
	ds_read_b128 v[160:163], v199
	ds_read_b128 v[182:185], v199 offset:1024
	ds_read_b128 v[186:189], v199 offset:2048
	ds_read_b128 v[190:193], v199 offset:3072
	ds_read_b128 v[202:205], v199 offset:4096
	ds_read_b128 v[206:209], v199 offset:5120
	ds_read_b128 v[210:213], v199 offset:6144
	ds_read_b128 v[214:217], v199 offset:7168
	global_load_lds_dwordx4 v[218:219], off
	v_lshl_add_u64 v[218:219], s[6:7], 0, v[176:177]
	s_add_i32 m0, s52, 0xe000
	s_nop 0
	global_load_lds_dwordx4 v[218:219], off
	s_waitcnt vmcnt(8)
	s_waitcnt lgkmcnt(0)
	s_barrier
	s_setprio 1
	s_waitcnt lgkmcnt(0)
	v_mfma_f32_16x16x32_bf16 v[144:147], v[40:43], v[160:163], v[144:147]
	v_mfma_f32_16x16x32_bf16 v[140:143], v[116:119], v[160:163], v[140:143]
	v_mfma_f32_16x16x32_bf16 v[132:135], v[40:43], v[186:189], v[132:135]
	v_mfma_f32_16x16x32_bf16 v[128:131], v[116:119], v[186:189], v[128:131]
	v_mfma_f32_16x16x32_bf16 v[120:123], v[40:43], v[202:205], v[120:123]
	v_mfma_f32_16x16x32_bf16 v[112:115], v[116:119], v[202:205], v[112:115]
	v_mfma_f32_16x16x32_bf16 v[108:111], v[40:43], v[210:213], v[108:111]
	v_mfma_f32_16x16x32_bf16 v[104:107], v[116:119], v[210:213], v[104:107]
	v_mfma_f32_16x16x32_bf16 v[144:147], v[44:47], v[182:185], v[144:147]
	v_mfma_f32_16x16x32_bf16 v[140:143], v[124:127], v[182:185], v[140:143]
	v_mfma_f32_16x16x32_bf16 v[132:135], v[44:47], v[190:193], v[132:135]
	v_mfma_f32_16x16x32_bf16 v[128:131], v[124:127], v[190:193], v[128:131]
	v_mfma_f32_16x16x32_bf16 v[120:123], v[44:47], v[206:209], v[120:123]
	v_mfma_f32_16x16x32_bf16 v[112:115], v[124:127], v[206:209], v[112:115]
	v_mfma_f32_16x16x32_bf16 v[108:111], v[44:47], v[214:217], v[108:111]
	v_mfma_f32_16x16x32_bf16 v[104:107], v[124:127], v[214:217], v[104:107]
	s_setprio 0
	s_setprio 1
	v_mfma_f32_16x16x32_bf16 v[100:103], v[136:139], v[160:163], v[100:103]
	v_mfma_f32_16x16x32_bf16 v[96:99], v[152:155], v[160:163], v[96:99]
	v_mfma_f32_16x16x32_bf16 v[92:95], v[136:139], v[186:189], v[92:95]
	v_mfma_f32_16x16x32_bf16 v[88:91], v[152:155], v[186:189], v[88:91]
	v_mfma_f32_16x16x32_bf16 v[84:87], v[136:139], v[202:205], v[84:87]
	v_mfma_f32_16x16x32_bf16 v[80:83], v[152:155], v[202:205], v[80:83]
	v_mfma_f32_16x16x32_bf16 v[76:79], v[136:139], v[210:213], v[76:79]
	v_mfma_f32_16x16x32_bf16 v[72:75], v[152:155], v[210:213], v[72:75]
	v_mfma_f32_16x16x32_bf16 v[100:103], v[148:151], v[182:185], v[100:103]
	v_mfma_f32_16x16x32_bf16 v[96:99], v[156:159], v[182:185], v[96:99]
	v_mfma_f32_16x16x32_bf16 v[92:95], v[148:151], v[190:193], v[92:95]
	v_mfma_f32_16x16x32_bf16 v[88:91], v[156:159], v[190:193], v[88:91]
	v_mfma_f32_16x16x32_bf16 v[84:87], v[148:151], v[206:209], v[84:87]
	v_mfma_f32_16x16x32_bf16 v[80:83], v[156:159], v[206:209], v[80:83]
	v_mfma_f32_16x16x32_bf16 v[76:79], v[148:151], v[214:217], v[76:79]
	v_mfma_f32_16x16x32_bf16 v[72:75], v[156:159], v[214:217], v[72:75]
	s_setprio 0
	s_barrier
	s_add_i32 s4, s62, s43
	v_lshl_add_u64 v[218:219], s[26:27], 0, v[168:169]
	s_mov_b32 m0, s4
	ds_read_b128 v[160:163], v199 offset:16384
	ds_read_b128 v[182:185], v199 offset:17408
	ds_read_b128 v[186:189], v199 offset:18432
	ds_read_b128 v[190:193], v199 offset:19456
	ds_read_b128 v[202:205], v199 offset:20480
	ds_read_b128 v[206:209], v199 offset:21504
	ds_read_b128 v[210:213], v199 offset:22528
	ds_read_b128 v[214:217], v199 offset:23552
	global_load_lds_dwordx4 v[218:219], off
	s_add_i32 m0, s4, 0x2000
	s_add_u32 s4, s26, 0x30000
	v_lshl_add_u64 v[220:221], s[26:27], 0, v[164:165]
	s_addc_u32 s5, s27, 0
	s_add_i32 s6, s63, s43
	global_load_lds_dwordx4 v[220:221], off
	v_lshl_add_u64 v[222:223], s[4:5], 0, v[168:169]
	s_mov_b32 m0, s6
	v_lshl_add_u64 v[224:225], s[30:31], 0, v[166:167]
	global_load_lds_dwordx4 v[222:223], off
	v_lshl_add_u64 v[222:223], s[4:5], 0, v[164:165]
	s_add_i32 m0, s6, 0x2000
	s_nop 0
	global_load_lds_dwordx4 v[222:223], off
	v_lshl_add_u64 v[222:223], s[30:31], 0, v[170:171]
	s_mov_b32 m0, s52
	s_nop 0
	global_load_lds_dwordx4 v[222:223], off
	s_mov_b32 m0, s53
	s_nop 0
	global_load_lds_dwordx4 v[224:225], off
	s_waitcnt vmcnt(8)
	s_waitcnt lgkmcnt(0)
	s_barrier
; #define PG8_STAGE(bufoff, gbase, voff) do { _Pragma("unroll") for (int _i = 0; _i < 2; ++_i) \
;         __builtin_amdgcn_global_load_lds((const unsigned*)((const char*)(gbase) + (voff)[_i]), (LAS unsigned*)(lds + (bufoff) + ldsw + _i * 8192), 16, 0, 0); } while (0)
; #define PG8_LDA(dst, b, h) do { _Pragma("unroll") for (int m = 0; m < 4; ++m) _Pragma("unroll") for (int k = 0; k < 2; ++k) dst[m][k] = *(const LAS bf16x8*)(lds + PG8_SA(b, h) + aoff + m * 2048 + k * 1024); } while (0)
; #define PG8_LDB(dst, b, h) do { _Pragma("unroll") for (int n = 0; n < 2; ++n) _Pragma("unroll") for (int k = 0; k < 2; ++k) dst[n][k] = *(const LAS bf16x8*)(lds + PG8_SB(b, h) + boff + n * 2048 + k * 1024); } while (0)
; #define PG8_MMA(ai, bj, At, Bt) do { __builtin_amdgcn_s_setprio(1); _Pragma("unroll") for (int m = 0; m < 4; ++m) _Pragma("unroll") for (int n = 0; n < 2; ++n) _Pragma("unroll") for (int k = 0; k < 2; ++k) \
;         acc[ai][bj][m][n] = __builtin_amdgcn_mfma_f32_16x16x32_bf16(Bt[n][k], At[m][k], acc[ai][bj][m][n], 0, 0, 0); __builtin_amdgcn_s_setprio(0); } while (0)
; #define PG8_WAIT_V(n) asm volatile("s_waitcnt vmcnt(" #n ")" ::: "memory")
; #define PG8_WAIT_L(n) asm volatile("s_waitcnt lgkmcnt(" #n ")" ::: "memory")
; #define PG8_BAR __builtin_amdgcn_s_barrier()
; #define PG8_SCHED __builtin_amdgcn_sched_barrier(0)
; template <class Epi, class Sched>
; __device__ __forceinline__ void gemm_phase(LAS unsigned char* lds, const Gemm g, const Sched& S, const Epi& E, const int tid) {
;     ...
;             PG8_WAIT_V(8); PG8_WAIT_L(0); PG8_BAR; PG8_MMA(1, 0, At, B0); PG8_MMA(1, 1, At, B1); PG8_BAR; PG8_SCHED;
;             PG8_LDB(B0, 1, 0); PG8_LDB(B1, 1, 1); PG8_SCHED; PG8_LDA(At, 1, 0); PG8_STAGE(PG8_SA(0, 1), a2 + hstepA, voffA);
;             PG8_WAIT_V(8); PG8_WAIT_L(0); PG8_BAR; PG8_MMA(0, 0, At, B0); PG8_MMA(0, 1, At, B1); PG8_BAR; PG8_SCHED;
	s_setprio 1
	s_waitcnt lgkmcnt(0)
	v_mfma_f32_16x16x32_bf16 v[68:71], v[40:43], v[160:163], v[68:71]
	v_mfma_f32_16x16x32_bf16 v[64:67], v[116:119], v[160:163], v[64:67]
	v_mfma_f32_16x16x32_bf16 v[60:63], v[40:43], v[186:189], v[60:63]
	v_mfma_f32_16x16x32_bf16 v[56:59], v[116:119], v[186:189], v[56:59]
	v_mfma_f32_16x16x32_bf16 v[52:55], v[40:43], v[202:205], v[52:55]
	v_mfma_f32_16x16x32_bf16 v[48:51], v[116:119], v[202:205], v[48:51]
	v_mfma_f32_16x16x32_bf16 v[36:39], v[40:43], v[210:213], v[36:39]
	v_mfma_f32_16x16x32_bf16 v[32:35], v[116:119], v[210:213], v[32:35]
	v_mfma_f32_16x16x32_bf16 v[68:71], v[44:47], v[182:185], v[68:71]
	v_mfma_f32_16x16x32_bf16 v[64:67], v[124:127], v[182:185], v[64:67]
	v_mfma_f32_16x16x32_bf16 v[60:63], v[44:47], v[190:193], v[60:63]
	v_mfma_f32_16x16x32_bf16 v[56:59], v[124:127], v[190:193], v[56:59]
	v_mfma_f32_16x16x32_bf16 v[52:55], v[44:47], v[206:209], v[52:55]
	v_mfma_f32_16x16x32_bf16 v[48:51], v[124:127], v[206:209], v[48:51]
	v_mfma_f32_16x16x32_bf16 v[36:39], v[44:47], v[214:217], v[36:39]
	v_mfma_f32_16x16x32_bf16 v[32:35], v[124:127], v[214:217], v[32:35]
	s_setprio 0
	s_setprio 1
	v_mfma_f32_16x16x32_bf16 v[28:31], v[136:139], v[160:163], v[28:31]
	v_mfma_f32_16x16x32_bf16 v[24:27], v[152:155], v[160:163], v[24:27]
	v_mfma_f32_16x16x32_bf16 v[20:23], v[136:139], v[186:189], v[20:23]
	v_mfma_f32_16x16x32_bf16 v[16:19], v[152:155], v[186:189], v[16:19]
	v_mfma_f32_16x16x32_bf16 v[12:15], v[136:139], v[202:205], v[12:15]
	v_mfma_f32_16x16x32_bf16 v[8:11], v[152:155], v[202:205], v[8:11]
	v_mfma_f32_16x16x32_bf16 v[4:7], v[136:139], v[210:213], v[4:7]
	v_mfma_f32_16x16x32_bf16 v[0:3], v[152:155], v[210:213], v[0:3]
	v_mfma_f32_16x16x32_bf16 v[28:31], v[148:151], v[182:185], v[28:31]
	v_mfma_f32_16x16x32_bf16 v[24:27], v[156:159], v[182:185], v[24:27]
	v_mfma_f32_16x16x32_bf16 v[20:23], v[148:151], v[190:193], v[20:23]
	v_mfma_f32_16x16x32_bf16 v[16:19], v[156:159], v[190:193], v[16:19]
	v_mfma_f32_16x16x32_bf16 v[12:15], v[148:151], v[206:209], v[12:15]
	v_mfma_f32_16x16x32_bf16 v[8:11], v[156:159], v[206:209], v[8:11]
	v_mfma_f32_16x16x32_bf16 v[4:7], v[148:151], v[214:217], v[4:7]
	v_mfma_f32_16x16x32_bf16 v[0:3], v[156:159], v[214:217], v[0:3]
	s_setprio 0
	s_barrier
	s_add_i32 s6, 0, 0x18000
	s_add_i32 s7, 0, 0x1c000
	v_add_u32_e32 v124, s6, v196
	v_add_u32_e32 v156, s7, v196
	ds_read_b128 v[40:43], v124
	ds_read_b128 v[44:47], v124 offset:1024
	ds_read_b128 v[116:119], v124 offset:2048
	ds_read_b128 v[124:127], v124 offset:3072
	ds_read_b128 v[136:139], v156
	ds_read_b128 v[148:151], v156 offset:1024
	ds_read_b128 v[152:155], v156 offset:2048
	ds_read_b128 v[156:159], v156 offset:3072
	s_add_u32 s4, s30, 0x30000
	s_addc_u32 s5, s31, 0
	s_mov_b32 m0, s54
	v_lshl_add_u64 v[226:227], s[4:5], 0, v[170:171]
	ds_read_b128 v[160:163], v199 offset:32768
	ds_read_b128 v[182:185], v199 offset:33792
	ds_read_b128 v[186:189], v199 offset:34816
	ds_read_b128 v[190:193], v199 offset:35840
	ds_read_b128 v[202:205], v199 offset:36864
	ds_read_b128 v[206:209], v199 offset:37888
	ds_read_b128 v[210:213], v199 offset:38912
	ds_read_b128 v[214:217], v199 offset:39936
	global_load_lds_dwordx4 v[226:227], off
	v_lshl_add_u64 v[226:227], s[4:5], 0, v[166:167]
	s_mov_b32 m0, s55
	s_nop 0
	global_load_lds_dwordx4 v[226:227], off
	s_waitcnt vmcnt(8)
	s_waitcnt lgkmcnt(0)
	s_barrier
	s_setprio 1
	s_waitcnt lgkmcnt(0)
	v_mfma_f32_16x16x32_bf16 v[144:147], v[40:43], v[160:163], v[144:147]
	v_mfma_f32_16x16x32_bf16 v[140:143], v[116:119], v[160:163], v[140:143]
	v_mfma_f32_16x16x32_bf16 v[132:135], v[40:43], v[186:189], v[132:135]
	v_mfma_f32_16x16x32_bf16 v[128:131], v[116:119], v[186:189], v[128:131]
	v_mfma_f32_16x16x32_bf16 v[120:123], v[40:43], v[202:205], v[120:123]
	v_mfma_f32_16x16x32_bf16 v[112:115], v[116:119], v[202:205], v[112:115]
	v_mfma_f32_16x16x32_bf16 v[108:111], v[40:43], v[210:213], v[108:111]
	v_mfma_f32_16x16x32_bf16 v[104:107], v[116:119], v[210:213], v[104:107]
	v_mfma_f32_16x16x32_bf16 v[144:147], v[44:47], v[182:185], v[144:147]
	v_mfma_f32_16x16x32_bf16 v[140:143], v[124:127], v[182:185], v[140:143]
	v_mfma_f32_16x16x32_bf16 v[132:135], v[44:47], v[190:193], v[132:135]
	v_mfma_f32_16x16x32_bf16 v[128:131], v[124:127], v[190:193], v[128:131]
	v_mfma_f32_16x16x32_bf16 v[120:123], v[44:47], v[206:209], v[120:123]
	v_mfma_f32_16x16x32_bf16 v[112:115], v[124:127], v[206:209], v[112:115]
	v_mfma_f32_16x16x32_bf16 v[108:111], v[44:47], v[214:217], v[108:111]
	v_mfma_f32_16x16x32_bf16 v[104:107], v[124:127], v[214:217], v[104:107]
	s_setprio 0
	s_setprio 1
	v_mfma_f32_16x16x32_bf16 v[100:103], v[136:139], v[160:163], v[100:103]
	v_mfma_f32_16x16x32_bf16 v[96:99], v[152:155], v[160:163], v[96:99]
	v_mfma_f32_16x16x32_bf16 v[92:95], v[136:139], v[186:189], v[92:95]
	v_mfma_f32_16x16x32_bf16 v[88:91], v[152:155], v[186:189], v[88:91]
	v_mfma_f32_16x16x32_bf16 v[84:87], v[136:139], v[202:205], v[84:87]
	v_mfma_f32_16x16x32_bf16 v[80:83], v[152:155], v[202:205], v[80:83]
	v_mfma_f32_16x16x32_bf16 v[76:79], v[136:139], v[210:213], v[76:79]
	v_mfma_f32_16x16x32_bf16 v[72:75], v[152:155], v[210:213], v[72:75]
	v_mfma_f32_16x16x32_bf16 v[100:103], v[148:151], v[182:185], v[100:103]
	v_mfma_f32_16x16x32_bf16 v[96:99], v[156:159], v[182:185], v[96:99]
	v_mfma_f32_16x16x32_bf16 v[92:95], v[148:151], v[190:193], v[92:95]
	v_mfma_f32_16x16x32_bf16 v[88:91], v[156:159], v[190:193], v[88:91]
	v_mfma_f32_16x16x32_bf16 v[84:87], v[148:151], v[206:209], v[84:87]
	v_mfma_f32_16x16x32_bf16 v[80:83], v[156:159], v[206:209], v[80:83]
	v_mfma_f32_16x16x32_bf16 v[76:79], v[148:151], v[214:217], v[76:79]
	v_mfma_f32_16x16x32_bf16 v[72:75], v[156:159], v[214:217], v[72:75]
	s_setprio 0
	s_barrier
; #define PG8_STAGE(bufoff, gbase, voff) do { _Pragma("unroll") for (int _i = 0; _i < 2; ++_i) \
;         __builtin_amdgcn_global_load_lds((const unsigned*)((const char*)(gbase) + (voff)[_i]), (LAS unsigned*)(lds + (bufoff) + ldsw + _i * 8192), 16, 0, 0); } while (0)
; #define PG8_LDA(dst, b, h) do { _Pragma("unroll") for (int m = 0; m < 4; ++m) _Pragma("unroll") for (int k = 0; k < 2; ++k) dst[m][k] = *(const LAS bf16x8*)(lds + PG8_SA(b, h) + aoff + m * 2048 + k * 1024); } while (0)
; #define PG8_MMA(ai, bj, At, Bt) do { __builtin_amdgcn_s_setprio(1); _Pragma("unroll") for (int m = 0; m < 4; ++m) _Pragma("unroll") for (int n = 0; n < 2; ++n) _Pragma("unroll") for (int k = 0; k < 2; ++k) \
;         acc[ai][bj][m][n] = __builtin_amdgcn_mfma_f32_16x16x32_bf16(Bt[n][k], At[m][k], acc[ai][bj][m][n], 0, 0, 0); __builtin_amdgcn_s_setprio(0); } while (0)
; #define PG8_WAIT_V(n) asm volatile("s_waitcnt vmcnt(" #n ")" ::: "memory")
; #define PG8_WAIT_L(n) asm volatile("s_waitcnt lgkmcnt(" #n ")" ::: "memory")
; #define PG8_BAR __builtin_amdgcn_s_barrier()
; #define PG8_SCHED __builtin_amdgcn_sched_barrier(0)
; template <class Epi, class Sched>
; __device__ __forceinline__ void gemm_phase(LAS unsigned char* lds, const Gemm g, const Sched& S, const Epi& E, const int tid) {
;     ...
;         for (int t = 0; t < nt; t += 2) {
;             const bool last = (t == nt - 2);
;             const char* a1 = cA + (size_t)(t + 1) * kstepA;
;             const char* a2 = last ? nA : cA + (size_t)(t + 2) * kstepA; const char* b2 = last ? nB : cB + (size_t)(t + 2) * kstep;
;     ...
;             PG8_LDA(At, 1, 1); PG8_STAGE(PG8_SB(1, 0), b3, voffB); PG8_STAGE(PG8_SB(1, 1), b3 + hstepB, voffB); PG8_STAGE(PG8_SA(1, 0), a3, voffA);
;             PG8_WAIT_V(8); PG8_WAIT_L(0); PG8_BAR; PG8_MMA(1, 0, At, B0); PG8_MMA(1, 1, At, B1); PG8_BAR; PG8_SCHED;
;         }
	s_add_i32 s4, s6, s43
	v_lshl_add_u64 v[218:219], v[218:219], 0, s[36:37]
	s_mov_b32 m0, s4
	ds_read_b128 v[160:163], v199 offset:49152
	ds_read_b128 v[182:185], v199 offset:50176
	ds_read_b128 v[186:189], v199 offset:51200
	ds_read_b128 v[190:193], v199 offset:52224
	ds_read_b128 v[202:205], v199 offset:53248
	ds_read_b128 v[206:209], v199 offset:54272
	ds_read_b128 v[210:213], v199 offset:55296
	ds_read_b128 v[214:217], v199 offset:56320
	global_load_lds_dwordx4 v[218:219], off
	s_add_i32 m0, s4, 0x2000
	s_add_u32 s4, s26, 0x30080
	v_lshl_add_u64 v[218:219], v[220:221], 0, s[36:37]
	s_addc_u32 s5, s27, 0
	s_add_i32 s6, s7, s43
	global_load_lds_dwordx4 v[218:219], off
	v_lshl_add_u64 v[218:219], s[4:5], 0, v[168:169]
	s_mov_b32 m0, s6
	s_nop 0
	global_load_lds_dwordx4 v[218:219], off
	v_lshl_add_u64 v[218:219], s[4:5], 0, v[164:165]
	s_add_i32 m0, s6, 0x2000
	s_nop 0
	global_load_lds_dwordx4 v[218:219], off
	v_lshl_add_u64 v[218:219], v[222:223], 0, s[36:37]
	s_mov_b32 m0, s51
	s_nop 0
	global_load_lds_dwordx4 v[218:219], off
	v_lshl_add_u64 v[218:219], v[224:225], 0, s[36:37]
	s_mov_b32 m0, s60
	s_nop 0
	global_load_lds_dwordx4 v[218:219], off
	s_waitcnt vmcnt(8)
	s_waitcnt lgkmcnt(0)
	s_barrier
	s_setprio 1
	s_waitcnt lgkmcnt(0)
	v_mfma_f32_16x16x32_bf16 v[68:71], v[40:43], v[160:163], v[68:71]
	v_mfma_f32_16x16x32_bf16 v[64:67], v[116:119], v[160:163], v[64:67]
	v_mfma_f32_16x16x32_bf16 v[60:63], v[40:43], v[186:189], v[60:63]
	v_mfma_f32_16x16x32_bf16 v[56:59], v[116:119], v[186:189], v[56:59]
	v_mfma_f32_16x16x32_bf16 v[52:55], v[40:43], v[202:205], v[52:55]
	v_mfma_f32_16x16x32_bf16 v[48:51], v[116:119], v[202:205], v[48:51]
	v_mfma_f32_16x16x32_bf16 v[36:39], v[40:43], v[210:213], v[36:39]
	v_mfma_f32_16x16x32_bf16 v[32:35], v[116:119], v[210:213], v[32:35]
	v_mfma_f32_16x16x32_bf16 v[68:71], v[44:47], v[182:185], v[68:71]
	v_mfma_f32_16x16x32_bf16 v[64:67], v[124:127], v[182:185], v[64:67]
	v_mfma_f32_16x16x32_bf16 v[60:63], v[44:47], v[190:193], v[60:63]
	v_mfma_f32_16x16x32_bf16 v[56:59], v[124:127], v[190:193], v[56:59]
	v_mfma_f32_16x16x32_bf16 v[52:55], v[44:47], v[206:209], v[52:55]
	v_mfma_f32_16x16x32_bf16 v[48:51], v[124:127], v[206:209], v[48:51]
	v_mfma_f32_16x16x32_bf16 v[36:39], v[44:47], v[214:217], v[36:39]
	v_mfma_f32_16x16x32_bf16 v[32:35], v[124:127], v[214:217], v[32:35]
	s_setprio 0
	s_setprio 1
	v_mfma_f32_16x16x32_bf16 v[28:31], v[136:139], v[160:163], v[28:31]
	v_mfma_f32_16x16x32_bf16 v[24:27], v[152:155], v[160:163], v[24:27]
	v_mfma_f32_16x16x32_bf16 v[20:23], v[136:139], v[186:189], v[20:23]
	v_mfma_f32_16x16x32_bf16 v[16:19], v[152:155], v[186:189], v[16:19]
	v_mfma_f32_16x16x32_bf16 v[12:15], v[136:139], v[202:205], v[12:15]
	v_mfma_f32_16x16x32_bf16 v[8:11], v[152:155], v[202:205], v[8:11]
	v_mfma_f32_16x16x32_bf16 v[4:7], v[136:139], v[210:213], v[4:7]
	v_mfma_f32_16x16x32_bf16 v[0:3], v[152:155], v[210:213], v[0:3]
	v_mfma_f32_16x16x32_bf16 v[28:31], v[148:151], v[182:185], v[28:31]
	v_mfma_f32_16x16x32_bf16 v[24:27], v[156:159], v[182:185], v[24:27]
	v_mfma_f32_16x16x32_bf16 v[20:23], v[148:151], v[190:193], v[20:23]
	v_mfma_f32_16x16x32_bf16 v[16:19], v[156:159], v[190:193], v[16:19]
	v_mfma_f32_16x16x32_bf16 v[12:15], v[148:151], v[206:209], v[12:15]
	v_mfma_f32_16x16x32_bf16 v[8:11], v[156:159], v[206:209], v[8:11]
	v_mfma_f32_16x16x32_bf16 v[4:7], v[148:151], v[214:217], v[4:7]
	v_mfma_f32_16x16x32_bf16 v[0:3], v[156:159], v[214:217], v[0:3]
	s_setprio 0
	s_add_i32 s88, s88, 2
	s_add_u32 s40, s40, 0x100
	s_addc_u32 s41, s41, 0
	s_cmp_gt_u32 s88, 9
	s_mov_b64 s[6:7], s[8:9]
	s_barrier
	s_cbranch_scc0 .LBB0_936
	s_and_b64 vcc, exec, s[48:49]
	s_cbranch_vccz .LBB0_939
	s_barrier

; #define PG8_STAGE(bufoff, gbase, voff) do { _Pragma("unroll") for (int _i = 0; _i < 2; ++_i) \
;         __builtin_amdgcn_global_load_lds((const unsigned*)((const char*)(gbase) + (voff)[_i]), (LAS unsigned*)(lds + (bufoff) + ldsw + _i * 8192), 16, 0, 0); } while (0)
; #define PG8_LDA(dst, b, h) do { _Pragma("unroll") for (int m = 0; m < 4; ++m) _Pragma("unroll") for (int k = 0; k < 2; ++k) dst[m][k] = *(const LAS bf16x8*)(lds + PG8_SA(b, h) + aoff + m * 2048 + k * 1024); } while (0)
; #define PG8_LDB(dst, b, h) do { _Pragma("unroll") for (int n = 0; n < 2; ++n) _Pragma("unroll") for (int k = 0; k < 2; ++k) dst[n][k] = *(const LAS bf16x8*)(lds + PG8_SB(b, h) + boff + n * 2048 + k * 1024); } while (0)
; #define PG8_MMA(ai, bj, At, Bt) do { __builtin_amdgcn_s_setprio(1); _Pragma("unroll") for (int m = 0; m < 4; ++m) _Pragma("unroll") for (int n = 0; n < 2; ++n) _Pragma("unroll") for (int k = 0; k < 2; ++k) \
;         acc[ai][bj][m][n] = __builtin_amdgcn_mfma_f32_16x16x32_bf16(Bt[n][k], At[m][k], acc[ai][bj][m][n], 0, 0, 0); __builtin_amdgcn_s_setprio(0); } while (0)
; #define PG8_WAIT_V(n) asm volatile("s_waitcnt vmcnt(" #n ")" ::: "memory")
; #define PG8_WAIT_L(n) asm volatile("s_waitcnt lgkmcnt(" #n ")" ::: "memory")
; #define PG8_BAR __builtin_amdgcn_s_barrier()
; template <class Epi, class Sched>
; __device__ __forceinline__ void gemm_phase(LAS unsigned char* lds, const Gemm g, const Sched& S, const Epi& E, const int tid) {
;     ...
;             const bool last = (t == nt - 2);
;             const char* a1 = cA + (size_t)(t + 1) * kstepA;
;             const char* a2 = last ? nA : cA + (size_t)(t + 2) * kstepA; const char* b2 = last ? nB : cB + (size_t)(t + 2) * kstep;
;             const char* a3 = a2 + kstepA; const char* b3 = b2 + kstep;
;             if constexpr (Epi::HAS_MID) { if (t == g.tmid) E.mid(acc, cur, ui, wr, wc, fr, fq); }
;             PG8_LDB(B0, 0, 0); PG8_LDB(B1, 0, 1); PG8_SCHED; PG8_LDA(At, 0, 0); PG8_STAGE(PG8_SA(1, 1), a1 + hstepA, voffA);
;             PG8_WAIT_V(8); PG8_WAIT_L(0); PG8_BAR; PG8_MMA(0, 0, At, B0); PG8_MMA(0, 1, At, B1); PG8_BAR; PG8_SCHED;
;             PG8_LDA(At, 0, 1); PG8_STAGE(PG8_SB(0, 0), b2, voffB); PG8_STAGE(PG8_SB(0, 1), b2 + hstepB, voffB); PG8_STAGE(PG8_SA(0, 0), a2, voffA);
;             PG8_WAIT_V(8); PG8_WAIT_L(0); PG8_BAR; PG8_MMA(1, 0, At, B0); PG8_MMA(1, 1, At, B1); PG8_BAR; PG8_SCHED;
.LBB0_1040:
	ds_read_b128 v[84:87], v204
	ds_read_b128 v[92:95], v204 offset:1024
	ds_read_b128 v[136:139], v204 offset:2048
	ds_read_b128 v[140:143], v204 offset:3072
	ds_read_b128 v[144:147], v205
	ds_read_b128 v[148:151], v205 offset:1024
	ds_read_b128 v[152:155], v205 offset:2048
	ds_read_b128 v[156:159], v205 offset:3072
	s_add_u32 s40, s38, 0xa00000
	s_addc_u32 s41, s39, 0
	s_cmp_eq_u32 s75, 12
	s_cselect_b32 s52, s27, s40
	s_cselect_b32 s53, s9, s41
	s_cselect_b32 s50, s35, s72
	s_cselect_b32 s51, s25, s73
	s_add_u32 s48, s52, 0x500000
	s_addc_u32 s49, s53, 0
	v_lshl_add_u64 v[198:199], s[38:39], 0, v[174:175]
	s_add_i32 m0, s55, 0xc000
	ds_read_b128 v[160:163], v206
	ds_read_b128 v[182:185], v206 offset:1024
	ds_read_b128 v[186:189], v206 offset:2048
	ds_read_b128 v[190:193], v206 offset:3072
	ds_read_b128 v[194:197], v206 offset:4096
	ds_read_b128 v[208:211], v206 offset:5120
	ds_read_b128 v[212:215], v206 offset:6144
	ds_read_b128 v[216:219], v206 offset:7168
	global_load_lds_dwordx4 v[198:199], off
	v_lshl_add_u64 v[198:199], s[38:39], 0, v[176:177]
	s_add_i32 m0, s55, 0xe000
	s_nop 0
	global_load_lds_dwordx4 v[198:199], off
	s_waitcnt vmcnt(8)
	s_waitcnt lgkmcnt(0)
	s_barrier
	s_setprio 1
	s_waitcnt lgkmcnt(0)
	v_mfma_f32_16x16x32_bf16 v[132:135], v[84:87], v[160:163], v[132:135]
	v_mfma_f32_16x16x32_bf16 v[128:131], v[136:139], v[160:163], v[128:131]
	v_mfma_f32_16x16x32_bf16 v[124:127], v[84:87], v[186:189], v[124:127]
	v_mfma_f32_16x16x32_bf16 v[120:123], v[136:139], v[186:189], v[120:123]
	v_mfma_f32_16x16x32_bf16 v[116:119], v[84:87], v[194:197], v[116:119]
	v_mfma_f32_16x16x32_bf16 v[112:115], v[136:139], v[194:197], v[112:115]
	v_mfma_f32_16x16x32_bf16 v[108:111], v[84:87], v[212:215], v[108:111]
	v_mfma_f32_16x16x32_bf16 v[104:107], v[136:139], v[212:215], v[104:107]
	v_mfma_f32_16x16x32_bf16 v[132:135], v[92:95], v[182:185], v[132:135]
	v_mfma_f32_16x16x32_bf16 v[128:131], v[140:143], v[182:185], v[128:131]
	v_mfma_f32_16x16x32_bf16 v[124:127], v[92:95], v[190:193], v[124:127]
	v_mfma_f32_16x16x32_bf16 v[120:123], v[140:143], v[190:193], v[120:123]
	v_mfma_f32_16x16x32_bf16 v[116:119], v[92:95], v[208:211], v[116:119]
	v_mfma_f32_16x16x32_bf16 v[112:115], v[140:143], v[208:211], v[112:115]
	v_mfma_f32_16x16x32_bf16 v[108:111], v[92:95], v[216:219], v[108:111]
	v_mfma_f32_16x16x32_bf16 v[104:107], v[140:143], v[216:219], v[104:107]
	s_setprio 0
	s_setprio 1
	v_mfma_f32_16x16x32_bf16 v[60:63], v[144:147], v[160:163], v[60:63]
	v_mfma_f32_16x16x32_bf16 v[56:59], v[152:155], v[160:163], v[56:59]
	v_mfma_f32_16x16x32_bf16 v[52:55], v[144:147], v[186:189], v[52:55]
	v_mfma_f32_16x16x32_bf16 v[48:51], v[152:155], v[186:189], v[48:51]
	v_mfma_f32_16x16x32_bf16 v[44:47], v[144:147], v[194:197], v[44:47]
	v_mfma_f32_16x16x32_bf16 v[40:43], v[152:155], v[194:197], v[40:43]
	v_mfma_f32_16x16x32_bf16 v[36:39], v[144:147], v[212:215], v[36:39]
	v_mfma_f32_16x16x32_bf16 v[32:35], v[152:155], v[212:215], v[32:35]
	v_mfma_f32_16x16x32_bf16 v[60:63], v[148:151], v[182:185], v[60:63]
	v_mfma_f32_16x16x32_bf16 v[56:59], v[156:159], v[182:185], v[56:59]
	v_mfma_f32_16x16x32_bf16 v[52:55], v[148:151], v[190:193], v[52:55]
	v_mfma_f32_16x16x32_bf16 v[48:51], v[156:159], v[190:193], v[48:51]
	v_mfma_f32_16x16x32_bf16 v[44:47], v[148:151], v[208:211], v[44:47]
	v_mfma_f32_16x16x32_bf16 v[40:43], v[156:159], v[208:211], v[40:43]
	v_mfma_f32_16x16x32_bf16 v[36:39], v[148:151], v[216:219], v[36:39]
	v_mfma_f32_16x16x32_bf16 v[32:35], v[156:159], v[216:219], v[32:35]
	s_setprio 0
	s_barrier
	s_add_i32 s16, s69, s54
	v_lshl_add_u64 v[198:199], s[50:51], 0, v[166:167]
	s_mov_b32 m0, s16
	ds_read_b128 v[160:163], v206 offset:16384
	ds_read_b128 v[182:185], v206 offset:17408
	ds_read_b128 v[186:189], v206 offset:18432
	ds_read_b128 v[190:193], v206 offset:19456
	ds_read_b128 v[194:197], v206 offset:20480
	ds_read_b128 v[208:211], v206 offset:21504
	ds_read_b128 v[212:215], v206 offset:22528
	ds_read_b128 v[216:219], v206 offset:23552
	global_load_lds_dwordx4 v[198:199], off
	s_add_i32 m0, s16, 0x2000
	s_add_u32 s16, s50, 0x40000
	v_lshl_add_u64 v[220:221], s[50:51], 0, v[170:171]
	s_addc_u32 s17, s51, 0
	s_add_i32 s20, s43, s54
	global_load_lds_dwordx4 v[220:221], off
	v_lshl_add_u64 v[222:223], s[16:17], 0, v[166:167]
	s_mov_b32 m0, s20
	s_nop 0
	global_load_lds_dwordx4 v[222:223], off
	v_lshl_add_u64 v[222:223], s[16:17], 0, v[170:171]
	s_add_i32 m0, s20, 0x2000
	s_nop 0
	global_load_lds_dwordx4 v[222:223], off
	v_lshl_add_u64 v[222:223], s[52:53], 0, v[164:165]
	s_mov_b32 m0, s55
	s_nop 0
	global_load_lds_dwordx4 v[222:223], off
	v_lshl_add_u64 v[222:223], s[52:53], 0, v[168:169]
	s_mov_b32 m0, s56
	s_nop 0
	global_load_lds_dwordx4 v[222:223], off
	s_waitcnt vmcnt(8)
	s_waitcnt lgkmcnt(0)
	s_barrier
; #define PG8_STAGE(bufoff, gbase, voff) do { _Pragma("unroll") for (int _i = 0; _i < 2; ++_i) \
;         __builtin_amdgcn_global_load_lds((const unsigned*)((const char*)(gbase) + (voff)[_i]), (LAS unsigned*)(lds + (bufoff) + ldsw + _i * 8192), 16, 0, 0); } while (0)
; #define PG8_LDA(dst, b, h) do { _Pragma("unroll") for (int m = 0; m < 4; ++m) _Pragma("unroll") for (int k = 0; k < 2; ++k) dst[m][k] = *(const LAS bf16x8*)(lds + PG8_SA(b, h) + aoff + m * 2048 + k * 1024); } while (0)
; #define PG8_LDB(dst, b, h) do { _Pragma("unroll") for (int n = 0; n < 2; ++n) _Pragma("unroll") for (int k = 0; k < 2; ++k) dst[n][k] = *(const LAS bf16x8*)(lds + PG8_SB(b, h) + boff + n * 2048 + k * 1024); } while (0)
; #define PG8_MMA(ai, bj, At, Bt) do { __builtin_amdgcn_s_setprio(1); _Pragma("unroll") for (int m = 0; m < 4; ++m) _Pragma("unroll") for (int n = 0; n < 2; ++n) _Pragma("unroll") for (int k = 0; k < 2; ++k) \
;         acc[ai][bj][m][n] = __builtin_amdgcn_mfma_f32_16x16x32_bf16(Bt[n][k], At[m][k], acc[ai][bj][m][n], 0, 0, 0); __builtin_amdgcn_s_setprio(0); } while (0)
; #define PG8_WAIT_V(n) asm volatile("s_waitcnt vmcnt(" #n ")" ::: "memory")
; #define PG8_WAIT_L(n) asm volatile("s_waitcnt lgkmcnt(" #n ")" ::: "memory")
; #define PG8_BAR __builtin_amdgcn_s_barrier()
; #define PG8_SCHED __builtin_amdgcn_sched_barrier(0)
; template <class Epi, class Sched>
; __device__ __forceinline__ void gemm_phase(LAS unsigned char* lds, const Gemm g, const Sched& S, const Epi& E, const int tid) {
;     ...
;             PG8_WAIT_V(8); PG8_WAIT_L(0); PG8_BAR; PG8_MMA(1, 0, At, B0); PG8_MMA(1, 1, At, B1); PG8_BAR; PG8_SCHED;
;             PG8_LDB(B0, 1, 0); PG8_LDB(B1, 1, 1); PG8_SCHED; PG8_LDA(At, 1, 0); PG8_STAGE(PG8_SA(0, 1), a2 + hstepA, voffA);
;             PG8_WAIT_V(8); PG8_WAIT_L(0); PG8_BAR; PG8_MMA(0, 0, At, B0); PG8_MMA(0, 1, At, B1); PG8_BAR; PG8_SCHED;
	s_setprio 1
	s_waitcnt lgkmcnt(0)
	v_mfma_f32_16x16x32_bf16 v[100:103], v[84:87], v[160:163], v[100:103]
	v_mfma_f32_16x16x32_bf16 v[96:99], v[136:139], v[160:163], v[96:99]
	v_mfma_f32_16x16x32_bf16 v[88:91], v[84:87], v[186:189], v[88:91]
	v_mfma_f32_16x16x32_bf16 v[80:83], v[136:139], v[186:189], v[80:83]
	v_mfma_f32_16x16x32_bf16 v[76:79], v[84:87], v[194:197], v[76:79]
	v_mfma_f32_16x16x32_bf16 v[72:75], v[136:139], v[194:197], v[72:75]
	v_mfma_f32_16x16x32_bf16 v[68:71], v[84:87], v[212:215], v[68:71]
	v_mfma_f32_16x16x32_bf16 v[64:67], v[136:139], v[212:215], v[64:67]
	v_mfma_f32_16x16x32_bf16 v[100:103], v[92:95], v[182:185], v[100:103]
	v_mfma_f32_16x16x32_bf16 v[96:99], v[140:143], v[182:185], v[96:99]
	v_mfma_f32_16x16x32_bf16 v[88:91], v[92:95], v[190:193], v[88:91]
	v_mfma_f32_16x16x32_bf16 v[80:83], v[140:143], v[190:193], v[80:83]
	v_mfma_f32_16x16x32_bf16 v[76:79], v[92:95], v[208:211], v[76:79]
	v_mfma_f32_16x16x32_bf16 v[72:75], v[140:143], v[208:211], v[72:75]
	v_mfma_f32_16x16x32_bf16 v[68:71], v[92:95], v[216:219], v[68:71]
	v_mfma_f32_16x16x32_bf16 v[64:67], v[140:143], v[216:219], v[64:67]
	s_setprio 0
	s_setprio 1
	v_mfma_f32_16x16x32_bf16 v[28:31], v[144:147], v[160:163], v[28:31]
	v_mfma_f32_16x16x32_bf16 v[24:27], v[152:155], v[160:163], v[24:27]
	v_mfma_f32_16x16x32_bf16 v[20:23], v[144:147], v[186:189], v[20:23]
	v_mfma_f32_16x16x32_bf16 v[16:19], v[152:155], v[186:189], v[16:19]
	v_mfma_f32_16x16x32_bf16 v[12:15], v[144:147], v[194:197], v[12:15]
	v_mfma_f32_16x16x32_bf16 v[8:11], v[152:155], v[194:197], v[8:11]
	v_mfma_f32_16x16x32_bf16 v[4:7], v[144:147], v[212:215], v[4:7]
	v_mfma_f32_16x16x32_bf16 v[0:3], v[152:155], v[212:215], v[0:3]
	v_mfma_f32_16x16x32_bf16 v[28:31], v[148:151], v[182:185], v[28:31]
	v_mfma_f32_16x16x32_bf16 v[24:27], v[156:159], v[182:185], v[24:27]
	v_mfma_f32_16x16x32_bf16 v[20:23], v[148:151], v[190:193], v[20:23]
	v_mfma_f32_16x16x32_bf16 v[16:19], v[156:159], v[190:193], v[16:19]
	v_mfma_f32_16x16x32_bf16 v[12:15], v[148:151], v[208:211], v[12:15]
	v_mfma_f32_16x16x32_bf16 v[8:11], v[156:159], v[208:211], v[8:11]
	v_mfma_f32_16x16x32_bf16 v[4:7], v[148:151], v[216:219], v[4:7]
	v_mfma_f32_16x16x32_bf16 v[0:3], v[156:159], v[216:219], v[0:3]
	s_setprio 0
	s_barrier
	s_add_i32 s20, 0, 0x18000
	s_add_i32 s21, 0, 0x1c000
	v_add_u32_e32 v140, s20, v203
	v_add_u32_e32 v156, s21, v203
	ds_read_b128 v[84:87], v140
	ds_read_b128 v[92:95], v140 offset:1024
	ds_read_b128 v[136:139], v140 offset:2048
	ds_read_b128 v[140:143], v140 offset:3072
	ds_read_b128 v[144:147], v156
	ds_read_b128 v[148:151], v156 offset:1024
	ds_read_b128 v[152:155], v156 offset:2048
	ds_read_b128 v[156:159], v156 offset:3072
	s_add_u32 s16, s52, 0x1000
	s_addc_u32 s17, s53, 0
	s_mov_b32 m0, s57
	v_lshl_add_u64 v[222:223], s[16:17], 0, v[164:165]
	ds_read_b128 v[160:163], v206 offset:32768
	ds_read_b128 v[182:185], v206 offset:33792
	ds_read_b128 v[186:189], v206 offset:34816
	ds_read_b128 v[190:193], v206 offset:35840
	ds_read_b128 v[194:197], v206 offset:36864
	ds_read_b128 v[208:211], v206 offset:37888
	ds_read_b128 v[212:215], v206 offset:38912
	ds_read_b128 v[216:219], v206 offset:39936
	global_load_lds_dwordx4 v[222:223], off
	v_lshl_add_u64 v[222:223], s[16:17], 0, v[168:169]
	s_mov_b32 m0, s58
	s_nop 0
	global_load_lds_dwordx4 v[222:223], off
	s_waitcnt vmcnt(8)
	s_waitcnt lgkmcnt(0)
	s_barrier
	s_setprio 1
	s_waitcnt lgkmcnt(0)
	v_mfma_f32_16x16x32_bf16 v[132:135], v[84:87], v[160:163], v[132:135]
	v_mfma_f32_16x16x32_bf16 v[128:131], v[136:139], v[160:163], v[128:131]
	v_mfma_f32_16x16x32_bf16 v[124:127], v[84:87], v[186:189], v[124:127]
	v_mfma_f32_16x16x32_bf16 v[120:123], v[136:139], v[186:189], v[120:123]
	v_mfma_f32_16x16x32_bf16 v[116:119], v[84:87], v[194:197], v[116:119]
	v_mfma_f32_16x16x32_bf16 v[112:115], v[136:139], v[194:197], v[112:115]
	v_mfma_f32_16x16x32_bf16 v[108:111], v[84:87], v[212:215], v[108:111]
	v_mfma_f32_16x16x32_bf16 v[104:107], v[136:139], v[212:215], v[104:107]
	v_mfma_f32_16x16x32_bf16 v[132:135], v[92:95], v[182:185], v[132:135]
	v_mfma_f32_16x16x32_bf16 v[128:131], v[140:143], v[182:185], v[128:131]
	v_mfma_f32_16x16x32_bf16 v[124:127], v[92:95], v[190:193], v[124:127]
	v_mfma_f32_16x16x32_bf16 v[120:123], v[140:143], v[190:193], v[120:123]
	v_mfma_f32_16x16x32_bf16 v[116:119], v[92:95], v[208:211], v[116:119]
	v_mfma_f32_16x16x32_bf16 v[112:115], v[140:143], v[208:211], v[112:115]
	v_mfma_f32_16x16x32_bf16 v[108:111], v[92:95], v[216:219], v[108:111]
	v_mfma_f32_16x16x32_bf16 v[104:107], v[140:143], v[216:219], v[104:107]
	s_setprio 0
	s_setprio 1
	v_mfma_f32_16x16x32_bf16 v[60:63], v[144:147], v[160:163], v[60:63]
	v_mfma_f32_16x16x32_bf16 v[56:59], v[152:155], v[160:163], v[56:59]
	v_mfma_f32_16x16x32_bf16 v[52:55], v[144:147], v[186:189], v[52:55]
	v_mfma_f32_16x16x32_bf16 v[48:51], v[152:155], v[186:189], v[48:51]
	v_mfma_f32_16x16x32_bf16 v[44:47], v[144:147], v[194:197], v[44:47]
	v_mfma_f32_16x16x32_bf16 v[40:43], v[152:155], v[194:197], v[40:43]
	v_mfma_f32_16x16x32_bf16 v[36:39], v[144:147], v[212:215], v[36:39]
	v_mfma_f32_16x16x32_bf16 v[32:35], v[152:155], v[212:215], v[32:35]
	v_mfma_f32_16x16x32_bf16 v[60:63], v[148:151], v[182:185], v[60:63]
	v_mfma_f32_16x16x32_bf16 v[56:59], v[156:159], v[182:185], v[56:59]
	v_mfma_f32_16x16x32_bf16 v[52:55], v[148:151], v[190:193], v[52:55]
	v_mfma_f32_16x16x32_bf16 v[48:51], v[156:159], v[190:193], v[48:51]
	v_mfma_f32_16x16x32_bf16 v[44:47], v[148:151], v[208:211], v[44:47]
	v_mfma_f32_16x16x32_bf16 v[40:43], v[156:159], v[208:211], v[40:43]
	v_mfma_f32_16x16x32_bf16 v[36:39], v[148:151], v[216:219], v[36:39]
	v_mfma_f32_16x16x32_bf16 v[32:35], v[156:159], v[216:219], v[32:35]
	s_setprio 0
	s_barrier
; #define PG8_STAGE(bufoff, gbase, voff) do { _Pragma("unroll") for (int _i = 0; _i < 2; ++_i) \
;         __builtin_amdgcn_global_load_lds((const unsigned*)((const char*)(gbase) + (voff)[_i]), (LAS unsigned*)(lds + (bufoff) + ldsw + _i * 8192), 16, 0, 0); } while (0)
; #define PG8_LDA(dst, b, h) do { _Pragma("unroll") for (int m = 0; m < 4; ++m) _Pragma("unroll") for (int k = 0; k < 2; ++k) dst[m][k] = *(const LAS bf16x8*)(lds + PG8_SA(b, h) + aoff + m * 2048 + k * 1024); } while (0)
; #define PG8_MMA(ai, bj, At, Bt) do { __builtin_amdgcn_s_setprio(1); _Pragma("unroll") for (int m = 0; m < 4; ++m) _Pragma("unroll") for (int n = 0; n < 2; ++n) _Pragma("unroll") for (int k = 0; k < 2; ++k) \
;         acc[ai][bj][m][n] = __builtin_amdgcn_mfma_f32_16x16x32_bf16(Bt[n][k], At[m][k], acc[ai][bj][m][n], 0, 0, 0); __builtin_amdgcn_s_setprio(0); } while (0)
; #define PG8_WAIT_V(n) asm volatile("s_waitcnt vmcnt(" #n ")" ::: "memory")
; #define PG8_WAIT_L(n) asm volatile("s_waitcnt lgkmcnt(" #n ")" ::: "memory")
; #define PG8_BAR __builtin_amdgcn_s_barrier()
; #define PG8_SCHED __builtin_amdgcn_sched_barrier(0)
; template <class Epi, class Sched>
; __device__ __forceinline__ void gemm_phase(LAS unsigned char* lds, const Gemm g, const Sched& S, const Epi& E, const int tid) {
;     ...
;         for (int t = 0; t < nt; t += 2) {
;             const bool last = (t == nt - 2);
;             const char* a1 = cA + (size_t)(t + 1) * kstepA;
;             const char* a2 = last ? nA : cA + (size_t)(t + 2) * kstepA; const char* b2 = last ? nB : cB + (size_t)(t + 2) * kstep;
;     ...
;             PG8_LDA(At, 1, 1); PG8_STAGE(PG8_SB(1, 0), b3, voffB); PG8_STAGE(PG8_SB(1, 1), b3 + hstepB, voffB); PG8_STAGE(PG8_SA(1, 0), a3, voffA);
;             PG8_WAIT_V(8); PG8_WAIT_L(0); PG8_BAR; PG8_MMA(1, 0, At, B0); PG8_MMA(1, 1, At, B1); PG8_BAR; PG8_SCHED;
;         }
	s_add_i32 s16, s20, s54
	v_lshl_add_u64 v[198:199], v[198:199], 0, s[4:5]
	s_mov_b32 m0, s16
	ds_read_b128 v[160:163], v206 offset:49152
	ds_read_b128 v[182:185], v206 offset:50176
	ds_read_b128 v[186:189], v206 offset:51200
	ds_read_b128 v[190:193], v206 offset:52224
	ds_read_b128 v[194:197], v206 offset:53248
	ds_read_b128 v[208:211], v206 offset:54272
	ds_read_b128 v[212:215], v206 offset:55296
	ds_read_b128 v[216:219], v206 offset:56320
	global_load_lds_dwordx4 v[198:199], off
	s_add_i32 m0, s16, 0x2000
	s_add_u32 s16, s50, 0x40080
	v_lshl_add_u64 v[198:199], v[220:221], 0, s[4:5]
	s_addc_u32 s17, s51, 0
	s_add_i32 s20, s21, s54
	global_load_lds_dwordx4 v[198:199], off
	v_lshl_add_u64 v[198:199], s[16:17], 0, v[166:167]
	s_mov_b32 m0, s20
	s_nop 0
	global_load_lds_dwordx4 v[198:199], off
	v_lshl_add_u64 v[198:199], s[16:17], 0, v[170:171]
	s_add_i32 m0, s20, 0x2000
	s_nop 0
	global_load_lds_dwordx4 v[198:199], off
	v_lshl_add_u64 v[198:199], s[48:49], 0, v[164:165]
	s_mov_b32 m0, s62
	s_nop 0
	global_load_lds_dwordx4 v[198:199], off
	v_lshl_add_u64 v[198:199], s[48:49], 0, v[168:169]
	s_mov_b32 m0, s64
	s_nop 0
	global_load_lds_dwordx4 v[198:199], off
	s_waitcnt vmcnt(8)
	s_waitcnt lgkmcnt(0)
	s_barrier
	s_setprio 1
	s_waitcnt lgkmcnt(0)
	v_mfma_f32_16x16x32_bf16 v[100:103], v[84:87], v[160:163], v[100:103]
	v_mfma_f32_16x16x32_bf16 v[96:99], v[136:139], v[160:163], v[96:99]
	v_mfma_f32_16x16x32_bf16 v[88:91], v[84:87], v[186:189], v[88:91]
	v_mfma_f32_16x16x32_bf16 v[80:83], v[136:139], v[186:189], v[80:83]
	v_mfma_f32_16x16x32_bf16 v[76:79], v[84:87], v[194:197], v[76:79]
	v_mfma_f32_16x16x32_bf16 v[72:75], v[136:139], v[194:197], v[72:75]
	v_mfma_f32_16x16x32_bf16 v[68:71], v[84:87], v[212:215], v[68:71]
	v_mfma_f32_16x16x32_bf16 v[64:67], v[136:139], v[212:215], v[64:67]
	v_mfma_f32_16x16x32_bf16 v[100:103], v[92:95], v[182:185], v[100:103]
	v_mfma_f32_16x16x32_bf16 v[96:99], v[140:143], v[182:185], v[96:99]
	v_mfma_f32_16x16x32_bf16 v[88:91], v[92:95], v[190:193], v[88:91]
	v_mfma_f32_16x16x32_bf16 v[80:83], v[140:143], v[190:193], v[80:83]
	v_mfma_f32_16x16x32_bf16 v[76:79], v[92:95], v[208:211], v[76:79]
	v_mfma_f32_16x16x32_bf16 v[72:75], v[140:143], v[208:211], v[72:75]
	v_mfma_f32_16x16x32_bf16 v[68:71], v[92:95], v[216:219], v[68:71]
	v_mfma_f32_16x16x32_bf16 v[64:67], v[140:143], v[216:219], v[64:67]
	s_setprio 0
	s_setprio 1
	v_mfma_f32_16x16x32_bf16 v[28:31], v[144:147], v[160:163], v[28:31]
	v_mfma_f32_16x16x32_bf16 v[24:27], v[152:155], v[160:163], v[24:27]
	v_mfma_f32_16x16x32_bf16 v[20:23], v[144:147], v[186:189], v[20:23]
	v_mfma_f32_16x16x32_bf16 v[16:19], v[152:155], v[186:189], v[16:19]
	v_mfma_f32_16x16x32_bf16 v[12:15], v[144:147], v[194:197], v[12:15]
	v_mfma_f32_16x16x32_bf16 v[8:11], v[152:155], v[194:197], v[8:11]
	v_mfma_f32_16x16x32_bf16 v[4:7], v[144:147], v[212:215], v[4:7]
	v_mfma_f32_16x16x32_bf16 v[0:3], v[152:155], v[212:215], v[0:3]
	v_mfma_f32_16x16x32_bf16 v[28:31], v[148:151], v[182:185], v[28:31]
	v_mfma_f32_16x16x32_bf16 v[24:27], v[156:159], v[182:185], v[24:27]
	v_mfma_f32_16x16x32_bf16 v[20:23], v[148:151], v[190:193], v[20:23]
	v_mfma_f32_16x16x32_bf16 v[16:19], v[156:159], v[190:193], v[16:19]
	v_mfma_f32_16x16x32_bf16 v[12:15], v[148:151], v[208:211], v[12:15]
	v_mfma_f32_16x16x32_bf16 v[8:11], v[156:159], v[208:211], v[8:11]
	v_mfma_f32_16x16x32_bf16 v[4:7], v[148:151], v[216:219], v[4:7]
	v_mfma_f32_16x16x32_bf16 v[0:3], v[156:159], v[216:219], v[0:3]
	s_setprio 0
	s_add_i32 s75, s75, 2
	s_add_u32 s72, s72, 0x100
	s_addc_u32 s73, s73, 0
	s_cmp_gt_u32 s75, 13
	s_mov_b64 s[38:39], s[40:41]
	s_barrier
	s_cbranch_scc0 .LBB0_1040
	s_and_b64 vcc, exec, s[6:7]
	s_cbranch_vccz .LBB0_1043
	s_barrier

; #define PG8_STAGE(bufoff, gbase, voff) do { _Pragma("unroll") for (int _i = 0; _i < 2; ++_i) \
;         __builtin_amdgcn_global_load_lds((const unsigned*)((const char*)(gbase) + (voff)[_i]), (LAS unsigned*)(lds + (bufoff) + ldsw + _i * 8192), 16, 0, 0); } while (0)
; #define PG8_LDA(dst, b, h) do { _Pragma("unroll") for (int m = 0; m < 4; ++m) _Pragma("unroll") for (int k = 0; k < 2; ++k) dst[m][k] = *(const LAS bf16x8*)(lds + PG8_SA(b, h) + aoff + m * 2048 + k * 1024); } while (0)
; #define PG8_LDB(dst, b, h) do { _Pragma("unroll") for (int n = 0; n < 2; ++n) _Pragma("unroll") for (int k = 0; k < 2; ++k) dst[n][k] = *(const LAS bf16x8*)(lds + PG8_SB(b, h) + boff + n * 2048 + k * 1024); } while (0)
; #define PG8_MMA(ai, bj, At, Bt) do { __builtin_amdgcn_s_setprio(1); _Pragma("unroll") for (int m = 0; m < 4; ++m) _Pragma("unroll") for (int n = 0; n < 2; ++n) _Pragma("unroll") for (int k = 0; k < 2; ++k) \
;         acc[ai][bj][m][n] = __builtin_amdgcn_mfma_f32_16x16x32_bf16(Bt[n][k], At[m][k], acc[ai][bj][m][n], 0, 0, 0); __builtin_amdgcn_s_setprio(0); } while (0)
; #define PG8_WAIT_V(n) asm volatile("s_waitcnt vmcnt(" #n ")" ::: "memory")
; #define PG8_WAIT_L(n) asm volatile("s_waitcnt lgkmcnt(" #n ")" ::: "memory")
; #define PG8_BAR __builtin_amdgcn_s_barrier()
; template <class Epi, class Sched>
; __device__ __forceinline__ void gemm_phase(LAS unsigned char* lds, const Gemm g, const Sched& S, const Epi& E, const int tid) {
;     ...
;             const bool last = (t == nt - 2);
;             const char* a1 = cA + (size_t)(t + 1) * kstepA;
;             const char* a2 = last ? nA : cA + (size_t)(t + 2) * kstepA; const char* b2 = last ? nB : cB + (size_t)(t + 2) * kstep;
;             const char* a3 = a2 + kstepA; const char* b3 = b2 + kstep;
;             if constexpr (Epi::HAS_MID) { if (t == g.tmid) E.mid(acc, cur, ui, wr, wc, fr, fq); }
;             PG8_LDB(B0, 0, 0); PG8_LDB(B1, 0, 1); PG8_SCHED; PG8_LDA(At, 0, 0); PG8_STAGE(PG8_SA(1, 1), a1 + hstepA, voffA);
;             PG8_WAIT_V(8); PG8_WAIT_L(0); PG8_BAR; PG8_MMA(0, 0, At, B0); PG8_MMA(0, 1, At, B1); PG8_BAR; PG8_SCHED;
;             PG8_LDA(At, 0, 1); PG8_STAGE(PG8_SB(0, 0), b2, voffB); PG8_STAGE(PG8_SB(0, 1), b2 + hstepB, voffB); PG8_STAGE(PG8_SA(0, 0), a2, voffA);
;             PG8_WAIT_V(8); PG8_WAIT_L(0); PG8_BAR; PG8_MMA(1, 0, At, B0); PG8_MMA(1, 1, At, B1); PG8_BAR; PG8_SCHED;
.LBB0_1150:
	v_add_u32_e32 v1, s67, v252
	ds_read_b128 v[132:135], v1
	ds_read_b128 v[136:139], v1 offset:1024
	ds_read_b128 v[140:143], v1 offset:2048
	ds_read_b128 v[144:147], v1 offset:3072
	v_add_u32_e32 v1, s68, v252
	s_add_u32 s16, s38, s50
	ds_read_b128 v[148:151], v1
	ds_read_b128 v[156:159], v1 offset:1024
	ds_read_b128 v[164:167], v1 offset:2048
	ds_read_b128 v[168:171], v1 offset:3072
	s_addc_u32 s17, s39, s51
	s_add_u32 s16, s16, 0x100
	s_addc_u32 s17, s17, 0
	s_add_u32 s20, s70, s50
	s_addc_u32 s21, s71, s51
	s_cmpk_eq_i32 s50, 0xf00
	s_cselect_b32 s55, s7, s17
	s_cselect_b32 s54, s9, s16
	s_cselect_b32 s53, s18, s21
	s_cselect_b32 s52, s35, s20
	v_lshl_add_u64 v[2:3], v[68:69], 0, s[50:51]
	s_add_i32 m0, s56, 0xc000
	ds_read_b128 v[172:175], v208
	ds_read_b128 v[176:179], v208 offset:1024
	ds_read_b128 v[180:183], v208 offset:2048
	ds_read_b128 v[184:187], v208 offset:3072
	ds_read_b128 v[188:191], v208 offset:4096
	ds_read_b128 v[192:195], v208 offset:5120
	ds_read_b128 v[210:213], v208 offset:6144
	ds_read_b128 v[214:217], v208 offset:7168
	global_load_lds_dwordx4 v[2:3], off
	v_lshl_add_u64 v[2:3], v[70:71], 0, s[50:51]
	s_add_i32 m0, s56, 0xe000
	s_nop 0
	global_load_lds_dwordx4 v[2:3], off
	s_waitcnt vmcnt(8)
	s_waitcnt lgkmcnt(0)
	s_barrier
	s_setprio 1
	s_waitcnt lgkmcnt(0)
	v_mfma_f32_16x16x32_bf16 v[160:163], v[132:135], v[172:175], v[160:163]
	v_mfma_f32_16x16x32_bf16 v[152:155], v[140:143], v[172:175], v[152:155]
	v_mfma_f32_16x16x32_bf16 v[128:131], v[132:135], v[180:183], v[128:131]
	v_mfma_f32_16x16x32_bf16 v[124:127], v[140:143], v[180:183], v[124:127]
	v_mfma_f32_16x16x32_bf16 v[120:123], v[132:135], v[188:191], v[120:123]
	v_mfma_f32_16x16x32_bf16 v[116:119], v[140:143], v[188:191], v[116:119]
	v_mfma_f32_16x16x32_bf16 v[112:115], v[132:135], v[210:213], v[112:115]
	v_mfma_f32_16x16x32_bf16 v[108:111], v[140:143], v[210:213], v[108:111]
	v_mfma_f32_16x16x32_bf16 v[160:163], v[136:139], v[176:179], v[160:163]
	v_mfma_f32_16x16x32_bf16 v[152:155], v[144:147], v[176:179], v[152:155]
	v_mfma_f32_16x16x32_bf16 v[128:131], v[136:139], v[184:187], v[128:131]
	v_mfma_f32_16x16x32_bf16 v[124:127], v[144:147], v[184:187], v[124:127]
	v_mfma_f32_16x16x32_bf16 v[120:123], v[136:139], v[192:195], v[120:123]
	v_mfma_f32_16x16x32_bf16 v[116:119], v[144:147], v[192:195], v[116:119]
	v_mfma_f32_16x16x32_bf16 v[112:115], v[136:139], v[214:217], v[112:115]
	v_mfma_f32_16x16x32_bf16 v[108:111], v[144:147], v[214:217], v[108:111]
	s_setprio 0
	s_setprio 1
	v_mfma_f32_16x16x32_bf16 v[64:67], v[148:151], v[172:175], v[64:67]
	v_mfma_f32_16x16x32_bf16 v[60:63], v[164:167], v[172:175], v[60:63]
	v_mfma_f32_16x16x32_bf16 v[56:59], v[148:151], v[180:183], v[56:59]
	v_mfma_f32_16x16x32_bf16 v[52:55], v[164:167], v[180:183], v[52:55]
	v_mfma_f32_16x16x32_bf16 v[48:51], v[148:151], v[188:191], v[48:51]
	v_mfma_f32_16x16x32_bf16 v[44:47], v[164:167], v[188:191], v[44:47]
	v_mfma_f32_16x16x32_bf16 v[40:43], v[148:151], v[210:213], v[40:43]
	v_mfma_f32_16x16x32_bf16 v[36:39], v[164:167], v[210:213], v[36:39]
	v_mfma_f32_16x16x32_bf16 v[64:67], v[156:159], v[176:179], v[64:67]
	v_mfma_f32_16x16x32_bf16 v[60:63], v[168:171], v[176:179], v[60:63]
	v_mfma_f32_16x16x32_bf16 v[56:59], v[156:159], v[184:187], v[56:59]
	v_mfma_f32_16x16x32_bf16 v[52:55], v[168:171], v[184:187], v[52:55]
	v_mfma_f32_16x16x32_bf16 v[48:51], v[156:159], v[192:195], v[48:51]
	v_mfma_f32_16x16x32_bf16 v[44:47], v[168:171], v[192:195], v[44:47]
	v_mfma_f32_16x16x32_bf16 v[40:43], v[156:159], v[214:217], v[40:43]
	v_mfma_f32_16x16x32_bf16 v[36:39], v[168:171], v[214:217], v[36:39]
	s_setprio 0
	s_barrier
	s_add_i32 s16, s67, s43
	v_lshl_add_u64 v[218:219], s[52:53], 0, v[198:199]
	s_mov_b32 m0, s16
	ds_read_b128 v[172:175], v208 offset:16384
	ds_read_b128 v[176:179], v208 offset:17408
	ds_read_b128 v[180:183], v208 offset:18432
	ds_read_b128 v[184:187], v208 offset:19456
	ds_read_b128 v[188:191], v208 offset:20480
	ds_read_b128 v[192:195], v208 offset:21504
	ds_read_b128 v[210:213], v208 offset:22528
	ds_read_b128 v[214:217], v208 offset:23552
	global_load_lds_dwordx4 v[218:219], off
	s_add_i32 m0, s16, 0x2000
	s_add_u32 s16, s52, 0x80000
	v_lshl_add_u64 v[220:221], s[52:53], 0, v[202:203]
	s_addc_u32 s17, s53, 0
	s_add_i32 s20, s68, s43
	global_load_lds_dwordx4 v[220:221], off
	v_lshl_add_u64 v[2:3], s[16:17], 0, v[198:199]
	s_mov_b32 m0, s20
	v_lshl_add_u64 v[222:223], s[54:55], 0, v[196:197]
	global_load_lds_dwordx4 v[2:3], off
	v_lshl_add_u64 v[2:3], s[16:17], 0, v[202:203]
	s_add_i32 m0, s20, 0x2000
	v_lshl_add_u64 v[224:225], s[54:55], 0, v[200:201]
	global_load_lds_dwordx4 v[2:3], off
	s_mov_b32 m0, s56
	s_nop 0
	global_load_lds_dwordx4 v[222:223], off
	s_mov_b32 m0, s57
	s_nop 0
	global_load_lds_dwordx4 v[224:225], off
	s_waitcnt vmcnt(8)
	s_waitcnt lgkmcnt(0)
	s_barrier
; #define PG8_STAGE(bufoff, gbase, voff) do { _Pragma("unroll") for (int _i = 0; _i < 2; ++_i) \
;         __builtin_amdgcn_global_load_lds((const unsigned*)((const char*)(gbase) + (voff)[_i]), (LAS unsigned*)(lds + (bufoff) + ldsw + _i * 8192), 16, 0, 0); } while (0)
; #define PG8_LDA(dst, b, h) do { _Pragma("unroll") for (int m = 0; m < 4; ++m) _Pragma("unroll") for (int k = 0; k < 2; ++k) dst[m][k] = *(const LAS bf16x8*)(lds + PG8_SA(b, h) + aoff + m * 2048 + k * 1024); } while (0)
; #define PG8_LDB(dst, b, h) do { _Pragma("unroll") for (int n = 0; n < 2; ++n) _Pragma("unroll") for (int k = 0; k < 2; ++k) dst[n][k] = *(const LAS bf16x8*)(lds + PG8_SB(b, h) + boff + n * 2048 + k * 1024); } while (0)
; #define PG8_MMA(ai, bj, At, Bt) do { __builtin_amdgcn_s_setprio(1); _Pragma("unroll") for (int m = 0; m < 4; ++m) _Pragma("unroll") for (int n = 0; n < 2; ++n) _Pragma("unroll") for (int k = 0; k < 2; ++k) \
;         acc[ai][bj][m][n] = __builtin_amdgcn_mfma_f32_16x16x32_bf16(Bt[n][k], At[m][k], acc[ai][bj][m][n], 0, 0, 0); __builtin_amdgcn_s_setprio(0); } while (0)
; #define PG8_WAIT_V(n) asm volatile("s_waitcnt vmcnt(" #n ")" ::: "memory")
; #define PG8_WAIT_L(n) asm volatile("s_waitcnt lgkmcnt(" #n ")" ::: "memory")
; #define PG8_BAR __builtin_amdgcn_s_barrier()
; #define PG8_SCHED __builtin_amdgcn_sched_barrier(0)
; template <class Epi, class Sched>
; __device__ __forceinline__ void gemm_phase(LAS unsigned char* lds, const Gemm g, const Sched& S, const Epi& E, const int tid) {
;     ...
;             PG8_WAIT_V(8); PG8_WAIT_L(0); PG8_BAR; PG8_MMA(1, 0, At, B0); PG8_MMA(1, 1, At, B1); PG8_BAR; PG8_SCHED;
;             PG8_LDB(B0, 1, 0); PG8_LDB(B1, 1, 1); PG8_SCHED; PG8_LDA(At, 1, 0); PG8_STAGE(PG8_SA(0, 1), a2 + hstepA, voffA);
;             PG8_WAIT_V(8); PG8_WAIT_L(0); PG8_BAR; PG8_MMA(0, 0, At, B0); PG8_MMA(0, 1, At, B1); PG8_BAR; PG8_SCHED;
	s_setprio 1
	s_waitcnt lgkmcnt(0)
	v_mfma_f32_16x16x32_bf16 v[104:107], v[132:135], v[172:175], v[104:107]
	v_mfma_f32_16x16x32_bf16 v[100:103], v[140:143], v[172:175], v[100:103]
	v_mfma_f32_16x16x32_bf16 v[96:99], v[132:135], v[180:183], v[96:99]
	v_mfma_f32_16x16x32_bf16 v[92:95], v[140:143], v[180:183], v[92:95]
	v_mfma_f32_16x16x32_bf16 v[88:91], v[132:135], v[188:191], v[88:91]
	v_mfma_f32_16x16x32_bf16 v[84:87], v[140:143], v[188:191], v[84:87]
	v_mfma_f32_16x16x32_bf16 v[80:83], v[132:135], v[210:213], v[80:83]
	v_mfma_f32_16x16x32_bf16 v[74:77], v[140:143], v[210:213], v[76:79]
	v_mfma_f32_16x16x32_bf16 v[104:107], v[136:139], v[176:179], v[104:107]
	v_mfma_f32_16x16x32_bf16 v[100:103], v[144:147], v[176:179], v[100:103]
	v_mfma_f32_16x16x32_bf16 v[96:99], v[136:139], v[184:187], v[96:99]
	v_mfma_f32_16x16x32_bf16 v[92:95], v[144:147], v[184:187], v[92:95]
	v_mfma_f32_16x16x32_bf16 v[88:91], v[136:139], v[192:195], v[88:91]
	v_mfma_f32_16x16x32_bf16 v[84:87], v[144:147], v[192:195], v[84:87]
	v_mfma_f32_16x16x32_bf16 v[80:83], v[136:139], v[214:217], v[80:83]
	v_mfma_f32_16x16x32_bf16 v[74:77], v[144:147], v[214:217], v[74:77]
	s_setprio 0
	s_setprio 1
	v_mfma_f32_16x16x32_bf16 v[32:35], v[148:151], v[172:175], v[32:35]
	v_mfma_f32_16x16x32_bf16 v[28:31], v[164:167], v[172:175], v[28:31]
	v_mfma_f32_16x16x32_bf16 v[24:27], v[148:151], v[180:183], v[24:27]
	v_mfma_f32_16x16x32_bf16 v[20:23], v[164:167], v[180:183], v[20:23]
	v_mfma_f32_16x16x32_bf16 v[16:19], v[148:151], v[188:191], v[16:19]
	v_mfma_f32_16x16x32_bf16 v[12:15], v[164:167], v[188:191], v[12:15]
	v_mfma_f32_16x16x32_bf16 v[8:11], v[148:151], v[210:213], v[8:11]
	v_mfma_f32_16x16x32_bf16 v[2:5], v[164:167], v[210:213], v[4:7]
	v_mfma_f32_16x16x32_bf16 v[32:35], v[156:159], v[176:179], v[32:35]
	v_mfma_f32_16x16x32_bf16 v[28:31], v[168:171], v[176:179], v[28:31]
	v_mfma_f32_16x16x32_bf16 v[24:27], v[156:159], v[184:187], v[24:27]
	v_mfma_f32_16x16x32_bf16 v[20:23], v[168:171], v[184:187], v[20:23]
	v_mfma_f32_16x16x32_bf16 v[16:19], v[156:159], v[192:195], v[16:19]
	v_mfma_f32_16x16x32_bf16 v[12:15], v[168:171], v[192:195], v[12:15]
	v_mfma_f32_16x16x32_bf16 v[8:11], v[156:159], v[214:217], v[8:11]
	v_mfma_f32_16x16x32_bf16 v[2:5], v[168:171], v[214:217], v[2:5]
	s_setprio 0
	s_barrier
	s_add_i32 s20, 0, 0x18000
	v_add_u32_e32 v1, s20, v252
	s_add_i32 s21, 0, 0x1c000
	ds_read_b128 v[132:135], v1
	ds_read_b128 v[136:139], v1 offset:1024
	ds_read_b128 v[140:143], v1 offset:2048
	ds_read_b128 v[144:147], v1 offset:3072
	v_add_u32_e32 v1, s21, v252
	ds_read_b128 v[148:151], v1
	ds_read_b128 v[156:159], v1 offset:1024
	ds_read_b128 v[164:167], v1 offset:2048
	ds_read_b128 v[168:171], v1 offset:3072
	s_add_u32 s16, s54, 0x80000
	s_addc_u32 s17, s55, 0
	s_mov_b32 m0, s58
	v_lshl_add_u64 v[6:7], s[16:17], 0, v[196:197]
	ds_read_b128 v[172:175], v208 offset:32768
	ds_read_b128 v[176:179], v208 offset:33792
	ds_read_b128 v[180:183], v208 offset:34816
	ds_read_b128 v[184:187], v208 offset:35840
	ds_read_b128 v[188:191], v208 offset:36864
	ds_read_b128 v[192:195], v208 offset:37888
	ds_read_b128 v[210:213], v208 offset:38912
	ds_read_b128 v[214:217], v208 offset:39936
	global_load_lds_dwordx4 v[6:7], off
	v_lshl_add_u64 v[6:7], s[16:17], 0, v[200:201]
	s_mov_b32 m0, s59
	s_nop 0
	global_load_lds_dwordx4 v[6:7], off
	s_waitcnt vmcnt(8)
	s_waitcnt lgkmcnt(0)
	s_barrier
	s_setprio 1
	s_waitcnt lgkmcnt(0)
	v_mfma_f32_16x16x32_bf16 v[160:163], v[132:135], v[172:175], v[160:163]
	v_mfma_f32_16x16x32_bf16 v[152:155], v[140:143], v[172:175], v[152:155]
	v_mfma_f32_16x16x32_bf16 v[128:131], v[132:135], v[180:183], v[128:131]
	v_mfma_f32_16x16x32_bf16 v[124:127], v[140:143], v[180:183], v[124:127]
	v_mfma_f32_16x16x32_bf16 v[120:123], v[132:135], v[188:191], v[120:123]
	v_mfma_f32_16x16x32_bf16 v[116:119], v[140:143], v[188:191], v[116:119]
	v_mfma_f32_16x16x32_bf16 v[112:115], v[132:135], v[210:213], v[112:115]
	v_mfma_f32_16x16x32_bf16 v[108:111], v[140:143], v[210:213], v[108:111]
	v_mfma_f32_16x16x32_bf16 v[160:163], v[136:139], v[176:179], v[160:163]
	v_mfma_f32_16x16x32_bf16 v[152:155], v[144:147], v[176:179], v[152:155]
	v_mfma_f32_16x16x32_bf16 v[128:131], v[136:139], v[184:187], v[128:131]
	v_mfma_f32_16x16x32_bf16 v[124:127], v[144:147], v[184:187], v[124:127]
	v_mfma_f32_16x16x32_bf16 v[120:123], v[136:139], v[192:195], v[120:123]
	v_mfma_f32_16x16x32_bf16 v[116:119], v[144:147], v[192:195], v[116:119]
	v_mfma_f32_16x16x32_bf16 v[112:115], v[136:139], v[214:217], v[112:115]
	v_mfma_f32_16x16x32_bf16 v[108:111], v[144:147], v[214:217], v[108:111]
	s_setprio 0
	s_setprio 1
	v_mfma_f32_16x16x32_bf16 v[64:67], v[148:151], v[172:175], v[64:67]
	v_mfma_f32_16x16x32_bf16 v[60:63], v[164:167], v[172:175], v[60:63]
	v_mfma_f32_16x16x32_bf16 v[56:59], v[148:151], v[180:183], v[56:59]
	v_mfma_f32_16x16x32_bf16 v[52:55], v[164:167], v[180:183], v[52:55]
	v_mfma_f32_16x16x32_bf16 v[48:51], v[148:151], v[188:191], v[48:51]
	v_mfma_f32_16x16x32_bf16 v[44:47], v[164:167], v[188:191], v[44:47]
	v_mfma_f32_16x16x32_bf16 v[40:43], v[148:151], v[210:213], v[40:43]
	v_mfma_f32_16x16x32_bf16 v[36:39], v[164:167], v[210:213], v[36:39]
	v_mfma_f32_16x16x32_bf16 v[64:67], v[156:159], v[176:179], v[64:67]
	v_mfma_f32_16x16x32_bf16 v[60:63], v[168:171], v[176:179], v[60:63]
	v_mfma_f32_16x16x32_bf16 v[56:59], v[156:159], v[184:187], v[56:59]
	v_mfma_f32_16x16x32_bf16 v[52:55], v[168:171], v[184:187], v[52:55]
	v_mfma_f32_16x16x32_bf16 v[48:51], v[156:159], v[192:195], v[48:51]
	v_mfma_f32_16x16x32_bf16 v[44:47], v[168:171], v[192:195], v[44:47]
	v_mfma_f32_16x16x32_bf16 v[40:43], v[156:159], v[214:217], v[40:43]
	v_mfma_f32_16x16x32_bf16 v[36:39], v[168:171], v[214:217], v[36:39]
	s_setprio 0
	s_barrier
; #define PG8_STAGE(bufoff, gbase, voff) do { _Pragma("unroll") for (int _i = 0; _i < 2; ++_i) \
;         __builtin_amdgcn_global_load_lds((const unsigned*)((const char*)(gbase) + (voff)[_i]), (LAS unsigned*)(lds + (bufoff) + ldsw + _i * 8192), 16, 0, 0); } while (0)
; #define PG8_LDA(dst, b, h) do { _Pragma("unroll") for (int m = 0; m < 4; ++m) _Pragma("unroll") for (int k = 0; k < 2; ++k) dst[m][k] = *(const LAS bf16x8*)(lds + PG8_SA(b, h) + aoff + m * 2048 + k * 1024); } while (0)
; #define PG8_MMA(ai, bj, At, Bt) do { __builtin_amdgcn_s_setprio(1); _Pragma("unroll") for (int m = 0; m < 4; ++m) _Pragma("unroll") for (int n = 0; n < 2; ++n) _Pragma("unroll") for (int k = 0; k < 2; ++k) \
;         acc[ai][bj][m][n] = __builtin_amdgcn_mfma_f32_16x16x32_bf16(Bt[n][k], At[m][k], acc[ai][bj][m][n], 0, 0, 0); __builtin_amdgcn_s_setprio(0); } while (0)
; #define PG8_WAIT_V(n) asm volatile("s_waitcnt vmcnt(" #n ")" ::: "memory")
; #define PG8_WAIT_L(n) asm volatile("s_waitcnt lgkmcnt(" #n ")" ::: "memory")
; #define PG8_BAR __builtin_amdgcn_s_barrier()
; #define PG8_SCHED __builtin_amdgcn_sched_barrier(0)
; template <class Epi, class Sched>
; __device__ __forceinline__ void gemm_phase(LAS unsigned char* lds, const Gemm g, const Sched& S, const Epi& E, const int tid) {
;     ...
;         for (int t = 0; t < nt; t += 2) {
;             const bool last = (t == nt - 2);
;             const char* a1 = cA + (size_t)(t + 1) * kstepA;
;             const char* a2 = last ? nA : cA + (size_t)(t + 2) * kstepA; const char* b2 = last ? nB : cB + (size_t)(t + 2) * kstep;
;     ...
;             PG8_LDA(At, 1, 1); PG8_STAGE(PG8_SB(1, 0), b3, voffB); PG8_STAGE(PG8_SB(1, 1), b3 + hstepB, voffB); PG8_STAGE(PG8_SA(1, 0), a3, voffA);
;             PG8_WAIT_V(8); PG8_WAIT_L(0); PG8_BAR; PG8_MMA(1, 0, At, B0); PG8_MMA(1, 1, At, B1); PG8_BAR; PG8_SCHED;
;         }
	s_add_i32 s16, s20, s43
	v_lshl_add_u64 v[6:7], v[218:219], 0, s[26:27]
	s_mov_b32 m0, s16
	ds_read_b128 v[172:175], v208 offset:49152
	ds_read_b128 v[176:179], v208 offset:50176
	ds_read_b128 v[180:183], v208 offset:51200
	ds_read_b128 v[184:187], v208 offset:52224
	ds_read_b128 v[188:191], v208 offset:53248
	ds_read_b128 v[192:195], v208 offset:54272
	ds_read_b128 v[210:213], v208 offset:55296
	ds_read_b128 v[214:217], v208 offset:56320
	global_load_lds_dwordx4 v[6:7], off
	s_add_i32 m0, s16, 0x2000
	s_add_u32 s16, s52, 0x80080
	v_lshl_add_u64 v[6:7], v[220:221], 0, s[26:27]
	s_addc_u32 s17, s53, 0
	s_add_i32 s20, s21, s43
	global_load_lds_dwordx4 v[6:7], off
	v_lshl_add_u64 v[6:7], s[16:17], 0, v[198:199]
	s_mov_b32 m0, s20
	s_nop 0
	global_load_lds_dwordx4 v[6:7], off
	v_lshl_add_u64 v[6:7], s[16:17], 0, v[202:203]
	s_add_i32 m0, s20, 0x2000
	s_nop 0
	global_load_lds_dwordx4 v[6:7], off
	v_lshl_add_u64 v[6:7], v[222:223], 0, s[26:27]
	s_mov_b32 m0, s63
	s_nop 0
	global_load_lds_dwordx4 v[6:7], off
	v_lshl_add_u64 v[6:7], v[224:225], 0, s[26:27]
	s_mov_b32 m0, s64
	s_nop 0
	global_load_lds_dwordx4 v[6:7], off
	s_waitcnt vmcnt(8)
	s_waitcnt lgkmcnt(0)
	s_barrier
	s_setprio 1
	s_waitcnt lgkmcnt(0)
	v_mfma_f32_16x16x32_bf16 v[104:107], v[132:135], v[172:175], v[104:107]
	v_mfma_f32_16x16x32_bf16 v[100:103], v[140:143], v[172:175], v[100:103]
	v_mfma_f32_16x16x32_bf16 v[96:99], v[132:135], v[180:183], v[96:99]
	v_mfma_f32_16x16x32_bf16 v[92:95], v[140:143], v[180:183], v[92:95]
	v_mfma_f32_16x16x32_bf16 v[88:91], v[132:135], v[188:191], v[88:91]
	v_mfma_f32_16x16x32_bf16 v[84:87], v[140:143], v[188:191], v[84:87]
	v_mfma_f32_16x16x32_bf16 v[78:81], v[132:135], v[210:213], v[80:83]
	v_mfma_f32_16x16x32_bf16 v[74:77], v[140:143], v[210:213], v[74:77]
	v_mfma_f32_16x16x32_bf16 v[104:107], v[136:139], v[176:179], v[104:107]
	v_mfma_f32_16x16x32_bf16 v[100:103], v[144:147], v[176:179], v[100:103]
	v_mfma_f32_16x16x32_bf16 v[96:99], v[136:139], v[184:187], v[96:99]
	v_mfma_f32_16x16x32_bf16 v[92:95], v[144:147], v[184:187], v[92:95]
	v_mfma_f32_16x16x32_bf16 v[88:91], v[136:139], v[192:195], v[88:91]
	v_mfma_f32_16x16x32_bf16 v[84:87], v[144:147], v[192:195], v[84:87]
	v_mfma_f32_16x16x32_bf16 v[80:83], v[136:139], v[214:217], v[78:81]
	v_mfma_f32_16x16x32_bf16 v[76:79], v[144:147], v[214:217], v[74:77]
	s_setprio 0
	s_setprio 1
	v_mfma_f32_16x16x32_bf16 v[32:35], v[148:151], v[172:175], v[32:35]
	v_mfma_f32_16x16x32_bf16 v[28:31], v[164:167], v[172:175], v[28:31]
	v_mfma_f32_16x16x32_bf16 v[24:27], v[148:151], v[180:183], v[24:27]
	v_mfma_f32_16x16x32_bf16 v[20:23], v[164:167], v[180:183], v[20:23]
	v_mfma_f32_16x16x32_bf16 v[16:19], v[148:151], v[188:191], v[16:19]
	v_mfma_f32_16x16x32_bf16 v[12:15], v[164:167], v[188:191], v[12:15]
	v_mfma_f32_16x16x32_bf16 v[6:9], v[148:151], v[210:213], v[8:11]
	v_mfma_f32_16x16x32_bf16 v[2:5], v[164:167], v[210:213], v[2:5]
	v_mfma_f32_16x16x32_bf16 v[32:35], v[156:159], v[176:179], v[32:35]
	v_mfma_f32_16x16x32_bf16 v[28:31], v[168:171], v[176:179], v[28:31]
	v_mfma_f32_16x16x32_bf16 v[24:27], v[156:159], v[184:187], v[24:27]
	v_mfma_f32_16x16x32_bf16 v[20:23], v[168:171], v[184:187], v[20:23]
	v_mfma_f32_16x16x32_bf16 v[16:19], v[156:159], v[192:195], v[16:19]
	v_mfma_f32_16x16x32_bf16 v[12:15], v[168:171], v[192:195], v[12:15]
	v_mfma_f32_16x16x32_bf16 v[8:11], v[156:159], v[214:217], v[6:9]
	v_mfma_f32_16x16x32_bf16 v[4:7], v[168:171], v[214:217], v[2:5]
	s_setprio 0
	s_add_i32 s72, s72, 2
	s_add_u32 s50, s50, 0x100
	s_addc_u32 s51, s51, 0
	s_cmp_gt_u32 s72, 29
	s_barrier
	s_cbranch_scc1 .LBB0_1153

; #define PG8_STAGE(bufoff, gbase, voff) do { _Pragma("unroll") for (int _i = 0; _i < 2; ++_i) \
;         __builtin_amdgcn_global_load_lds((const unsigned*)((const char*)(gbase) + (voff)[_i]), (LAS unsigned*)(lds + (bufoff) + ldsw + _i * 8192), 16, 0, 0); } while (0)
; #define PG8_LDA(dst, b, h) do { _Pragma("unroll") for (int m = 0; m < 4; ++m) _Pragma("unroll") for (int k = 0; k < 2; ++k) dst[m][k] = *(const LAS bf16x8*)(lds + PG8_SA(b, h) + aoff + m * 2048 + k * 1024); } while (0)
; #define PG8_LDB(dst, b, h) do { _Pragma("unroll") for (int n = 0; n < 2; ++n) _Pragma("unroll") for (int k = 0; k < 2; ++k) dst[n][k] = *(const LAS bf16x8*)(lds + PG8_SB(b, h) + boff + n * 2048 + k * 1024); } while (0)
; #define PG8_MMA(ai, bj, At, Bt) do { __builtin_amdgcn_s_setprio(1); _Pragma("unroll") for (int m = 0; m < 4; ++m) _Pragma("unroll") for (int n = 0; n < 2; ++n) _Pragma("unroll") for (int k = 0; k < 2; ++k) \
;         acc[ai][bj][m][n] = __builtin_amdgcn_mfma_f32_16x16x32_bf16(Bt[n][k], At[m][k], acc[ai][bj][m][n], 0, 0, 0); __builtin_amdgcn_s_setprio(0); } while (0)
; #define PG8_WAIT_V(n) asm volatile("s_waitcnt vmcnt(" #n ")" ::: "memory")
; #define PG8_WAIT_L(n) asm volatile("s_waitcnt lgkmcnt(" #n ")" ::: "memory")
; #define PG8_BAR __builtin_amdgcn_s_barrier()
; template <class Epi, class Sched>
; __device__ __forceinline__ void gemm_phase(LAS unsigned char* lds, const Gemm g, const Sched& S, const Epi& E, const int tid) {
;     ...
;             const bool last = (t == nt - 2);
;             const char* a1 = cA + (size_t)(t + 1) * kstepA;
;             const char* a2 = last ? nA : cA + (size_t)(t + 2) * kstepA; const char* b2 = last ? nB : cB + (size_t)(t + 2) * kstep;
;             const char* a3 = a2 + kstepA; const char* b3 = b2 + kstep;
;             if constexpr (Epi::HAS_MID) { if (t == g.tmid) E.mid(acc, cur, ui, wr, wc, fr, fq); }
;             PG8_LDB(B0, 0, 0); PG8_LDB(B1, 0, 1); PG8_SCHED; PG8_LDA(At, 0, 0); PG8_STAGE(PG8_SA(1, 1), a1 + hstepA, voffA);
;             PG8_WAIT_V(8); PG8_WAIT_L(0); PG8_BAR; PG8_MMA(0, 0, At, B0); PG8_MMA(0, 1, At, B1); PG8_BAR; PG8_SCHED;
;             PG8_LDA(At, 0, 1); PG8_STAGE(PG8_SB(0, 0), b2, voffB); PG8_STAGE(PG8_SB(0, 1), b2 + hstepB, voffB); PG8_STAGE(PG8_SA(0, 0), a2, voffA);
;             PG8_WAIT_V(8); PG8_WAIT_L(0); PG8_BAR; PG8_MMA(1, 0, At, B0); PG8_MMA(1, 1, At, B1); PG8_BAR; PG8_SCHED;
.LBB0_1314:
	ds_read_b128 v[64:67], v171
	ds_read_b128 v[68:71], v171 offset:1024
	ds_read_b128 v[136:139], v171 offset:2048
	ds_read_b128 v[140:143], v171 offset:3072
	ds_read_b128 v[172:175], v177
	ds_read_b128 v[182:185], v177 offset:1024
	ds_read_b128 v[186:189], v177 offset:2048
	ds_read_b128 v[190:193], v177 offset:3072
	s_add_u32 s16, s8, 0xfff80080
	s_addc_u32 s17, s9, -1
	s_cmp_eq_u32 s62, 28
	s_cselect_b32 s45, s18, s17
	s_cselect_b32 s44, s35, s16
	s_cselect_b32 s43, s31, s61
	s_cselect_b32 s42, s59, s60
	v_lshl_add_u64 v[164:165], s[8:9], 0, v[156:157]
	s_add_i32 m0, s48, 0xc000
	ds_read_b128 v[194:197], v181
	ds_read_b128 v[198:201], v181 offset:1024
	ds_read_b128 v[202:205], v181 offset:2048
	ds_read_b128 v[206:209], v181 offset:3072
	ds_read_b128 v[210:213], v181 offset:4096
	ds_read_b128 v[214:217], v181 offset:5120
	ds_read_b128 v[218:221], v181 offset:6144
	ds_read_b128 v[222:225], v181 offset:7168
	global_load_lds_dwordx4 v[164:165], off
	v_lshl_add_u64 v[164:165], s[8:9], 0, v[158:159]
	s_add_i32 m0, s48, 0xe000
	s_nop 0
	global_load_lds_dwordx4 v[164:165], off
	s_waitcnt vmcnt(8)
	s_waitcnt lgkmcnt(0)
	s_barrier
	s_setprio 1
	s_waitcnt lgkmcnt(0)
	v_mfma_f32_16x16x32_bf16 v[132:135], v[64:67], v[194:197], v[132:135]
	v_mfma_f32_16x16x32_bf16 v[124:127], v[136:139], v[194:197], v[124:127]
	v_mfma_f32_16x16x32_bf16 v[116:119], v[64:67], v[202:205], v[116:119]
	v_mfma_f32_16x16x32_bf16 v[108:111], v[136:139], v[202:205], v[108:111]
	v_mfma_f32_16x16x32_bf16 v[100:103], v[64:67], v[210:213], v[100:103]
	v_mfma_f32_16x16x32_bf16 v[92:95], v[136:139], v[210:213], v[92:95]
	v_mfma_f32_16x16x32_bf16 v[84:87], v[64:67], v[218:221], v[84:87]
	v_mfma_f32_16x16x32_bf16 v[76:79], v[136:139], v[218:221], v[76:79]
	v_mfma_f32_16x16x32_bf16 v[132:135], v[68:71], v[198:201], v[132:135]
	v_mfma_f32_16x16x32_bf16 v[124:127], v[140:143], v[198:201], v[124:127]
	v_mfma_f32_16x16x32_bf16 v[116:119], v[68:71], v[206:209], v[116:119]
	v_mfma_f32_16x16x32_bf16 v[108:111], v[140:143], v[206:209], v[108:111]
	v_mfma_f32_16x16x32_bf16 v[100:103], v[68:71], v[214:217], v[100:103]
	v_mfma_f32_16x16x32_bf16 v[92:95], v[140:143], v[214:217], v[92:95]
	v_mfma_f32_16x16x32_bf16 v[84:87], v[68:71], v[222:225], v[84:87]
	v_mfma_f32_16x16x32_bf16 v[76:79], v[140:143], v[222:225], v[76:79]
	s_setprio 0
	s_setprio 1
	v_mfma_f32_16x16x32_bf16 v[128:131], v[172:175], v[194:197], v[128:131]
	v_mfma_f32_16x16x32_bf16 v[120:123], v[186:189], v[194:197], v[120:123]
	v_mfma_f32_16x16x32_bf16 v[112:115], v[172:175], v[202:205], v[112:115]
	v_mfma_f32_16x16x32_bf16 v[104:107], v[186:189], v[202:205], v[104:107]
	v_mfma_f32_16x16x32_bf16 v[96:99], v[172:175], v[210:213], v[96:99]
	v_mfma_f32_16x16x32_bf16 v[88:91], v[186:189], v[210:213], v[88:91]
	v_mfma_f32_16x16x32_bf16 v[80:83], v[172:175], v[218:221], v[80:83]
	v_mfma_f32_16x16x32_bf16 v[72:75], v[186:189], v[218:221], v[72:75]
	v_mfma_f32_16x16x32_bf16 v[128:131], v[182:185], v[198:201], v[128:131]
	v_mfma_f32_16x16x32_bf16 v[120:123], v[190:193], v[198:201], v[120:123]
	v_mfma_f32_16x16x32_bf16 v[112:115], v[182:185], v[206:209], v[112:115]
	v_mfma_f32_16x16x32_bf16 v[104:107], v[190:193], v[206:209], v[104:107]
	v_mfma_f32_16x16x32_bf16 v[96:99], v[182:185], v[214:217], v[96:99]
	v_mfma_f32_16x16x32_bf16 v[88:91], v[190:193], v[214:217], v[88:91]
	v_mfma_f32_16x16x32_bf16 v[80:83], v[182:185], v[222:225], v[80:83]
	v_mfma_f32_16x16x32_bf16 v[72:75], v[190:193], v[222:225], v[72:75]
	s_setprio 0
	s_barrier
	s_add_i32 s16, s55, s46
	v_lshl_add_u64 v[164:165], s[42:43], 0, v[146:147]
	s_mov_b32 m0, s16
	ds_read_b128 v[194:197], v181 offset:16384
	ds_read_b128 v[198:201], v181 offset:17408
	ds_read_b128 v[202:205], v181 offset:18432
	ds_read_b128 v[206:209], v181 offset:19456
	ds_read_b128 v[210:213], v181 offset:20480
	ds_read_b128 v[214:217], v181 offset:21504
	ds_read_b128 v[218:221], v181 offset:22528
	ds_read_b128 v[222:225], v181 offset:23552
	global_load_lds_dwordx4 v[164:165], off
	s_add_i32 m0, s16, 0x2000
	s_add_u32 s16, s42, 0x80000
	v_lshl_add_u64 v[168:169], s[42:43], 0, v[150:151]
	s_addc_u32 s17, s43, 0
	s_add_i32 s20, s56, s46
	global_load_lds_dwordx4 v[168:169], off
	v_lshl_add_u64 v[178:179], s[16:17], 0, v[146:147]
	s_mov_b32 m0, s20
	v_lshl_add_u64 v[226:227], s[44:45], 0, v[148:149]
	global_load_lds_dwordx4 v[178:179], off
	v_lshl_add_u64 v[178:179], s[16:17], 0, v[150:151]
	s_add_i32 m0, s20, 0x2000
	s_nop 0
	global_load_lds_dwordx4 v[178:179], off
	v_lshl_add_u64 v[178:179], s[44:45], 0, v[144:145]
	s_mov_b32 m0, s48
	s_nop 0
	global_load_lds_dwordx4 v[178:179], off
	s_mov_b32 m0, s49
	s_nop 0
	global_load_lds_dwordx4 v[226:227], off
	s_waitcnt vmcnt(8)
	s_waitcnt lgkmcnt(0)
	s_barrier
; #define PG8_STAGE(bufoff, gbase, voff) do { _Pragma("unroll") for (int _i = 0; _i < 2; ++_i) \
;         __builtin_amdgcn_global_load_lds((const unsigned*)((const char*)(gbase) + (voff)[_i]), (LAS unsigned*)(lds + (bufoff) + ldsw + _i * 8192), 16, 0, 0); } while (0)
; #define PG8_LDA(dst, b, h) do { _Pragma("unroll") for (int m = 0; m < 4; ++m) _Pragma("unroll") for (int k = 0; k < 2; ++k) dst[m][k] = *(const LAS bf16x8*)(lds + PG8_SA(b, h) + aoff + m * 2048 + k * 1024); } while (0)
; #define PG8_LDB(dst, b, h) do { _Pragma("unroll") for (int n = 0; n < 2; ++n) _Pragma("unroll") for (int k = 0; k < 2; ++k) dst[n][k] = *(const LAS bf16x8*)(lds + PG8_SB(b, h) + boff + n * 2048 + k * 1024); } while (0)
; #define PG8_MMA(ai, bj, At, Bt) do { __builtin_amdgcn_s_setprio(1); _Pragma("unroll") for (int m = 0; m < 4; ++m) _Pragma("unroll") for (int n = 0; n < 2; ++n) _Pragma("unroll") for (int k = 0; k < 2; ++k) \
;         acc[ai][bj][m][n] = __builtin_amdgcn_mfma_f32_16x16x32_bf16(Bt[n][k], At[m][k], acc[ai][bj][m][n], 0, 0, 0); __builtin_amdgcn_s_setprio(0); } while (0)
; #define PG8_WAIT_V(n) asm volatile("s_waitcnt vmcnt(" #n ")" ::: "memory")
; #define PG8_WAIT_L(n) asm volatile("s_waitcnt lgkmcnt(" #n ")" ::: "memory")
; #define PG8_BAR __builtin_amdgcn_s_barrier()
; #define PG8_SCHED __builtin_amdgcn_sched_barrier(0)
; template <class Epi, class Sched>
; __device__ __forceinline__ void gemm_phase(LAS unsigned char* lds, const Gemm g, const Sched& S, const Epi& E, const int tid) {
;     ...
;             PG8_WAIT_V(8); PG8_WAIT_L(0); PG8_BAR; PG8_MMA(1, 0, At, B0); PG8_MMA(1, 1, At, B1); PG8_BAR; PG8_SCHED;
;             PG8_LDB(B0, 1, 0); PG8_LDB(B1, 1, 1); PG8_SCHED; PG8_LDA(At, 1, 0); PG8_STAGE(PG8_SA(0, 1), a2 + hstepA, voffA);
;             PG8_WAIT_V(8); PG8_WAIT_L(0); PG8_BAR; PG8_MMA(0, 0, At, B0); PG8_MMA(0, 1, At, B1); PG8_BAR; PG8_SCHED;
	s_setprio 1
	s_waitcnt lgkmcnt(0)
	v_mfma_f32_16x16x32_bf16 v[60:63], v[64:67], v[194:197], v[60:63]
	v_mfma_f32_16x16x32_bf16 v[52:55], v[136:139], v[194:197], v[52:55]
	v_mfma_f32_16x16x32_bf16 v[44:47], v[64:67], v[202:205], v[44:47]
	v_mfma_f32_16x16x32_bf16 v[36:39], v[136:139], v[202:205], v[36:39]
	v_mfma_f32_16x16x32_bf16 v[28:31], v[64:67], v[210:213], v[28:31]
	v_mfma_f32_16x16x32_bf16 v[20:23], v[136:139], v[210:213], v[20:23]
	v_mfma_f32_16x16x32_bf16 v[12:15], v[64:67], v[218:221], v[12:15]
	v_mfma_f32_16x16x32_bf16 v[4:7], v[136:139], v[218:221], v[4:7]
	v_mfma_f32_16x16x32_bf16 v[60:63], v[68:71], v[198:201], v[60:63]
	v_mfma_f32_16x16x32_bf16 v[52:55], v[140:143], v[198:201], v[52:55]
	v_mfma_f32_16x16x32_bf16 v[44:47], v[68:71], v[206:209], v[44:47]
	v_mfma_f32_16x16x32_bf16 v[36:39], v[140:143], v[206:209], v[36:39]
	v_mfma_f32_16x16x32_bf16 v[28:31], v[68:71], v[214:217], v[28:31]
	v_mfma_f32_16x16x32_bf16 v[20:23], v[140:143], v[214:217], v[20:23]
	v_mfma_f32_16x16x32_bf16 v[12:15], v[68:71], v[222:225], v[12:15]
	v_mfma_f32_16x16x32_bf16 v[4:7], v[140:143], v[222:225], v[4:7]
	s_setprio 0
	s_setprio 1
	v_mfma_f32_16x16x32_bf16 v[56:59], v[172:175], v[194:197], v[56:59]
	v_mfma_f32_16x16x32_bf16 v[48:51], v[186:189], v[194:197], v[48:51]
	v_mfma_f32_16x16x32_bf16 v[40:43], v[172:175], v[202:205], v[40:43]
	v_mfma_f32_16x16x32_bf16 v[32:35], v[186:189], v[202:205], v[32:35]
	v_mfma_f32_16x16x32_bf16 v[24:27], v[172:175], v[210:213], v[24:27]
	v_mfma_f32_16x16x32_bf16 v[16:19], v[186:189], v[210:213], v[16:19]
	v_mfma_f32_16x16x32_bf16 v[8:11], v[172:175], v[218:221], v[8:11]
	v_mfma_f32_16x16x32_bf16 v[0:3], v[186:189], v[218:221], v[0:3]
	v_mfma_f32_16x16x32_bf16 v[56:59], v[182:185], v[198:201], v[56:59]
	v_mfma_f32_16x16x32_bf16 v[48:51], v[190:193], v[198:201], v[48:51]
	v_mfma_f32_16x16x32_bf16 v[40:43], v[182:185], v[206:209], v[40:43]
	v_mfma_f32_16x16x32_bf16 v[32:35], v[190:193], v[206:209], v[32:35]
	v_mfma_f32_16x16x32_bf16 v[24:27], v[182:185], v[214:217], v[24:27]
	v_mfma_f32_16x16x32_bf16 v[16:19], v[190:193], v[214:217], v[16:19]
	v_mfma_f32_16x16x32_bf16 v[8:11], v[182:185], v[222:225], v[8:11]
	v_mfma_f32_16x16x32_bf16 v[0:3], v[190:193], v[222:225], v[0:3]
	s_setprio 0
	s_barrier
	s_add_i32 s20, 0, 0x18000
	s_add_i32 s21, 0, 0x1c000
	v_add_u32_e32 v140, s20, v167
	v_add_u32_e32 v152, s21, v167
	ds_read_b128 v[64:67], v140
	ds_read_b128 v[68:71], v140 offset:1024
	ds_read_b128 v[136:139], v140 offset:2048
	ds_read_b128 v[140:143], v140 offset:3072
	ds_read_b128 v[172:175], v152
	ds_read_b128 v[182:185], v152 offset:1024
	ds_read_b128 v[186:189], v152 offset:2048
	ds_read_b128 v[190:193], v152 offset:3072
	s_add_u32 s16, s44, 0x80000
	s_addc_u32 s17, s45, 0
	s_mov_b32 m0, s50
	v_lshl_add_u64 v[228:229], s[16:17], 0, v[144:145]
	ds_read_b128 v[194:197], v181 offset:32768
	ds_read_b128 v[198:201], v181 offset:33792
	ds_read_b128 v[202:205], v181 offset:34816
	ds_read_b128 v[206:209], v181 offset:35840
	ds_read_b128 v[210:213], v181 offset:36864
	ds_read_b128 v[214:217], v181 offset:37888
	ds_read_b128 v[218:221], v181 offset:38912
	ds_read_b128 v[222:225], v181 offset:39936
	global_load_lds_dwordx4 v[228:229], off
	v_lshl_add_u64 v[228:229], s[16:17], 0, v[148:149]
	s_mov_b32 m0, s51
	s_nop 0
	global_load_lds_dwordx4 v[228:229], off
	s_waitcnt vmcnt(8)
	s_waitcnt lgkmcnt(0)
	s_barrier
	s_setprio 1
	s_waitcnt lgkmcnt(0)
	v_mfma_f32_16x16x32_bf16 v[132:135], v[64:67], v[194:197], v[132:135]
	v_mfma_f32_16x16x32_bf16 v[124:127], v[136:139], v[194:197], v[124:127]
	v_mfma_f32_16x16x32_bf16 v[116:119], v[64:67], v[202:205], v[116:119]
	v_mfma_f32_16x16x32_bf16 v[108:111], v[136:139], v[202:205], v[108:111]
	v_mfma_f32_16x16x32_bf16 v[100:103], v[64:67], v[210:213], v[100:103]
	v_mfma_f32_16x16x32_bf16 v[92:95], v[136:139], v[210:213], v[92:95]
	v_mfma_f32_16x16x32_bf16 v[84:87], v[64:67], v[218:221], v[84:87]
	v_mfma_f32_16x16x32_bf16 v[76:79], v[136:139], v[218:221], v[76:79]
	v_mfma_f32_16x16x32_bf16 v[132:135], v[68:71], v[198:201], v[132:135]
	v_mfma_f32_16x16x32_bf16 v[124:127], v[140:143], v[198:201], v[124:127]
	v_mfma_f32_16x16x32_bf16 v[116:119], v[68:71], v[206:209], v[116:119]
	v_mfma_f32_16x16x32_bf16 v[108:111], v[140:143], v[206:209], v[108:111]
	v_mfma_f32_16x16x32_bf16 v[100:103], v[68:71], v[214:217], v[100:103]
	v_mfma_f32_16x16x32_bf16 v[92:95], v[140:143], v[214:217], v[92:95]
	v_mfma_f32_16x16x32_bf16 v[84:87], v[68:71], v[222:225], v[84:87]
	v_mfma_f32_16x16x32_bf16 v[76:79], v[140:143], v[222:225], v[76:79]
	s_setprio 0
	s_setprio 1
	v_mfma_f32_16x16x32_bf16 v[128:131], v[172:175], v[194:197], v[128:131]
	v_mfma_f32_16x16x32_bf16 v[120:123], v[186:189], v[194:197], v[120:123]
	v_mfma_f32_16x16x32_bf16 v[112:115], v[172:175], v[202:205], v[112:115]
	v_mfma_f32_16x16x32_bf16 v[104:107], v[186:189], v[202:205], v[104:107]
	v_mfma_f32_16x16x32_bf16 v[96:99], v[172:175], v[210:213], v[96:99]
	v_mfma_f32_16x16x32_bf16 v[88:91], v[186:189], v[210:213], v[88:91]
	v_mfma_f32_16x16x32_bf16 v[80:83], v[172:175], v[218:221], v[80:83]
	v_mfma_f32_16x16x32_bf16 v[72:75], v[186:189], v[218:221], v[72:75]
	v_mfma_f32_16x16x32_bf16 v[128:131], v[182:185], v[198:201], v[128:131]
	v_mfma_f32_16x16x32_bf16 v[120:123], v[190:193], v[198:201], v[120:123]
	v_mfma_f32_16x16x32_bf16 v[112:115], v[182:185], v[206:209], v[112:115]
	v_mfma_f32_16x16x32_bf16 v[104:107], v[190:193], v[206:209], v[104:107]
	v_mfma_f32_16x16x32_bf16 v[96:99], v[182:185], v[214:217], v[96:99]
	v_mfma_f32_16x16x32_bf16 v[88:91], v[190:193], v[214:217], v[88:91]
	v_mfma_f32_16x16x32_bf16 v[80:83], v[182:185], v[222:225], v[80:83]
	v_mfma_f32_16x16x32_bf16 v[72:75], v[190:193], v[222:225], v[72:75]
	s_setprio 0
	s_barrier
; #define PG8_STAGE(bufoff, gbase, voff) do { _Pragma("unroll") for (int _i = 0; _i < 2; ++_i) \
;         __builtin_amdgcn_global_load_lds((const unsigned*)((const char*)(gbase) + (voff)[_i]), (LAS unsigned*)(lds + (bufoff) + ldsw + _i * 8192), 16, 0, 0); } while (0)
; #define PG8_LDA(dst, b, h) do { _Pragma("unroll") for (int m = 0; m < 4; ++m) _Pragma("unroll") for (int k = 0; k < 2; ++k) dst[m][k] = *(const LAS bf16x8*)(lds + PG8_SA(b, h) + aoff + m * 2048 + k * 1024); } while (0)
; #define PG8_MMA(ai, bj, At, Bt) do { __builtin_amdgcn_s_setprio(1); _Pragma("unroll") for (int m = 0; m < 4; ++m) _Pragma("unroll") for (int n = 0; n < 2; ++n) _Pragma("unroll") for (int k = 0; k < 2; ++k) \
;         acc[ai][bj][m][n] = __builtin_amdgcn_mfma_f32_16x16x32_bf16(Bt[n][k], At[m][k], acc[ai][bj][m][n], 0, 0, 0); __builtin_amdgcn_s_setprio(0); } while (0)
; #define PG8_WAIT_V(n) asm volatile("s_waitcnt vmcnt(" #n ")" ::: "memory")
; #define PG8_WAIT_L(n) asm volatile("s_waitcnt lgkmcnt(" #n ")" ::: "memory")
; #define PG8_BAR __builtin_amdgcn_s_barrier()
; #define PG8_SCHED __builtin_amdgcn_sched_barrier(0)
; template <class Epi, class Sched>
; __device__ __forceinline__ void gemm_phase(LAS unsigned char* lds, const Gemm g, const Sched& S, const Epi& E, const int tid) {
;     ...
;         for (int t = 0; t < nt; t += 2) {
;             const bool last = (t == nt - 2);
;             const char* a1 = cA + (size_t)(t + 1) * kstepA;
;             const char* a2 = last ? nA : cA + (size_t)(t + 2) * kstepA; const char* b2 = last ? nB : cB + (size_t)(t + 2) * kstep;
;     ...
;             PG8_LDA(At, 1, 1); PG8_STAGE(PG8_SB(1, 0), b3, voffB); PG8_STAGE(PG8_SB(1, 1), b3 + hstepB, voffB); PG8_STAGE(PG8_SA(1, 0), a3, voffA);
;             PG8_WAIT_V(8); PG8_WAIT_L(0); PG8_BAR; PG8_MMA(1, 0, At, B0); PG8_MMA(1, 1, At, B1); PG8_BAR; PG8_SCHED;
;         }
	s_add_i32 s16, s20, s46
	v_lshl_add_u64 v[164:165], v[164:165], 0, s[26:27]
	s_mov_b32 m0, s16
	ds_read_b128 v[194:197], v181 offset:49152
	ds_read_b128 v[198:201], v181 offset:50176
	ds_read_b128 v[202:205], v181 offset:51200
	ds_read_b128 v[206:209], v181 offset:52224
	ds_read_b128 v[210:213], v181 offset:53248
	ds_read_b128 v[214:217], v181 offset:54272
	ds_read_b128 v[218:221], v181 offset:55296
	ds_read_b128 v[222:225], v181 offset:56320
	global_load_lds_dwordx4 v[164:165], off
	s_add_i32 m0, s16, 0x2000
	s_add_u32 s16, s42, 0x80080
	v_lshl_add_u64 v[164:165], v[168:169], 0, s[26:27]
	s_addc_u32 s17, s43, 0
	s_add_i32 s20, s21, s46
	global_load_lds_dwordx4 v[164:165], off
	v_lshl_add_u64 v[164:165], s[16:17], 0, v[146:147]
	s_mov_b32 m0, s20
	s_nop 0
	global_load_lds_dwordx4 v[164:165], off
	v_lshl_add_u64 v[164:165], s[16:17], 0, v[150:151]
	s_add_i32 m0, s20, 0x2000
	s_nop 0
	global_load_lds_dwordx4 v[164:165], off
	v_lshl_add_u64 v[164:165], v[178:179], 0, s[26:27]
	s_mov_b32 m0, s53
	s_nop 0
	global_load_lds_dwordx4 v[164:165], off
	v_lshl_add_u64 v[164:165], v[226:227], 0, s[26:27]
	s_mov_b32 m0, s54
	s_nop 0
	global_load_lds_dwordx4 v[164:165], off
	s_waitcnt vmcnt(8)
	s_waitcnt lgkmcnt(0)
	s_barrier
	s_setprio 1
	s_waitcnt lgkmcnt(0)
	v_mfma_f32_16x16x32_bf16 v[60:63], v[64:67], v[194:197], v[60:63]
	v_mfma_f32_16x16x32_bf16 v[52:55], v[136:139], v[194:197], v[52:55]
	v_mfma_f32_16x16x32_bf16 v[44:47], v[64:67], v[202:205], v[44:47]
	v_mfma_f32_16x16x32_bf16 v[36:39], v[136:139], v[202:205], v[36:39]
	v_mfma_f32_16x16x32_bf16 v[28:31], v[64:67], v[210:213], v[28:31]
	v_mfma_f32_16x16x32_bf16 v[20:23], v[136:139], v[210:213], v[20:23]
	v_mfma_f32_16x16x32_bf16 v[12:15], v[64:67], v[218:221], v[12:15]
	v_mfma_f32_16x16x32_bf16 v[4:7], v[136:139], v[218:221], v[4:7]
	v_mfma_f32_16x16x32_bf16 v[60:63], v[68:71], v[198:201], v[60:63]
	v_mfma_f32_16x16x32_bf16 v[52:55], v[140:143], v[198:201], v[52:55]
	v_mfma_f32_16x16x32_bf16 v[44:47], v[68:71], v[206:209], v[44:47]
	v_mfma_f32_16x16x32_bf16 v[36:39], v[140:143], v[206:209], v[36:39]
	v_mfma_f32_16x16x32_bf16 v[28:31], v[68:71], v[214:217], v[28:31]
	v_mfma_f32_16x16x32_bf16 v[20:23], v[140:143], v[214:217], v[20:23]
	v_mfma_f32_16x16x32_bf16 v[12:15], v[68:71], v[222:225], v[12:15]
	v_mfma_f32_16x16x32_bf16 v[4:7], v[140:143], v[222:225], v[4:7]
	s_setprio 0
	s_setprio 1
	v_mfma_f32_16x16x32_bf16 v[56:59], v[172:175], v[194:197], v[56:59]
	v_mfma_f32_16x16x32_bf16 v[48:51], v[186:189], v[194:197], v[48:51]
	v_mfma_f32_16x16x32_bf16 v[40:43], v[172:175], v[202:205], v[40:43]
	v_mfma_f32_16x16x32_bf16 v[32:35], v[186:189], v[202:205], v[32:35]
	v_mfma_f32_16x16x32_bf16 v[24:27], v[172:175], v[210:213], v[24:27]
	v_mfma_f32_16x16x32_bf16 v[16:19], v[186:189], v[210:213], v[16:19]
	v_mfma_f32_16x16x32_bf16 v[8:11], v[172:175], v[218:221], v[8:11]
	v_mfma_f32_16x16x32_bf16 v[0:3], v[186:189], v[218:221], v[0:3]
	v_mfma_f32_16x16x32_bf16 v[56:59], v[182:185], v[198:201], v[56:59]
	v_mfma_f32_16x16x32_bf16 v[48:51], v[190:193], v[198:201], v[48:51]
	v_mfma_f32_16x16x32_bf16 v[40:43], v[182:185], v[206:209], v[40:43]
	v_mfma_f32_16x16x32_bf16 v[32:35], v[190:193], v[206:209], v[32:35]
	v_mfma_f32_16x16x32_bf16 v[24:27], v[182:185], v[214:217], v[24:27]
	v_mfma_f32_16x16x32_bf16 v[16:19], v[190:193], v[214:217], v[16:19]
	v_mfma_f32_16x16x32_bf16 v[8:11], v[182:185], v[222:225], v[8:11]
	v_mfma_f32_16x16x32_bf16 v[0:3], v[190:193], v[222:225], v[0:3]
	s_setprio 0
	s_add_i32 s62, s62, 2
	s_add_u32 s8, s8, 0x100
	s_addc_u32 s9, s9, 0
	s_add_u32 s60, s60, 0x100
	s_addc_u32 s61, s61, 0
	s_cmp_gt_u32 s62, 29
	s_barrier
	s_cbranch_scc0 .LBB0_1314
	s_and_b64 vcc, exec, s[28:29]
	s_cbranch_vccz .LBB0_1317
	s_barrier

; #define PG8_STAGE(bufoff, gbase, voff) do { _Pragma("unroll") for (int _i = 0; _i < 2; ++_i) \
;         __builtin_amdgcn_global_load_lds((const unsigned*)((const char*)(gbase) + (voff)[_i]), (LAS unsigned*)(lds + (bufoff) + ldsw + _i * 8192), 16, 0, 0); } while (0)
; #define PG8_LDA(dst, b, h) do { _Pragma("unroll") for (int m = 0; m < 4; ++m) _Pragma("unroll") for (int k = 0; k < 2; ++k) dst[m][k] = *(const LAS bf16x8*)(lds + PG8_SA(b, h) + aoff + m * 2048 + k * 1024); } while (0)
; #define PG8_LDB(dst, b, h) do { _Pragma("unroll") for (int n = 0; n < 2; ++n) _Pragma("unroll") for (int k = 0; k < 2; ++k) dst[n][k] = *(const LAS bf16x8*)(lds + PG8_SB(b, h) + boff + n * 2048 + k * 1024); } while (0)
; #define PG8_MMA(ai, bj, At, Bt) do { __builtin_amdgcn_s_setprio(1); _Pragma("unroll") for (int m = 0; m < 4; ++m) _Pragma("unroll") for (int n = 0; n < 2; ++n) _Pragma("unroll") for (int k = 0; k < 2; ++k) \
;         acc[ai][bj][m][n] = __builtin_amdgcn_mfma_f32_16x16x32_bf16(Bt[n][k], At[m][k], acc[ai][bj][m][n], 0, 0, 0); __builtin_amdgcn_s_setprio(0); } while (0)
; #define PG8_WAIT_V(n) asm volatile("s_waitcnt vmcnt(" #n ")" ::: "memory")
; #define PG8_WAIT_L(n) asm volatile("s_waitcnt lgkmcnt(" #n ")" ::: "memory")
; #define PG8_BAR __builtin_amdgcn_s_barrier()
; template <class Epi, class Sched>
; __device__ __forceinline__ void gemm_phase(LAS unsigned char* lds, const Gemm g, const Sched& S, const Epi& E, const int tid) {
;     ...
;             const bool last = (t == nt - 2);
;             const char* a1 = cA + (size_t)(t + 1) * kstepA;
;             const char* a2 = last ? nA : cA + (size_t)(t + 2) * kstepA; const char* b2 = last ? nB : cB + (size_t)(t + 2) * kstep;
;             const char* a3 = a2 + kstepA; const char* b3 = b2 + kstep;
;             if constexpr (Epi::HAS_MID) { if (t == g.tmid) E.mid(acc, cur, ui, wr, wc, fr, fq); }
;             PG8_LDB(B0, 0, 0); PG8_LDB(B1, 0, 1); PG8_SCHED; PG8_LDA(At, 0, 0); PG8_STAGE(PG8_SA(1, 1), a1 + hstepA, voffA);
;             PG8_WAIT_V(8); PG8_WAIT_L(0); PG8_BAR; PG8_MMA(0, 0, At, B0); PG8_MMA(0, 1, At, B1); PG8_BAR; PG8_SCHED;
;             PG8_LDA(At, 0, 1); PG8_STAGE(PG8_SB(0, 0), b2, voffB); PG8_STAGE(PG8_SB(0, 1), b2 + hstepB, voffB); PG8_STAGE(PG8_SA(0, 0), a2, voffA);
;             PG8_WAIT_V(8); PG8_WAIT_L(0); PG8_BAR; PG8_MMA(1, 0, At, B0); PG8_MMA(1, 1, At, B1); PG8_BAR; PG8_SCHED;
.LBB0_1390:
	ds_read_b128 v[128:131], v189
	ds_read_b128 v[132:135], v189 offset:1024
	ds_read_b128 v[136:139], v189 offset:2048
	ds_read_b128 v[140:143], v189 offset:3072
	ds_read_b128 v[144:147], v190
	ds_read_b128 v[164:167], v190 offset:1024
	ds_read_b128 v[168:171], v190 offset:2048
	ds_read_b128 v[172:175], v190 offset:3072
	s_add_u32 s24, s20, 0x100
	s_addc_u32 s25, s21, 0
	s_cmpk_eq_i32 s53, 0x54
	s_cselect_b32 s29, s5, s25
	s_cselect_b32 s28, s4, s24
	s_cselect_b32 s27, s19, s52
	s_cselect_b32 s26, s18, s51
	v_lshl_add_u64 v[184:185], s[20:21], 0, v[156:157]
	s_add_i32 m0, s34, 0xc000
	ds_read_b128 v[176:179], v191
	ds_read_b128 v[180:183], v191 offset:1024
	ds_read_b128 v[192:195], v191 offset:2048
	ds_read_b128 v[196:199], v191 offset:3072
	ds_read_b128 v[200:203], v191 offset:4096
	ds_read_b128 v[204:207], v191 offset:5120
	ds_read_b128 v[208:211], v191 offset:6144
	ds_read_b128 v[212:215], v191 offset:7168
	global_load_lds_dwordx4 v[184:185], off
	v_lshl_add_u64 v[184:185], s[20:21], 0, v[158:159]
	s_add_i32 m0, s34, 0xe000
	s_nop 0
	global_load_lds_dwordx4 v[184:185], off
	s_waitcnt vmcnt(8)
	s_waitcnt lgkmcnt(0)
	s_barrier
	s_setprio 1
	s_waitcnt lgkmcnt(0)
	v_mfma_f32_16x16x32_bf16 v[124:127], v[128:131], v[176:179], v[124:127]
	v_mfma_f32_16x16x32_bf16 v[120:123], v[136:139], v[176:179], v[120:123]
	v_mfma_f32_16x16x32_bf16 v[116:119], v[128:131], v[192:195], v[116:119]
	v_mfma_f32_16x16x32_bf16 v[112:115], v[136:139], v[192:195], v[112:115]
	v_mfma_f32_16x16x32_bf16 v[108:111], v[128:131], v[200:203], v[108:111]
	v_mfma_f32_16x16x32_bf16 v[104:107], v[136:139], v[200:203], v[104:107]
	v_mfma_f32_16x16x32_bf16 v[100:103], v[128:131], v[208:211], v[100:103]
	v_mfma_f32_16x16x32_bf16 v[96:99], v[136:139], v[208:211], v[96:99]
	v_mfma_f32_16x16x32_bf16 v[124:127], v[132:135], v[180:183], v[124:127]
	v_mfma_f32_16x16x32_bf16 v[120:123], v[140:143], v[180:183], v[120:123]
	v_mfma_f32_16x16x32_bf16 v[116:119], v[132:135], v[196:199], v[116:119]
	v_mfma_f32_16x16x32_bf16 v[112:115], v[140:143], v[196:199], v[112:115]
	v_mfma_f32_16x16x32_bf16 v[108:111], v[132:135], v[204:207], v[108:111]
	v_mfma_f32_16x16x32_bf16 v[104:107], v[140:143], v[204:207], v[104:107]
	v_mfma_f32_16x16x32_bf16 v[100:103], v[132:135], v[212:215], v[100:103]
	v_mfma_f32_16x16x32_bf16 v[96:99], v[140:143], v[212:215], v[96:99]
	s_setprio 0
	s_setprio 1
	v_mfma_f32_16x16x32_bf16 v[68:71], v[144:147], v[176:179], v[68:71]
	v_mfma_f32_16x16x32_bf16 v[60:63], v[168:171], v[176:179], v[60:63]
	v_mfma_f32_16x16x32_bf16 v[52:55], v[144:147], v[192:195], v[52:55]
	v_mfma_f32_16x16x32_bf16 v[48:51], v[168:171], v[192:195], v[48:51]
	v_mfma_f32_16x16x32_bf16 v[44:47], v[144:147], v[200:203], v[44:47]
	v_mfma_f32_16x16x32_bf16 v[40:43], v[168:171], v[200:203], v[40:43]
	v_mfma_f32_16x16x32_bf16 v[36:39], v[144:147], v[208:211], v[36:39]
	v_mfma_f32_16x16x32_bf16 v[32:35], v[168:171], v[208:211], v[32:35]
	v_mfma_f32_16x16x32_bf16 v[68:71], v[164:167], v[180:183], v[68:71]
	v_mfma_f32_16x16x32_bf16 v[60:63], v[172:175], v[180:183], v[60:63]
	v_mfma_f32_16x16x32_bf16 v[52:55], v[164:167], v[196:199], v[52:55]
	v_mfma_f32_16x16x32_bf16 v[48:51], v[172:175], v[196:199], v[48:51]
	v_mfma_f32_16x16x32_bf16 v[44:47], v[164:167], v[204:207], v[44:47]
	v_mfma_f32_16x16x32_bf16 v[40:43], v[172:175], v[204:207], v[40:43]
	v_mfma_f32_16x16x32_bf16 v[36:39], v[164:167], v[212:215], v[36:39]
	v_mfma_f32_16x16x32_bf16 v[32:35], v[172:175], v[212:215], v[32:35]
	s_setprio 0
	s_barrier
	s_add_i32 s20, s44, s30
	v_lshl_add_u64 v[184:185], s[26:27], 0, v[152:153]
	s_mov_b32 m0, s20
	ds_read_b128 v[176:179], v191 offset:16384
	ds_read_b128 v[180:183], v191 offset:17408
	ds_read_b128 v[192:195], v191 offset:18432
	ds_read_b128 v[196:199], v191 offset:19456
	ds_read_b128 v[200:203], v191 offset:20480
	ds_read_b128 v[204:207], v191 offset:21504
	ds_read_b128 v[208:211], v191 offset:22528
	ds_read_b128 v[212:215], v191 offset:23552
	global_load_lds_dwordx4 v[184:185], off
	s_add_i32 m0, s20, 0x2000
	s_add_u32 s20, s26, 0x160000
	v_lshl_add_u64 v[216:217], s[26:27], 0, v[148:149]
	s_addc_u32 s21, s27, 0
	s_add_i32 s54, s45, s30
	global_load_lds_dwordx4 v[216:217], off
	v_lshl_add_u64 v[218:219], s[20:21], 0, v[152:153]
	s_mov_b32 m0, s54
	v_lshl_add_u64 v[220:221], s[28:29], 0, v[150:151]
	global_load_lds_dwordx4 v[218:219], off
	v_lshl_add_u64 v[218:219], s[20:21], 0, v[148:149]
	s_add_i32 m0, s54, 0x2000
	s_nop 0
	global_load_lds_dwordx4 v[218:219], off
	v_lshl_add_u64 v[218:219], s[28:29], 0, v[154:155]
	s_mov_b32 m0, s34
	s_nop 0
	global_load_lds_dwordx4 v[218:219], off
	s_mov_b32 m0, s35
	s_nop 0
	global_load_lds_dwordx4 v[220:221], off
	s_waitcnt vmcnt(8)
	s_waitcnt lgkmcnt(0)
	s_barrier
; #define PG8_STAGE(bufoff, gbase, voff) do { _Pragma("unroll") for (int _i = 0; _i < 2; ++_i) \
;         __builtin_amdgcn_global_load_lds((const unsigned*)((const char*)(gbase) + (voff)[_i]), (LAS unsigned*)(lds + (bufoff) + ldsw + _i * 8192), 16, 0, 0); } while (0)
; #define PG8_LDA(dst, b, h) do { _Pragma("unroll") for (int m = 0; m < 4; ++m) _Pragma("unroll") for (int k = 0; k < 2; ++k) dst[m][k] = *(const LAS bf16x8*)(lds + PG8_SA(b, h) + aoff + m * 2048 + k * 1024); } while (0)
; #define PG8_LDB(dst, b, h) do { _Pragma("unroll") for (int n = 0; n < 2; ++n) _Pragma("unroll") for (int k = 0; k < 2; ++k) dst[n][k] = *(const LAS bf16x8*)(lds + PG8_SB(b, h) + boff + n * 2048 + k * 1024); } while (0)
; #define PG8_MMA(ai, bj, At, Bt) do { __builtin_amdgcn_s_setprio(1); _Pragma("unroll") for (int m = 0; m < 4; ++m) _Pragma("unroll") for (int n = 0; n < 2; ++n) _Pragma("unroll") for (int k = 0; k < 2; ++k) \
;         acc[ai][bj][m][n] = __builtin_amdgcn_mfma_f32_16x16x32_bf16(Bt[n][k], At[m][k], acc[ai][bj][m][n], 0, 0, 0); __builtin_amdgcn_s_setprio(0); } while (0)
; #define PG8_WAIT_V(n) asm volatile("s_waitcnt vmcnt(" #n ")" ::: "memory")
; #define PG8_WAIT_L(n) asm volatile("s_waitcnt lgkmcnt(" #n ")" ::: "memory")
; #define PG8_BAR __builtin_amdgcn_s_barrier()
; #define PG8_SCHED __builtin_amdgcn_sched_barrier(0)
; template <class Epi, class Sched>
; __device__ __forceinline__ void gemm_phase(LAS unsigned char* lds, const Gemm g, const Sched& S, const Epi& E, const int tid) {
;     ...
;             PG8_WAIT_V(8); PG8_WAIT_L(0); PG8_BAR; PG8_MMA(1, 0, At, B0); PG8_MMA(1, 1, At, B1); PG8_BAR; PG8_SCHED;
;             PG8_LDB(B0, 1, 0); PG8_LDB(B1, 1, 1); PG8_SCHED; PG8_LDA(At, 1, 0); PG8_STAGE(PG8_SA(0, 1), a2 + hstepA, voffA);
;             PG8_WAIT_V(8); PG8_WAIT_L(0); PG8_BAR; PG8_MMA(0, 0, At, B0); PG8_MMA(0, 1, At, B1); PG8_BAR; PG8_SCHED;
	s_setprio 1
	s_waitcnt lgkmcnt(0)
	v_mfma_f32_16x16x32_bf16 v[92:95], v[128:131], v[176:179], v[92:95]
	v_mfma_f32_16x16x32_bf16 v[88:91], v[136:139], v[176:179], v[88:91]
	v_mfma_f32_16x16x32_bf16 v[84:87], v[128:131], v[192:195], v[84:87]
	v_mfma_f32_16x16x32_bf16 v[80:83], v[136:139], v[192:195], v[80:83]
	v_mfma_f32_16x16x32_bf16 v[76:79], v[128:131], v[200:203], v[76:79]
	v_mfma_f32_16x16x32_bf16 v[72:75], v[136:139], v[200:203], v[72:75]
	v_mfma_f32_16x16x32_bf16 v[64:67], v[128:131], v[208:211], v[64:67]
	v_mfma_f32_16x16x32_bf16 v[56:59], v[136:139], v[208:211], v[56:59]
	v_mfma_f32_16x16x32_bf16 v[92:95], v[132:135], v[180:183], v[92:95]
	v_mfma_f32_16x16x32_bf16 v[88:91], v[140:143], v[180:183], v[88:91]
	v_mfma_f32_16x16x32_bf16 v[84:87], v[132:135], v[196:199], v[84:87]
	v_mfma_f32_16x16x32_bf16 v[80:83], v[140:143], v[196:199], v[80:83]
	v_mfma_f32_16x16x32_bf16 v[76:79], v[132:135], v[204:207], v[76:79]
	v_mfma_f32_16x16x32_bf16 v[72:75], v[140:143], v[204:207], v[72:75]
	v_mfma_f32_16x16x32_bf16 v[64:67], v[132:135], v[212:215], v[64:67]
	v_mfma_f32_16x16x32_bf16 v[56:59], v[140:143], v[212:215], v[56:59]
	s_setprio 0
	s_setprio 1
	v_mfma_f32_16x16x32_bf16 v[28:31], v[144:147], v[176:179], v[28:31]
	v_mfma_f32_16x16x32_bf16 v[24:27], v[168:171], v[176:179], v[24:27]
	v_mfma_f32_16x16x32_bf16 v[20:23], v[144:147], v[192:195], v[20:23]
	v_mfma_f32_16x16x32_bf16 v[16:19], v[168:171], v[192:195], v[16:19]
	v_mfma_f32_16x16x32_bf16 v[12:15], v[144:147], v[200:203], v[12:15]
	v_mfma_f32_16x16x32_bf16 v[8:11], v[168:171], v[200:203], v[8:11]
	v_mfma_f32_16x16x32_bf16 v[4:7], v[144:147], v[208:211], v[4:7]
	v_mfma_f32_16x16x32_bf16 v[0:3], v[168:171], v[208:211], v[0:3]
	v_mfma_f32_16x16x32_bf16 v[28:31], v[164:167], v[180:183], v[28:31]
	v_mfma_f32_16x16x32_bf16 v[24:27], v[172:175], v[180:183], v[24:27]
	v_mfma_f32_16x16x32_bf16 v[20:23], v[164:167], v[196:199], v[20:23]
	v_mfma_f32_16x16x32_bf16 v[16:19], v[172:175], v[196:199], v[16:19]
	v_mfma_f32_16x16x32_bf16 v[12:15], v[164:167], v[204:207], v[12:15]
	v_mfma_f32_16x16x32_bf16 v[8:11], v[172:175], v[204:207], v[8:11]
	v_mfma_f32_16x16x32_bf16 v[4:7], v[164:167], v[212:215], v[4:7]
	v_mfma_f32_16x16x32_bf16 v[0:3], v[172:175], v[212:215], v[0:3]
	s_setprio 0
	s_barrier
	s_add_i32 s54, 0, 0x18000
	s_add_i32 s55, 0, 0x1c000
	v_add_u32_e32 v140, s54, v188
	v_add_u32_e32 v172, s55, v188
	ds_read_b128 v[128:131], v140
	ds_read_b128 v[132:135], v140 offset:1024
	ds_read_b128 v[136:139], v140 offset:2048
	ds_read_b128 v[140:143], v140 offset:3072
	ds_read_b128 v[144:147], v172
	ds_read_b128 v[164:167], v172 offset:1024
	ds_read_b128 v[168:171], v172 offset:2048
	ds_read_b128 v[172:175], v172 offset:3072
	s_add_u32 s20, s28, 0x160000
	s_addc_u32 s21, s29, 0
	s_mov_b32 m0, s36
	v_lshl_add_u64 v[222:223], s[20:21], 0, v[154:155]
	ds_read_b128 v[176:179], v191 offset:32768
	ds_read_b128 v[180:183], v191 offset:33792
	ds_read_b128 v[192:195], v191 offset:34816
	ds_read_b128 v[196:199], v191 offset:35840
	ds_read_b128 v[200:203], v191 offset:36864
	ds_read_b128 v[204:207], v191 offset:37888
	ds_read_b128 v[208:211], v191 offset:38912
	ds_read_b128 v[212:215], v191 offset:39936
	global_load_lds_dwordx4 v[222:223], off
	v_lshl_add_u64 v[222:223], s[20:21], 0, v[150:151]
	s_mov_b32 m0, s37
	s_nop 0
	global_load_lds_dwordx4 v[222:223], off
	s_waitcnt vmcnt(8)
	s_waitcnt lgkmcnt(0)
	s_barrier
	s_setprio 1
	s_waitcnt lgkmcnt(0)
	v_mfma_f32_16x16x32_bf16 v[124:127], v[128:131], v[176:179], v[124:127]
	v_mfma_f32_16x16x32_bf16 v[120:123], v[136:139], v[176:179], v[120:123]
	v_mfma_f32_16x16x32_bf16 v[116:119], v[128:131], v[192:195], v[116:119]
	v_mfma_f32_16x16x32_bf16 v[112:115], v[136:139], v[192:195], v[112:115]
	v_mfma_f32_16x16x32_bf16 v[108:111], v[128:131], v[200:203], v[108:111]
	v_mfma_f32_16x16x32_bf16 v[104:107], v[136:139], v[200:203], v[104:107]
	v_mfma_f32_16x16x32_bf16 v[100:103], v[128:131], v[208:211], v[100:103]
	v_mfma_f32_16x16x32_bf16 v[96:99], v[136:139], v[208:211], v[96:99]
	v_mfma_f32_16x16x32_bf16 v[124:127], v[132:135], v[180:183], v[124:127]
	v_mfma_f32_16x16x32_bf16 v[120:123], v[140:143], v[180:183], v[120:123]
	v_mfma_f32_16x16x32_bf16 v[116:119], v[132:135], v[196:199], v[116:119]
	v_mfma_f32_16x16x32_bf16 v[112:115], v[140:143], v[196:199], v[112:115]
	v_mfma_f32_16x16x32_bf16 v[108:111], v[132:135], v[204:207], v[108:111]
	v_mfma_f32_16x16x32_bf16 v[104:107], v[140:143], v[204:207], v[104:107]
	v_mfma_f32_16x16x32_bf16 v[100:103], v[132:135], v[212:215], v[100:103]
	v_mfma_f32_16x16x32_bf16 v[96:99], v[140:143], v[212:215], v[96:99]
	s_setprio 0
	s_setprio 1
	v_mfma_f32_16x16x32_bf16 v[68:71], v[144:147], v[176:179], v[68:71]
	v_mfma_f32_16x16x32_bf16 v[60:63], v[168:171], v[176:179], v[60:63]
	v_mfma_f32_16x16x32_bf16 v[52:55], v[144:147], v[192:195], v[52:55]
	v_mfma_f32_16x16x32_bf16 v[48:51], v[168:171], v[192:195], v[48:51]
	v_mfma_f32_16x16x32_bf16 v[44:47], v[144:147], v[200:203], v[44:47]
	v_mfma_f32_16x16x32_bf16 v[40:43], v[168:171], v[200:203], v[40:43]
	v_mfma_f32_16x16x32_bf16 v[36:39], v[144:147], v[208:211], v[36:39]
	v_mfma_f32_16x16x32_bf16 v[32:35], v[168:171], v[208:211], v[32:35]
	v_mfma_f32_16x16x32_bf16 v[68:71], v[164:167], v[180:183], v[68:71]
	v_mfma_f32_16x16x32_bf16 v[60:63], v[172:175], v[180:183], v[60:63]
	v_mfma_f32_16x16x32_bf16 v[52:55], v[164:167], v[196:199], v[52:55]
	v_mfma_f32_16x16x32_bf16 v[48:51], v[172:175], v[196:199], v[48:51]
	v_mfma_f32_16x16x32_bf16 v[44:47], v[164:167], v[204:207], v[44:47]
	v_mfma_f32_16x16x32_bf16 v[40:43], v[172:175], v[204:207], v[40:43]
	v_mfma_f32_16x16x32_bf16 v[36:39], v[164:167], v[212:215], v[36:39]
	v_mfma_f32_16x16x32_bf16 v[32:35], v[172:175], v[212:215], v[32:35]
	s_setprio 0
	s_barrier
; #define PG8_STAGE(bufoff, gbase, voff) do { _Pragma("unroll") for (int _i = 0; _i < 2; ++_i) \
;         __builtin_amdgcn_global_load_lds((const unsigned*)((const char*)(gbase) + (voff)[_i]), (LAS unsigned*)(lds + (bufoff) + ldsw + _i * 8192), 16, 0, 0); } while (0)
; #define PG8_LDA(dst, b, h) do { _Pragma("unroll") for (int m = 0; m < 4; ++m) _Pragma("unroll") for (int k = 0; k < 2; ++k) dst[m][k] = *(const LAS bf16x8*)(lds + PG8_SA(b, h) + aoff + m * 2048 + k * 1024); } while (0)
; #define PG8_MMA(ai, bj, At, Bt) do { __builtin_amdgcn_s_setprio(1); _Pragma("unroll") for (int m = 0; m < 4; ++m) _Pragma("unroll") for (int n = 0; n < 2; ++n) _Pragma("unroll") for (int k = 0; k < 2; ++k) \
;         acc[ai][bj][m][n] = __builtin_amdgcn_mfma_f32_16x16x32_bf16(Bt[n][k], At[m][k], acc[ai][bj][m][n], 0, 0, 0); __builtin_amdgcn_s_setprio(0); } while (0)
; #define PG8_WAIT_V(n) asm volatile("s_waitcnt vmcnt(" #n ")" ::: "memory")
; #define PG8_WAIT_L(n) asm volatile("s_waitcnt lgkmcnt(" #n ")" ::: "memory")
; #define PG8_BAR __builtin_amdgcn_s_barrier()
; #define PG8_SCHED __builtin_amdgcn_sched_barrier(0)
; template <class Epi, class Sched>
; __device__ __forceinline__ void gemm_phase(LAS unsigned char* lds, const Gemm g, const Sched& S, const Epi& E, const int tid) {
;     ...
;         for (int t = 0; t < nt; t += 2) {
;             const bool last = (t == nt - 2);
;             const char* a1 = cA + (size_t)(t + 1) * kstepA;
;             const char* a2 = last ? nA : cA + (size_t)(t + 2) * kstepA; const char* b2 = last ? nB : cB + (size_t)(t + 2) * kstep;
;     ...
;             PG8_LDA(At, 1, 1); PG8_STAGE(PG8_SB(1, 0), b3, voffB); PG8_STAGE(PG8_SB(1, 1), b3 + hstepB, voffB); PG8_STAGE(PG8_SA(1, 0), a3, voffA);
;             PG8_WAIT_V(8); PG8_WAIT_L(0); PG8_BAR; PG8_MMA(1, 0, At, B0); PG8_MMA(1, 1, At, B1); PG8_BAR; PG8_SCHED;
;         }
	s_add_i32 s20, s54, s30
	v_lshl_add_u64 v[184:185], v[184:185], 0, s[12:13]
	s_mov_b32 m0, s20
	ds_read_b128 v[176:179], v191 offset:49152
	ds_read_b128 v[180:183], v191 offset:50176
	ds_read_b128 v[192:195], v191 offset:51200
	ds_read_b128 v[196:199], v191 offset:52224
	ds_read_b128 v[200:203], v191 offset:53248
	ds_read_b128 v[204:207], v191 offset:54272
	ds_read_b128 v[208:211], v191 offset:55296
	ds_read_b128 v[212:215], v191 offset:56320
	global_load_lds_dwordx4 v[184:185], off
	s_add_i32 m0, s20, 0x2000
	s_add_u32 s20, s26, 0x160080
	v_lshl_add_u64 v[184:185], v[216:217], 0, s[12:13]
	s_addc_u32 s21, s27, 0
	s_add_i32 s26, s55, s30
	global_load_lds_dwordx4 v[184:185], off
	v_lshl_add_u64 v[184:185], s[20:21], 0, v[152:153]
	s_mov_b32 m0, s26
	s_nop 0
	global_load_lds_dwordx4 v[184:185], off
	v_lshl_add_u64 v[184:185], s[20:21], 0, v[148:149]
	s_add_i32 m0, s26, 0x2000
	s_nop 0
	global_load_lds_dwordx4 v[184:185], off
	v_lshl_add_u64 v[184:185], v[218:219], 0, s[12:13]
	s_mov_b32 m0, s39
	s_nop 0
	global_load_lds_dwordx4 v[184:185], off
	v_lshl_add_u64 v[184:185], v[220:221], 0, s[12:13]
	s_mov_b32 m0, s40
	s_nop 0
	global_load_lds_dwordx4 v[184:185], off
	s_waitcnt vmcnt(8)
	s_waitcnt lgkmcnt(0)
	s_barrier
	s_setprio 1
	s_waitcnt lgkmcnt(0)
	v_mfma_f32_16x16x32_bf16 v[92:95], v[128:131], v[176:179], v[92:95]
	v_mfma_f32_16x16x32_bf16 v[88:91], v[136:139], v[176:179], v[88:91]
	v_mfma_f32_16x16x32_bf16 v[84:87], v[128:131], v[192:195], v[84:87]
	v_mfma_f32_16x16x32_bf16 v[80:83], v[136:139], v[192:195], v[80:83]
	v_mfma_f32_16x16x32_bf16 v[76:79], v[128:131], v[200:203], v[76:79]
	v_mfma_f32_16x16x32_bf16 v[72:75], v[136:139], v[200:203], v[72:75]
	v_mfma_f32_16x16x32_bf16 v[64:67], v[128:131], v[208:211], v[64:67]
	v_mfma_f32_16x16x32_bf16 v[56:59], v[136:139], v[208:211], v[56:59]
	v_mfma_f32_16x16x32_bf16 v[92:95], v[132:135], v[180:183], v[92:95]
	v_mfma_f32_16x16x32_bf16 v[88:91], v[140:143], v[180:183], v[88:91]
	v_mfma_f32_16x16x32_bf16 v[84:87], v[132:135], v[196:199], v[84:87]
	v_mfma_f32_16x16x32_bf16 v[80:83], v[140:143], v[196:199], v[80:83]
	v_mfma_f32_16x16x32_bf16 v[76:79], v[132:135], v[204:207], v[76:79]
	v_mfma_f32_16x16x32_bf16 v[72:75], v[140:143], v[204:207], v[72:75]
	v_mfma_f32_16x16x32_bf16 v[64:67], v[132:135], v[212:215], v[64:67]
	v_mfma_f32_16x16x32_bf16 v[56:59], v[140:143], v[212:215], v[56:59]
	s_setprio 0
	s_setprio 1
	v_mfma_f32_16x16x32_bf16 v[28:31], v[144:147], v[176:179], v[28:31]
	v_mfma_f32_16x16x32_bf16 v[24:27], v[168:171], v[176:179], v[24:27]
	v_mfma_f32_16x16x32_bf16 v[20:23], v[144:147], v[192:195], v[20:23]
	v_mfma_f32_16x16x32_bf16 v[16:19], v[168:171], v[192:195], v[16:19]
	v_mfma_f32_16x16x32_bf16 v[12:15], v[144:147], v[200:203], v[12:15]
	v_mfma_f32_16x16x32_bf16 v[8:11], v[168:171], v[200:203], v[8:11]
	v_mfma_f32_16x16x32_bf16 v[4:7], v[144:147], v[208:211], v[4:7]
	v_mfma_f32_16x16x32_bf16 v[0:3], v[168:171], v[208:211], v[0:3]
	v_mfma_f32_16x16x32_bf16 v[28:31], v[164:167], v[180:183], v[28:31]
	v_mfma_f32_16x16x32_bf16 v[24:27], v[172:175], v[180:183], v[24:27]
	v_mfma_f32_16x16x32_bf16 v[20:23], v[164:167], v[196:199], v[20:23]
	v_mfma_f32_16x16x32_bf16 v[16:19], v[172:175], v[196:199], v[16:19]
	v_mfma_f32_16x16x32_bf16 v[12:15], v[164:167], v[204:207], v[12:15]
	v_mfma_f32_16x16x32_bf16 v[8:11], v[172:175], v[204:207], v[8:11]
	v_mfma_f32_16x16x32_bf16 v[4:7], v[164:167], v[212:215], v[4:7]
	v_mfma_f32_16x16x32_bf16 v[0:3], v[172:175], v[212:215], v[0:3]
	s_setprio 0
	s_add_i32 s53, s53, 2
	s_add_u32 s51, s51, 0x100
	s_addc_u32 s52, s52, 0
	s_cmpk_gt_u32 s53, 0x55
	s_mov_b64 s[20:21], s[24:25]
	s_barrier
	s_cbranch_scc0 .LBB0_1390
	s_and_b64 vcc, exec, s[14:15]
	s_cbranch_vccz .LBB0_1393
	s_barrier
